# hazard-free N=1 handoff by register renaming: last A fragment alternates per super-phase, last B fragment per K-tile (v[248:255])
# speedup vs baseline: 1.0142x; 1.0076x over previous
; #define PG8_STAGE(bufoff, gbase, voff) do { _Pragma("unroll") for (int _i = 0; _i < 2; ++_i) \
;         asm volatile("s_mov_b32 m0, %2\n\ts_nop 0\n\tglobal_load_lds_dwordx4 %0, %1" :: "v"((voff)[_i]), "s"((const char*)(gbase)), "s"(ldsbase + (unsigned)(bufoff) + ldsw + (unsigned)_i * 8192u) : "memory", "m0"); } while (0)
; #define PG8_LDA(dst, b, h) do { _Pragma("unroll") for (int m = 0; m < 4; ++m) _Pragma("unroll") for (int k = 0; k < 2; ++k) dst[m][k] = *(const PG8_LAS bf16x8*)(lds + PG8_SA(b, h) + aoff + m * 2048 + k * 1024); } while (0)
; #define PG8_LDB(dst, b, h) do { _Pragma("unroll") for (int n = 0; n < 2; ++n) _Pragma("unroll") for (int k = 0; k < 2; ++k) dst[n][k] = *(const PG8_LAS bf16x8*)(lds + PG8_SB(b, h) + boff + n * 2048 + k * 1024); } while (0)
; #define PG8_MMA(ai, bj, At, Bt) do { __builtin_amdgcn_s_setprio(1); _Pragma("unroll") for (int m = 0; m < 4; ++m) _Pragma("unroll") for (int n = 0; n < 2; ++n) _Pragma("unroll") for (int k = 0; k < 2; ++k) \
;         acc[ai][bj][m][n] = __builtin_amdgcn_mfma_f32_16x16x32_bf16(Bt[n][k], At[m][k], acc[ai][bj][m][n], 0, 0, 0); __builtin_amdgcn_s_setprio(0); } while (0)
; #define PG8_WAIT_V(n) asm volatile("s_waitcnt vmcnt(" #n ")" ::: "memory")
; #define PG8_WAIT_L(n) asm volatile("s_waitcnt lgkmcnt(" #n ")" ::: "memory")
; #define PG8_BAR __builtin_amdgcn_s_barrier()
; #define PG8_SCHED __builtin_amdgcn_sched_barrier(0)
; template <class Epi, class Sched, bool ALIGN_EPI = false, bool SP2 = false>
; __device__ __forceinline__ void gemm_phase(PG8_LAS unsigned char* lds, const Gemm g, const Sched& S, const Epi& E) {
;     ...
;             PG8_LDB(B0, 0, 0); PG8_LDB(B1, 0, 1); PG8_SCHED; PG8_LDA(At, 0, 0); PG8_STAGE(PG8_SA(1, 1), a1 + hstep, voffA);
;             PG8_WAIT_V(8); PG8_WAIT_L(0); PG8_BAR; PG8_MMA(0, 0, At, B0); PG8_MMA(0, 1, At, B1); PG8_BAR; PG8_SCHED;
;             PG8_LDA(At, 0, 1); PG8_STAGE(PG8_SB(0, 0), b2, voffB); PG8_STAGE(PG8_SB(0, 1), b2 + hstep, voffB); PG8_STAGE(PG8_SA(0, 0), a2, voffA);
.LBB0_138:
	ds_read_b128 v[148:151], v142
	ds_read_b128 v[152:155], v142 offset:1024
	ds_read_b128 v[156:159], v142 offset:2048
	ds_read_b128 v[160:163], v142 offset:3072
	ds_read_b128 v[164:167], v143
	ds_read_b128 v[168:171], v143 offset:1024
	ds_read_b128 v[172:175], v143 offset:2048
	ds_read_b128 v[176:179], v143 offset:3072
	s_add_u32 s62, s66, 0x100
	s_addc_u32 s63, s67, 0
	s_cmp_eq_u32 s96, 60
	s_cselect_b32 s86, s92, s62
	s_cselect_b32 s87, s13, s63
	s_cselect_b32 s84, s93, s94
	s_cselect_b32 s85, s11, s95
	s_add_u32 s76, s86, 0x80
	s_addc_u32 s77, s87, 0
	ds_read_b128 v[180:183], v144
	ds_read_b128 v[184:187], v144 offset:1024
	ds_read_b128 v[188:191], v144 offset:2048
	ds_read_b128 v[192:195], v144 offset:3072
	ds_read_b128 v[196:199], v144 offset:4096
	ds_read_b128 v[200:203], v144 offset:5120
	ds_read_b128 v[204:207], v144 offset:6144
	ds_read_b128 v[208:211], v144 offset:7168
	s_add_u32 s66, s66, 0x100080
	s_addc_u32 s67, s67, 0
	s_mov_b32 m0, s83
	s_nop 0
	global_load_lds_dwordx4 v136, s[66:67]
	s_nop 0
	s_mov_b32 m0, s88
	s_nop 0
	global_load_lds_dwordx4 v138, s[66:67]
	s_waitcnt vmcnt(8)
	s_waitcnt lgkmcnt(0)
	s_barrier
	s_setprio 1
	s_waitcnt lgkmcnt(7)
	v_mfma_f32_16x16x32_bf16 v[126:129], v[148:151], v[180:183], v[126:129]
	v_mfma_f32_16x16x32_bf16 v[122:125], v[156:159], v[180:183], v[122:125]
	s_waitcnt lgkmcnt(5)
	v_mfma_f32_16x16x32_bf16 v[110:113], v[148:151], v[188:191], v[110:113]
	v_mfma_f32_16x16x32_bf16 v[106:109], v[156:159], v[188:191], v[106:109]
	s_waitcnt lgkmcnt(3)
	v_mfma_f32_16x16x32_bf16 v[94:97], v[148:151], v[196:199], v[94:97]
	v_mfma_f32_16x16x32_bf16 v[90:93], v[156:159], v[196:199], v[90:93]
	s_waitcnt lgkmcnt(1)
	v_mfma_f32_16x16x32_bf16 v[78:81], v[148:151], v[204:207], v[78:81]
	v_mfma_f32_16x16x32_bf16 v[74:77], v[156:159], v[204:207], v[74:77]
	v_mfma_f32_16x16x32_bf16 v[126:129], v[152:155], v[184:187], v[126:129]
	v_mfma_f32_16x16x32_bf16 v[122:125], v[160:163], v[184:187], v[122:125]
	v_mfma_f32_16x16x32_bf16 v[110:113], v[152:155], v[192:195], v[110:113]
	v_mfma_f32_16x16x32_bf16 v[106:109], v[160:163], v[192:195], v[106:109]
	v_mfma_f32_16x16x32_bf16 v[94:97], v[152:155], v[200:203], v[94:97]
	v_mfma_f32_16x16x32_bf16 v[90:93], v[160:163], v[200:203], v[90:93]
	s_waitcnt lgkmcnt(0)
	v_mfma_f32_16x16x32_bf16 v[78:81], v[152:155], v[208:211], v[78:81]
	v_mfma_f32_16x16x32_bf16 v[74:77], v[160:163], v[208:211], v[74:77]
	s_setprio 0
	s_setprio 1
	v_mfma_f32_16x16x32_bf16 v[118:121], v[164:167], v[180:183], v[118:121]
	v_mfma_f32_16x16x32_bf16 v[114:117], v[172:175], v[180:183], v[114:117]
	v_mfma_f32_16x16x32_bf16 v[102:105], v[164:167], v[188:191], v[102:105]
	v_mfma_f32_16x16x32_bf16 v[98:101], v[172:175], v[188:191], v[98:101]
	v_mfma_f32_16x16x32_bf16 v[86:89], v[164:167], v[196:199], v[86:89]
	v_mfma_f32_16x16x32_bf16 v[82:85], v[172:175], v[196:199], v[82:85]
	v_mfma_f32_16x16x32_bf16 v[70:73], v[164:167], v[204:207], v[70:73]
	v_mfma_f32_16x16x32_bf16 v[66:69], v[172:175], v[204:207], v[66:69]
	v_mfma_f32_16x16x32_bf16 v[118:121], v[168:171], v[184:187], v[118:121]
	v_mfma_f32_16x16x32_bf16 v[114:117], v[176:179], v[184:187], v[114:117]
	v_mfma_f32_16x16x32_bf16 v[102:105], v[168:171], v[192:195], v[102:105]
	v_mfma_f32_16x16x32_bf16 v[98:101], v[176:179], v[192:195], v[98:101]
	v_mfma_f32_16x16x32_bf16 v[86:89], v[168:171], v[200:203], v[86:89]
	v_mfma_f32_16x16x32_bf16 v[82:85], v[176:179], v[200:203], v[82:85]
	v_mfma_f32_16x16x32_bf16 v[70:73], v[168:171], v[208:211], v[70:73]
	s_setprio 2
	s_barrier
	v_mfma_f32_16x16x32_bf16 v[66:69], v[176:179], v[208:211], v[66:69]
	s_setprio 0
	ds_read_b128 v[180:183], v144 offset:16384
	ds_read_b128 v[184:187], v144 offset:17408
	ds_read_b128 v[188:191], v144 offset:18432
	ds_read_b128 v[192:195], v144 offset:19456
	ds_read_b128 v[196:199], v144 offset:20480
	ds_read_b128 v[200:203], v144 offset:21504
	ds_read_b128 v[204:207], v144 offset:22528
	ds_read_b128 v[252:255], v144 offset:23552
	s_mov_b32 m0, s55
	s_nop 0
	global_load_lds_dwordx4 v137, s[84:85]
	s_add_u32 s66, s84, 0x100000
	s_mov_b32 m0, s56
	s_nop 0
	global_load_lds_dwordx4 v139, s[84:85]
	s_addc_u32 s67, s85, 0
	s_mov_b32 m0, s57
	s_nop 0
	global_load_lds_dwordx4 v137, s[66:67]
	s_nop 0
	s_mov_b32 m0, s58
	s_nop 0
	global_load_lds_dwordx4 v139, s[66:67]
	s_nop 0
	s_mov_b32 m0, s54
	s_nop 0
	global_load_lds_dwordx4 v136, s[86:87]
	s_nop 0
	s_mov_b32 m0, s59
	s_nop 0
	global_load_lds_dwordx4 v138, s[86:87]
	s_waitcnt vmcnt(8)
	s_waitcnt lgkmcnt(0)
	s_barrier
; #define PG8_STAGE(bufoff, gbase, voff) do { _Pragma("unroll") for (int _i = 0; _i < 2; ++_i) \
;         asm volatile("s_mov_b32 m0, %2\n\ts_nop 0\n\tglobal_load_lds_dwordx4 %0, %1" :: "v"((voff)[_i]), "s"((const char*)(gbase)), "s"(ldsbase + (unsigned)(bufoff) + ldsw + (unsigned)_i * 8192u) : "memory", "m0"); } while (0)
; #define PG8_LDA(dst, b, h) do { _Pragma("unroll") for (int m = 0; m < 4; ++m) _Pragma("unroll") for (int k = 0; k < 2; ++k) dst[m][k] = *(const PG8_LAS bf16x8*)(lds + PG8_SA(b, h) + aoff + m * 2048 + k * 1024); } while (0)
; #define PG8_LDB(dst, b, h) do { _Pragma("unroll") for (int n = 0; n < 2; ++n) _Pragma("unroll") for (int k = 0; k < 2; ++k) dst[n][k] = *(const PG8_LAS bf16x8*)(lds + PG8_SB(b, h) + boff + n * 2048 + k * 1024); } while (0)
; #define PG8_MMA(ai, bj, At, Bt) do { __builtin_amdgcn_s_setprio(1); _Pragma("unroll") for (int m = 0; m < 4; ++m) _Pragma("unroll") for (int n = 0; n < 2; ++n) _Pragma("unroll") for (int k = 0; k < 2; ++k) \
;         acc[ai][bj][m][n] = __builtin_amdgcn_mfma_f32_16x16x32_bf16(Bt[n][k], At[m][k], acc[ai][bj][m][n], 0, 0, 0); __builtin_amdgcn_s_setprio(0); } while (0)
; #define PG8_WAIT_V(n) asm volatile("s_waitcnt vmcnt(" #n ")" ::: "memory")
; #define PG8_WAIT_L(n) asm volatile("s_waitcnt lgkmcnt(" #n ")" ::: "memory")
; #define PG8_BAR __builtin_amdgcn_s_barrier()
; #define PG8_SCHED __builtin_amdgcn_sched_barrier(0)
; template <class Epi, class Sched, bool ALIGN_EPI = false, bool SP2 = false>
; __device__ __forceinline__ void gemm_phase(PG8_LAS unsigned char* lds, const Gemm g, const Sched& S, const Epi& E) {
;     ...
;             PG8_WAIT_V(8); PG8_WAIT_L(0); PG8_BAR; PG8_MMA(1, 0, At, B0); PG8_MMA(1, 1, At, B1); PG8_BAR; PG8_SCHED;
;             PG8_LDB(B0, 1, 0); PG8_LDB(B1, 1, 1); PG8_SCHED; PG8_LDA(At, 1, 0); PG8_STAGE(PG8_SA(0, 1), a2 + hstep, voffA);
;             PG8_WAIT_V(8); PG8_WAIT_L(0); PG8_BAR; PG8_MMA(0, 0, At, B0); PG8_MMA(0, 1, At, B1); PG8_BAR; PG8_SCHED;
;             PG8_LDA(At, 1, 1); PG8_STAGE(PG8_SB(1, 0), b3, voffB); PG8_STAGE(PG8_SB(1, 1), b3 + hstep, voffB); PG8_STAGE(PG8_SA(1, 0), a3, voffA);
	s_setprio 1
	s_waitcnt lgkmcnt(7)
	v_mfma_f32_16x16x32_bf16 v[62:65], v[148:151], v[180:183], v[62:65]
	v_mfma_f32_16x16x32_bf16 v[58:61], v[156:159], v[180:183], v[58:61]
	s_waitcnt lgkmcnt(5)
	v_mfma_f32_16x16x32_bf16 v[46:49], v[148:151], v[188:191], v[46:49]
	v_mfma_f32_16x16x32_bf16 v[42:45], v[156:159], v[188:191], v[42:45]
	s_waitcnt lgkmcnt(3)
	v_mfma_f32_16x16x32_bf16 v[30:33], v[148:151], v[196:199], v[30:33]
	v_mfma_f32_16x16x32_bf16 v[26:29], v[156:159], v[196:199], v[26:29]
	s_waitcnt lgkmcnt(1)
	v_mfma_f32_16x16x32_bf16 v[14:17], v[148:151], v[204:207], v[14:17]
	v_mfma_f32_16x16x32_bf16 v[10:13], v[156:159], v[204:207], v[10:13]
	v_mfma_f32_16x16x32_bf16 v[62:65], v[152:155], v[184:187], v[62:65]
	v_mfma_f32_16x16x32_bf16 v[58:61], v[160:163], v[184:187], v[58:61]
	v_mfma_f32_16x16x32_bf16 v[46:49], v[152:155], v[192:195], v[46:49]
	v_mfma_f32_16x16x32_bf16 v[42:45], v[160:163], v[192:195], v[42:45]
	v_mfma_f32_16x16x32_bf16 v[30:33], v[152:155], v[200:203], v[30:33]
	v_mfma_f32_16x16x32_bf16 v[26:29], v[160:163], v[200:203], v[26:29]
	s_waitcnt lgkmcnt(0)
	v_mfma_f32_16x16x32_bf16 v[14:17], v[152:155], v[252:255], v[14:17]
	v_mfma_f32_16x16x32_bf16 v[10:13], v[160:163], v[252:255], v[10:13]
	s_setprio 0
	s_setprio 1
	v_mfma_f32_16x16x32_bf16 v[54:57], v[164:167], v[180:183], v[54:57]
	v_mfma_f32_16x16x32_bf16 v[50:53], v[172:175], v[180:183], v[50:53]
	v_mfma_f32_16x16x32_bf16 v[38:41], v[164:167], v[188:191], v[38:41]
	v_mfma_f32_16x16x32_bf16 v[34:37], v[172:175], v[188:191], v[34:37]
	v_mfma_f32_16x16x32_bf16 v[22:25], v[164:167], v[196:199], v[22:25]
	v_mfma_f32_16x16x32_bf16 v[18:21], v[172:175], v[196:199], v[18:21]
	v_mfma_f32_16x16x32_bf16 v[6:9], v[164:167], v[204:207], v[6:9]
	v_mfma_f32_16x16x32_bf16 v[2:5], v[172:175], v[204:207], v[2:5]
	v_mfma_f32_16x16x32_bf16 v[54:57], v[168:171], v[184:187], v[54:57]
	v_mfma_f32_16x16x32_bf16 v[50:53], v[176:179], v[184:187], v[50:53]
	v_mfma_f32_16x16x32_bf16 v[38:41], v[168:171], v[192:195], v[38:41]
	v_mfma_f32_16x16x32_bf16 v[34:37], v[176:179], v[192:195], v[34:37]
	v_mfma_f32_16x16x32_bf16 v[22:25], v[168:171], v[200:203], v[22:25]
	v_mfma_f32_16x16x32_bf16 v[18:21], v[176:179], v[200:203], v[18:21]
	v_mfma_f32_16x16x32_bf16 v[6:9], v[168:171], v[252:255], v[6:9]
	s_setprio 2
	s_barrier
	v_mfma_f32_16x16x32_bf16 v[2:5], v[176:179], v[252:255], v[2:5]
	s_setprio 0
	ds_read_b128 v[148:151], v145
	ds_read_b128 v[152:155], v145 offset:1024
	ds_read_b128 v[156:159], v145 offset:2048
	ds_read_b128 v[160:163], v145 offset:3072
	ds_read_b128 v[164:167], v146
	ds_read_b128 v[168:171], v146 offset:1024
	ds_read_b128 v[172:175], v146 offset:2048
	ds_read_b128 v[248:251], v146 offset:3072
	ds_read_b128 v[180:183], v144 offset:32768
	ds_read_b128 v[184:187], v144 offset:33792
	ds_read_b128 v[188:191], v144 offset:34816
	ds_read_b128 v[192:195], v144 offset:35840
	ds_read_b128 v[196:199], v144 offset:36864
	ds_read_b128 v[200:203], v144 offset:37888
	ds_read_b128 v[204:207], v144 offset:38912
	ds_read_b128 v[208:211], v144 offset:39936
	s_add_u32 s66, s86, 0x100000
	s_addc_u32 s67, s87, 0
	s_mov_b32 m0, s60
	s_nop 0
	global_load_lds_dwordx4 v136, s[66:67]
	s_nop 0
	s_mov_b32 m0, s61
	s_nop 0
	global_load_lds_dwordx4 v138, s[66:67]
	s_waitcnt vmcnt(8)
	s_waitcnt lgkmcnt(0)
	s_barrier
	s_setprio 1
	s_waitcnt lgkmcnt(7)
	v_mfma_f32_16x16x32_bf16 v[126:129], v[148:151], v[180:183], v[126:129]
	v_mfma_f32_16x16x32_bf16 v[122:125], v[156:159], v[180:183], v[122:125]
	s_waitcnt lgkmcnt(5)
	v_mfma_f32_16x16x32_bf16 v[110:113], v[148:151], v[188:191], v[110:113]
	v_mfma_f32_16x16x32_bf16 v[106:109], v[156:159], v[188:191], v[106:109]
	s_waitcnt lgkmcnt(3)
	v_mfma_f32_16x16x32_bf16 v[94:97], v[148:151], v[196:199], v[94:97]
	v_mfma_f32_16x16x32_bf16 v[90:93], v[156:159], v[196:199], v[90:93]
	s_waitcnt lgkmcnt(1)
	v_mfma_f32_16x16x32_bf16 v[78:81], v[148:151], v[204:207], v[78:81]
	v_mfma_f32_16x16x32_bf16 v[74:77], v[156:159], v[204:207], v[74:77]
	v_mfma_f32_16x16x32_bf16 v[126:129], v[152:155], v[184:187], v[126:129]
	v_mfma_f32_16x16x32_bf16 v[122:125], v[160:163], v[184:187], v[122:125]
	v_mfma_f32_16x16x32_bf16 v[110:113], v[152:155], v[192:195], v[110:113]
	v_mfma_f32_16x16x32_bf16 v[106:109], v[160:163], v[192:195], v[106:109]
	v_mfma_f32_16x16x32_bf16 v[94:97], v[152:155], v[200:203], v[94:97]
	v_mfma_f32_16x16x32_bf16 v[90:93], v[160:163], v[200:203], v[90:93]
	s_waitcnt lgkmcnt(0)
	v_mfma_f32_16x16x32_bf16 v[78:81], v[152:155], v[208:211], v[78:81]
	v_mfma_f32_16x16x32_bf16 v[74:77], v[160:163], v[208:211], v[74:77]
	s_setprio 0
	s_setprio 1
	v_mfma_f32_16x16x32_bf16 v[118:121], v[164:167], v[180:183], v[118:121]
	v_mfma_f32_16x16x32_bf16 v[114:117], v[172:175], v[180:183], v[114:117]
	v_mfma_f32_16x16x32_bf16 v[102:105], v[164:167], v[188:191], v[102:105]
	v_mfma_f32_16x16x32_bf16 v[98:101], v[172:175], v[188:191], v[98:101]
	v_mfma_f32_16x16x32_bf16 v[86:89], v[164:167], v[196:199], v[86:89]
	v_mfma_f32_16x16x32_bf16 v[82:85], v[172:175], v[196:199], v[82:85]
	v_mfma_f32_16x16x32_bf16 v[70:73], v[164:167], v[204:207], v[70:73]
	v_mfma_f32_16x16x32_bf16 v[66:69], v[172:175], v[204:207], v[66:69]
	v_mfma_f32_16x16x32_bf16 v[118:121], v[168:171], v[184:187], v[118:121]
	v_mfma_f32_16x16x32_bf16 v[114:117], v[248:251], v[184:187], v[114:117]
	v_mfma_f32_16x16x32_bf16 v[102:105], v[168:171], v[192:195], v[102:105]
	v_mfma_f32_16x16x32_bf16 v[98:101], v[248:251], v[192:195], v[98:101]
	v_mfma_f32_16x16x32_bf16 v[86:89], v[168:171], v[200:203], v[86:89]
	v_mfma_f32_16x16x32_bf16 v[82:85], v[248:251], v[200:203], v[82:85]
	v_mfma_f32_16x16x32_bf16 v[70:73], v[168:171], v[208:211], v[70:73]
	s_setprio 2
	s_barrier
; __device__ __forceinline__ unsigned cvt_pk_bf16(float lo, float hi) { unsigned r; asm volatile("v_cvt_pk_bf16_f32 %0, %1, %2" : "=v"(r) : "v"(lo), "v"(hi)); return r; }
; __device__ __forceinline__ float silu_f(float x) { return x * sigmoid_f(x); }
; #define PG8_STAGE(bufoff, gbase, voff) do { _Pragma("unroll") for (int _i = 0; _i < 2; ++_i) \
;         asm volatile("s_mov_b32 m0, %2\n\ts_nop 0\n\tglobal_load_lds_dwordx4 %0, %1" :: "v"((voff)[_i]), "s"((const char*)(gbase)), "s"(ldsbase + (unsigned)(bufoff) + ldsw + (unsigned)_i * 8192u) : "memory", "m0"); } while (0)
; #define PG8_LDA(dst, b, h) do { _Pragma("unroll") for (int m = 0; m < 4; ++m) _Pragma("unroll") for (int k = 0; k < 2; ++k) dst[m][k] = *(const PG8_LAS bf16x8*)(lds + PG8_SA(b, h) + aoff + m * 2048 + k * 1024); } while (0)
; #define PG8_WAIT_V(n) asm volatile("s_waitcnt vmcnt(" #n ")" ::: "memory")
; #define PG8_WAIT_L(n) asm volatile("s_waitcnt lgkmcnt(" #n ")" ::: "memory")
; #define PG8_BAR __builtin_amdgcn_s_barrier()
; #define PG8_SCHED __builtin_amdgcn_sched_barrier(0)
;     __device__ __forceinline__ void operator()(const f32x4 (&acc)[2][2][4][2], const Unit& u, int wr, int wc, int fr, int fq) const {
;     ...
;             for (int m = 0; m < 4; ++m) { bf16_t* rowp = O + (size_t)(row0 + ai * HALF + m * 16) * ldc + col0;
;                 const f32x4 g0 = acc[ai][0][m][0], g1 = acc[ai][0][m][1], u0 = acc[ai][1][m][0], u1 = acc[ai][1][m][1];
;                 f32x4 v0, v1;
; #pragma unroll
;                 for (int j = 0; j < 4; ++j) { v0[j] = silu_f(g0[j]) * u0[j]; v1[j] = silu_f(g1[j]) * u1[j]; }
;                 u32x4 w; w.x = cvt_pk_bf16(v0[0], v0[1]); w.y = cvt_pk_bf16(v0[2], v0[3]); w.z = cvt_pk_bf16(v1[0], v1[1]); w.w = cvt_pk_bf16(v1[2], v1[3]);
;                 *(u32x4*)rowp = w; }
; template <class Epi, class Sched, bool ALIGN_EPI = false, bool SP2 = false>
; __device__ __forceinline__ void gemm_phase(PG8_LAS unsigned char* lds, const Gemm g, const Sched& S, const Epi& E) {
;     ...
;             PG8_WAIT_V(8); PG8_WAIT_L(0); PG8_BAR; PG8_MMA(0, 0, At, B0); PG8_MMA(0, 1, At, B1); PG8_BAR; PG8_SCHED;
;             PG8_LDA(At, 1, 1); PG8_STAGE(PG8_SB(1, 0), b3, voffB); PG8_STAGE(PG8_SB(1, 1), b3 + hstep, voffB); PG8_STAGE(PG8_SA(1, 0), a3, voffA);
;             PG8_WAIT_V(8); PG8_WAIT_L(0); PG8_BAR; PG8_MMA(1, 0, At, B0); PG8_MMA(1, 1, At, B1); PG8_BAR; PG8_SCHED;
	v_mfma_f32_16x16x32_bf16 v[66:69], v[248:251], v[208:211], v[66:69]
	s_setprio 0
	ds_read_b128 v[180:183], v144 offset:49152
	ds_read_b128 v[184:187], v144 offset:50176
	ds_read_b128 v[188:191], v144 offset:51200
	ds_read_b128 v[192:195], v144 offset:52224
	ds_read_b128 v[196:199], v144 offset:53248
	ds_read_b128 v[200:203], v144 offset:54272
	ds_read_b128 v[204:207], v144 offset:55296
	ds_read_b128 v[252:255], v144 offset:56320
	s_add_u32 s66, s84, 0x80
	s_addc_u32 s67, s85, 0
	s_mov_b32 m0, s64
	s_nop 0
	global_load_lds_dwordx4 v137, s[66:67]
	s_nop 0
	s_mov_b32 m0, s65
	s_nop 0
	global_load_lds_dwordx4 v139, s[66:67]
	s_add_u32 s66, s84, 0x100080
	s_addc_u32 s67, s85, 0
	s_mov_b32 m0, s70
	s_nop 0
	global_load_lds_dwordx4 v137, s[66:67]
	s_nop 0
	s_mov_b32 m0, s71
	s_nop 0
	global_load_lds_dwordx4 v139, s[66:67]
	s_nop 0
	s_mov_b32 m0, s68
	s_nop 0
	global_load_lds_dwordx4 v136, s[76:77]
	s_nop 0
	s_mov_b32 m0, s69
	s_nop 0
	global_load_lds_dwordx4 v138, s[76:77]
	s_waitcnt vmcnt(8)
	s_waitcnt lgkmcnt(0)
	s_barrier
	s_setprio 1
	s_waitcnt lgkmcnt(7)
	v_mfma_f32_16x16x32_bf16 v[62:65], v[148:151], v[180:183], v[62:65]
	v_mfma_f32_16x16x32_bf16 v[58:61], v[156:159], v[180:183], v[58:61]
	s_waitcnt lgkmcnt(5)
	v_mfma_f32_16x16x32_bf16 v[46:49], v[148:151], v[188:191], v[46:49]
	v_mfma_f32_16x16x32_bf16 v[42:45], v[156:159], v[188:191], v[42:45]
	s_waitcnt lgkmcnt(3)
	v_mfma_f32_16x16x32_bf16 v[30:33], v[148:151], v[196:199], v[30:33]
	v_mfma_f32_16x16x32_bf16 v[26:29], v[156:159], v[196:199], v[26:29]
	s_waitcnt lgkmcnt(1)
	v_mfma_f32_16x16x32_bf16 v[14:17], v[148:151], v[204:207], v[14:17]
	v_mfma_f32_16x16x32_bf16 v[10:13], v[156:159], v[204:207], v[10:13]
	v_mfma_f32_16x16x32_bf16 v[62:65], v[152:155], v[184:187], v[62:65]
	v_mfma_f32_16x16x32_bf16 v[58:61], v[160:163], v[184:187], v[58:61]
	v_mfma_f32_16x16x32_bf16 v[46:49], v[152:155], v[192:195], v[46:49]
	v_mfma_f32_16x16x32_bf16 v[42:45], v[160:163], v[192:195], v[42:45]
	v_mfma_f32_16x16x32_bf16 v[30:33], v[152:155], v[200:203], v[30:33]
	v_mfma_f32_16x16x32_bf16 v[26:29], v[160:163], v[200:203], v[26:29]
	s_waitcnt lgkmcnt(0)
	v_mfma_f32_16x16x32_bf16 v[14:17], v[152:155], v[252:255], v[14:17]
	v_mfma_f32_16x16x32_bf16 v[10:13], v[160:163], v[252:255], v[10:13]
	s_setprio 0
	s_setprio 1
	v_mfma_f32_16x16x32_bf16 v[54:57], v[164:167], v[180:183], v[54:57]
	v_mfma_f32_16x16x32_bf16 v[50:53], v[172:175], v[180:183], v[50:53]
	v_mfma_f32_16x16x32_bf16 v[38:41], v[164:167], v[188:191], v[38:41]
	v_mfma_f32_16x16x32_bf16 v[34:37], v[172:175], v[188:191], v[34:37]
	v_mfma_f32_16x16x32_bf16 v[22:25], v[164:167], v[196:199], v[22:25]
	v_mfma_f32_16x16x32_bf16 v[18:21], v[172:175], v[196:199], v[18:21]
	v_mfma_f32_16x16x32_bf16 v[6:9], v[164:167], v[204:207], v[6:9]
	v_mfma_f32_16x16x32_bf16 v[2:5], v[172:175], v[204:207], v[2:5]
	v_mfma_f32_16x16x32_bf16 v[54:57], v[168:171], v[184:187], v[54:57]
	v_mfma_f32_16x16x32_bf16 v[50:53], v[248:251], v[184:187], v[50:53]
	v_mfma_f32_16x16x32_bf16 v[38:41], v[168:171], v[192:195], v[38:41]
	v_mfma_f32_16x16x32_bf16 v[34:37], v[248:251], v[192:195], v[34:37]
	v_mfma_f32_16x16x32_bf16 v[22:25], v[168:171], v[200:203], v[22:25]
	v_mfma_f32_16x16x32_bf16 v[18:21], v[248:251], v[200:203], v[18:21]
	v_mfma_f32_16x16x32_bf16 v[6:9], v[168:171], v[252:255], v[6:9]
	s_setprio 2
	s_barrier
	v_mfma_f32_16x16x32_bf16 v[2:5], v[248:251], v[252:255], v[2:5]
	s_setprio 0
	s_add_i32 s96, s96, 2
	s_add_u32 s94, s94, 0x100
	s_addc_u32 s95, s95, 0
	s_cmp_gt_u32 s96, 61
	s_mov_b64 s[66:67], s[62:63]
	s_cbranch_scc0 .LBB0_138
	v_mul_f32_e32 v134, 0xbfb8aa3b, v126
	v_exp_f32_e32 v150, v134
	v_mul_f32_e32 v134, 0xbfb8aa3b, v122
	v_exp_f32_e32 v151, v134
	v_lshl_or_b32 v148, s91, 7, v141
	v_add_f32_e32 v150, 1.0, v150
	v_rcp_f32_e32 v152, v150
	v_add_f32_e32 v150, 1.0, v151
	v_rcp_f32_e32 v153, v150
	v_lshl_add_u32 v147, s82, 8, v140
	v_mul_f32_e32 v126, v126, v152
	v_mul_f32_e32 v118, v126, v118
	v_mul_f32_e32 v126, 0xbfb8aa3b, v127
	v_exp_f32_e32 v126, v126
	v_mul_f32_e32 v152, 0xbfb8aa3b, v123
	v_exp_f32_e32 v152, v152
	v_mul_f32_e32 v122, v122, v153
	v_mul_f32_e32 v122, v122, v114
	v_add_f32_e32 v114, 1.0, v126
	v_rcp_f32_e32 v114, v114
	v_add_f32_e32 v126, 1.0, v152
	v_mul_f32_e32 v152, 0xbfb8aa3b, v128
	v_rcp_f32_e32 v126, v126
	v_exp_f32_e32 v152, v152
	v_mul_f32_e32 v114, v127, v114
	v_mul_f32_e32 v119, v114, v119
	v_mul_f32_e32 v114, v123, v126
	v_add_f32_e32 v123, 1.0, v152
	v_rcp_f32_e32 v123, v123
	v_mul_f32_e32 v126, 0xbfb8aa3b, v124
	v_exp_f32_e32 v126, v126
	v_mul_f32_e32 v127, v114, v115
	v_mul_f32_e32 v114, v128, v123
	v_mul_f32_e32 v115, 0xbfb8aa3b, v129
	v_mul_f32_e32 v123, v114, v120
	v_exp_f32_e32 v115, v115
	v_mul_f32_e32 v120, 0xbfb8aa3b, v125
	v_exp_f32_e32 v120, v120
	v_add_f32_e32 v114, 1.0, v126
	v_rcp_f32_e32 v114, v114
	v_add_f32_e32 v115, 1.0, v115
	v_rcp_f32_e32 v115, v115
	v_add_f32_e32 v120, 1.0, v120
	v_rcp_f32_e32 v120, v120
	v_mul_f32_e32 v114, v124, v114
	v_mul_f32_e32 v124, v114, v116
	v_mul_f32_e32 v114, v129, v115
	v_ashrrev_i32_e32 v149, 31, v148
	v_mov_b64_e32 v[134:135], s[72:73]
	v_mul_f32_e32 v126, v114, v121
	v_mul_f32_e32 v114, v125, v120
	v_mad_i64_i32 v[150:151], s[62:63], v147, s90, v[134:135]
	v_mul_f32_e32 v125, v114, v117
	v_lshlrev_b64 v[114:115], 1, v[148:149]
	v_lshl_add_u64 v[120:121], v[150:151], 0, v[114:115]
	v_cvt_pk_bf16_f32 v116, v118, v119
	v_cvt_pk_bf16_f32 v117, v123, v126
	v_cvt_pk_bf16_f32 v118, v122, v127
	v_cvt_pk_bf16_f32 v119, v124, v125
	global_store_dwordx4 v[120:121], v[116:119], off
	s_and_b64 vcc, exec, s[0:1]
	s_mov_b32 s91, s10
	v_mul_f32_e32 v116, 0xbfb8aa3b, v110
	v_exp_f32_e32 v116, v116
; __device__ __forceinline__ unsigned cvt_pk_bf16(float lo, float hi) { unsigned r; asm volatile("v_cvt_pk_bf16_f32 %0, %1, %2" : "=v"(r) : "v"(lo), "v"(hi)); return r; }
; __device__ __forceinline__ float silu_f(float x) { return x * sigmoid_f(x); }
;     __device__ __forceinline__ void operator()(const f32x4 (&acc)[2][2][4][2], const Unit& u, int wr, int wc, int fr, int fq) const {
;     ...
;             for (int m = 0; m < 4; ++m) { bf16_t* rowp = O + (size_t)(row0 + ai * HALF + m * 16) * ldc + col0;
;                 const f32x4 g0 = acc[ai][0][m][0], g1 = acc[ai][0][m][1], u0 = acc[ai][1][m][0], u1 = acc[ai][1][m][1];
;                 f32x4 v0, v1;
; #pragma unroll
;                 for (int j = 0; j < 4; ++j) { v0[j] = silu_f(g0[j]) * u0[j]; v1[j] = silu_f(g1[j]) * u1[j]; }
;                 u32x4 w; w.x = cvt_pk_bf16(v0[0], v0[1]); w.y = cvt_pk_bf16(v0[2], v0[3]); w.z = cvt_pk_bf16(v1[0], v1[1]); w.w = cvt_pk_bf16(v1[2], v1[3]);
;                 *(u32x4*)rowp = w; }
	v_mul_f32_e32 v117, 0xbfb8aa3b, v106
	v_exp_f32_e32 v117, v117
	v_or_b32_e32 v118, 16, v147
	v_add_f32_e32 v116, 1.0, v116
	v_rcp_f32_e32 v119, v116
	v_add_f32_e32 v116, 1.0, v117
	v_rcp_f32_e32 v120, v116
	v_mad_i64_i32 v[116:117], s[62:63], v118, s90, v[134:135]
	v_mul_f32_e32 v110, v110, v119
	v_mul_f32_e32 v110, v110, v102
	v_mul_f32_e32 v102, v106, v120
	v_mul_f32_e32 v106, 0xbfb8aa3b, v111
	v_exp_f32_e32 v106, v106
	v_mul_f32_e32 v118, 0xbfb8aa3b, v107
	v_mul_f32_e32 v119, v102, v98
	v_exp_f32_e32 v118, v118
	v_add_f32_e32 v98, 1.0, v106
	v_rcp_f32_e32 v98, v98
	v_mul_f32_e32 v106, 0xbfb8aa3b, v112
	v_exp_f32_e32 v106, v106
	v_add_f32_e32 v102, 1.0, v118
	v_mul_f32_e32 v98, v111, v98
	v_rcp_f32_e32 v102, v102
	v_mul_f32_e32 v98, v98, v103
	v_add_f32_e32 v103, 1.0, v106
	v_rcp_f32_e32 v103, v103
	v_mul_f32_e32 v102, v107, v102
	v_mul_f32_e32 v106, 0xbfb8aa3b, v108
	v_mul_f32_e32 v107, v102, v99
	v_mul_f32_e32 v99, v112, v103
	v_exp_f32_e32 v106, v106
	v_mul_f32_e32 v99, v99, v104
	v_mul_f32_e32 v103, 0xbfb8aa3b, v113
	v_mul_f32_e32 v104, 0xbfb8aa3b, v109
	v_exp_f32_e32 v103, v103
	v_exp_f32_e32 v104, v104
	v_add_f32_e32 v102, 1.0, v106
	v_rcp_f32_e32 v102, v102
	v_add_f32_e32 v103, 1.0, v103
	v_add_f32_e32 v104, 1.0, v104
	v_rcp_f32_e32 v103, v103
	v_rcp_f32_e32 v104, v104
	v_mul_f32_e32 v102, v108, v102
	v_mul_f32_e32 v106, v102, v100
	v_mul_f32_e32 v100, v113, v103
	v_mul_f32_e32 v102, v109, v104
	v_mul_f32_e32 v100, v100, v105
	v_mul_f32_e32 v101, v102, v101
	v_lshl_add_u64 v[102:103], v[116:117], 0, v[114:115]
	v_cvt_pk_bf16_f32 v98, v110, v98
	v_cvt_pk_bf16_f32 v99, v99, v100
	v_cvt_pk_bf16_f32 v100, v119, v107
	v_cvt_pk_bf16_f32 v101, v106, v101
	global_store_dwordx4 v[102:103], v[98:101], off
	s_mov_b32 s82, s12
	s_mov_b64 s[66:67], s[14:15]
	v_mul_f32_e32 v98, 0xbfb8aa3b, v94
	v_exp_f32_e32 v98, v98
	v_mul_f32_e32 v99, 0xbfb8aa3b, v90
	v_exp_f32_e32 v99, v99
	v_or_b32_e32 v100, 32, v147
	v_add_f32_e32 v98, 1.0, v98
	v_rcp_f32_e32 v101, v98
	v_add_f32_e32 v98, 1.0, v99
	v_rcp_f32_e32 v102, v98
	v_mad_i64_i32 v[98:99], s[62:63], v100, s90, v[134:135]
	v_mul_f32_e32 v94, v94, v101
	v_mul_f32_e32 v94, v94, v86
	v_mul_f32_e32 v86, v90, v102
	v_mul_f32_e32 v90, 0xbfb8aa3b, v95
	v_exp_f32_e32 v90, v90
	v_mul_f32_e32 v100, 0xbfb8aa3b, v91
	v_mul_f32_e32 v101, v86, v82
	v_exp_f32_e32 v100, v100
	v_add_f32_e32 v82, 1.0, v90
	v_rcp_f32_e32 v82, v82
	v_mul_f32_e32 v90, 0xbfb8aa3b, v96
	v_exp_f32_e32 v90, v90
	v_add_f32_e32 v86, 1.0, v100
	v_mul_f32_e32 v82, v95, v82
	v_rcp_f32_e32 v86, v86
	v_mul_f32_e32 v82, v82, v87
	v_add_f32_e32 v87, 1.0, v90
	v_rcp_f32_e32 v87, v87
	v_mul_f32_e32 v86, v91, v86
	v_mul_f32_e32 v90, 0xbfb8aa3b, v92
	v_mul_f32_e32 v91, v86, v83
	v_mul_f32_e32 v83, v96, v87
	v_exp_f32_e32 v90, v90
	v_mul_f32_e32 v83, v83, v88
	v_mul_f32_e32 v87, 0xbfb8aa3b, v97
	v_mul_f32_e32 v88, 0xbfb8aa3b, v93
	v_exp_f32_e32 v87, v87
	v_exp_f32_e32 v88, v88
	v_add_f32_e32 v86, 1.0, v90
	v_rcp_f32_e32 v86, v86
	v_add_f32_e32 v87, 1.0, v87
	v_add_f32_e32 v88, 1.0, v88
	v_rcp_f32_e32 v87, v87
	v_rcp_f32_e32 v88, v88
	v_mul_f32_e32 v86, v92, v86
	v_mul_f32_e32 v90, v86, v84
	v_mul_f32_e32 v84, v97, v87
	v_mul_f32_e32 v86, v93, v88
	v_mul_f32_e32 v84, v84, v89
	v_mul_f32_e32 v85, v86, v85
	v_lshl_add_u64 v[86:87], v[98:99], 0, v[114:115]
	v_cvt_pk_bf16_f32 v82, v94, v82
	v_cvt_pk_bf16_f32 v83, v83, v84
	v_cvt_pk_bf16_f32 v84, v101, v91
	v_cvt_pk_bf16_f32 v85, v90, v85
	global_store_dwordx4 v[86:87], v[82:85], off
	s_nop 1
	v_mul_f32_e32 v82, 0xbfb8aa3b, v78
	v_exp_f32_e32 v82, v82
	v_mul_f32_e32 v83, 0xbfb8aa3b, v74
	v_exp_f32_e32 v83, v83
	v_or_b32_e32 v84, 48, v147
	v_add_f32_e32 v82, 1.0, v82
	v_rcp_f32_e32 v85, v82
	v_add_f32_e32 v82, 1.0, v83
	v_rcp_f32_e32 v86, v82
	v_mad_i64_i32 v[82:83], s[62:63], v84, s90, v[134:135]
	v_mul_f32_e32 v78, v78, v85
	v_mul_f32_e32 v78, v78, v70
	v_mul_f32_e32 v70, v74, v86
	v_mul_f32_e32 v74, 0xbfb8aa3b, v79
	v_exp_f32_e32 v74, v74
	v_mul_f32_e32 v84, 0xbfb8aa3b, v75
	v_mul_f32_e32 v85, v70, v66
	v_exp_f32_e32 v84, v84
	v_add_f32_e32 v66, 1.0, v74
	v_rcp_f32_e32 v66, v66
	v_mul_f32_e32 v74, 0xbfb8aa3b, v80
	v_exp_f32_e32 v74, v74
	v_add_f32_e32 v70, 1.0, v84
	v_mul_f32_e32 v66, v79, v66
	v_rcp_f32_e32 v70, v70
	v_mul_f32_e32 v66, v66, v71
	v_add_f32_e32 v71, 1.0, v74
	v_rcp_f32_e32 v71, v71
	v_mul_f32_e32 v70, v75, v70
	v_mul_f32_e32 v74, 0xbfb8aa3b, v76
	v_mul_f32_e32 v75, v70, v67
	v_mul_f32_e32 v67, v80, v71
	v_exp_f32_e32 v74, v74
	v_mul_f32_e32 v67, v67, v72
	v_mul_f32_e32 v71, 0xbfb8aa3b, v81
	v_mul_f32_e32 v72, 0xbfb8aa3b, v77
	v_exp_f32_e32 v71, v71
	v_exp_f32_e32 v72, v72
	v_add_f32_e32 v70, 1.0, v74
	v_rcp_f32_e32 v70, v70
	v_add_f32_e32 v71, 1.0, v71
	v_add_f32_e32 v72, 1.0, v72
	v_rcp_f32_e32 v71, v71
	v_rcp_f32_e32 v72, v72
	v_mul_f32_e32 v70, v76, v70
	v_mul_f32_e32 v74, v70, v68
	v_mul_f32_e32 v68, v81, v71
	v_mul_f32_e32 v70, v77, v72
	v_mul_f32_e32 v68, v68, v73
	v_mul_f32_e32 v69, v70, v69
	v_lshl_add_u64 v[70:71], v[82:83], 0, v[114:115]
	v_cvt_pk_bf16_f32 v66, v78, v66
	v_cvt_pk_bf16_f32 v67, v67, v68
	v_cvt_pk_bf16_f32 v68, v85, v75
	v_cvt_pk_bf16_f32 v69, v74, v69
	global_store_dwordx4 v[70:71], v[66:69], off
	s_nop 1
	v_mul_f32_e32 v66, 0xbfb8aa3b, v62
	v_exp_f32_e32 v66, v66
	v_mul_f32_e32 v67, 0xbfb8aa3b, v58
	v_exp_f32_e32 v67, v67
	v_add_u32_e32 v68, 0x80, v147
	v_add_f32_e32 v66, 1.0, v66
	v_rcp_f32_e32 v69, v66
	v_add_f32_e32 v66, 1.0, v67
	v_rcp_f32_e32 v70, v66
	v_mad_i64_i32 v[66:67], s[62:63], v68, s90, v[134:135]
	v_mul_f32_e32 v62, v62, v69
	v_mul_f32_e32 v62, v62, v54
	v_mul_f32_e32 v54, v58, v70
	v_mul_f32_e32 v58, 0xbfb8aa3b, v63
	v_exp_f32_e32 v58, v58
; __device__ __forceinline__ unsigned cvt_pk_bf16(float lo, float hi) { unsigned r; asm volatile("v_cvt_pk_bf16_f32 %0, %1, %2" : "=v"(r) : "v"(lo), "v"(hi)); return r; }
; __device__ __forceinline__ float silu_f(float x) { return x * sigmoid_f(x); }
; #define PG8_WAIT_V(n) asm volatile("s_waitcnt vmcnt(" #n ")" ::: "memory")
; #define PG8_BAR __builtin_amdgcn_s_barrier()
;     __device__ __forceinline__ void operator()(const f32x4 (&acc)[2][2][4][2], const Unit& u, int wr, int wc, int fr, int fq) const {
;     ...
;             for (int m = 0; m < 4; ++m) { bf16_t* rowp = O + (size_t)(row0 + ai * HALF + m * 16) * ldc + col0;
;                 const f32x4 g0 = acc[ai][0][m][0], g1 = acc[ai][0][m][1], u0 = acc[ai][1][m][0], u1 = acc[ai][1][m][1];
;                 f32x4 v0, v1;
; #pragma unroll
;                 for (int j = 0; j < 4; ++j) { v0[j] = silu_f(g0[j]) * u0[j]; v1[j] = silu_f(g1[j]) * u1[j]; }
;                 u32x4 w; w.x = cvt_pk_bf16(v0[0], v0[1]); w.y = cvt_pk_bf16(v0[2], v0[3]); w.z = cvt_pk_bf16(v1[0], v1[1]); w.w = cvt_pk_bf16(v1[2], v1[3]);
;                 *(u32x4*)rowp = w; }
; template <class Epi, class Sched, bool ALIGN_EPI = false, bool SP2 = false>
; __device__ __forceinline__ void gemm_phase(PG8_LAS unsigned char* lds, const Gemm g, const Sched& S, const Epi& E) {
;     ...
;         if (!has_next) break;
; #pragma unroll
;         for (int a = 0; a < 2; ++a)
; #pragma unroll
;             for (int b = 0; b < 2; ++b)
; #pragma unroll
;                 for (int m = 0; m < 4; ++m)
; #pragma unroll
;                     for (int n = 0; n < 2; ++n) acc[a][b][m][n] = (f32x4){0.f, 0.f, 0.f, 0.f};
;         cur = nxt; cA = nA; cB = nB; ++ui;
;         if constexpr (ALIGN_EPI) { if (wr == 1) PG8_BAR; }
;     }
;     PG8_WAIT_V(0);
;     if constexpr (!ALIGN_EPI) { if (wr == 0) PG8_BAR; }
;     PG8_BAR;
	v_mul_f32_e32 v68, 0xbfb8aa3b, v59
	v_mul_f32_e32 v69, v54, v50
	v_exp_f32_e32 v68, v68
	v_add_f32_e32 v50, 1.0, v58
	v_rcp_f32_e32 v50, v50
	v_mul_f32_e32 v58, 0xbfb8aa3b, v64
	v_exp_f32_e32 v58, v58
	v_add_f32_e32 v54, 1.0, v68
	v_mul_f32_e32 v50, v63, v50
	v_rcp_f32_e32 v54, v54
	v_mul_f32_e32 v50, v50, v55
	v_add_f32_e32 v55, 1.0, v58
	v_rcp_f32_e32 v55, v55
	v_mul_f32_e32 v54, v59, v54
	v_mul_f32_e32 v58, 0xbfb8aa3b, v60
	v_mul_f32_e32 v59, v54, v51
	v_mul_f32_e32 v51, v64, v55
	v_exp_f32_e32 v58, v58
	v_mul_f32_e32 v51, v51, v56
	v_mul_f32_e32 v55, 0xbfb8aa3b, v65
	v_mul_f32_e32 v56, 0xbfb8aa3b, v61
	v_exp_f32_e32 v55, v55
	v_exp_f32_e32 v56, v56
	v_add_f32_e32 v54, 1.0, v58
	v_rcp_f32_e32 v54, v54
	v_add_f32_e32 v55, 1.0, v55
	v_add_f32_e32 v56, 1.0, v56
	v_rcp_f32_e32 v55, v55
	v_rcp_f32_e32 v56, v56
	v_mul_f32_e32 v54, v60, v54
	v_mul_f32_e32 v58, v54, v52
	v_mul_f32_e32 v52, v65, v55
	v_mul_f32_e32 v54, v61, v56
	v_mul_f32_e32 v52, v52, v57
	v_mul_f32_e32 v53, v54, v53
	v_lshl_add_u64 v[54:55], v[66:67], 0, v[114:115]
	v_cvt_pk_bf16_f32 v50, v62, v50
	v_cvt_pk_bf16_f32 v51, v51, v52
	v_cvt_pk_bf16_f32 v52, v69, v59
	v_cvt_pk_bf16_f32 v53, v58, v53
	global_store_dwordx4 v[54:55], v[50:53], off
	s_nop 1
	v_mul_f32_e32 v50, 0xbfb8aa3b, v46
	v_exp_f32_e32 v50, v50
	v_mul_f32_e32 v51, 0xbfb8aa3b, v42
	v_exp_f32_e32 v51, v51
	v_add_u32_e32 v52, 0x90, v147
	v_add_f32_e32 v50, 1.0, v50
	v_rcp_f32_e32 v53, v50
	v_add_f32_e32 v50, 1.0, v51
	v_rcp_f32_e32 v54, v50
	v_mad_i64_i32 v[50:51], s[62:63], v52, s90, v[134:135]
	v_mul_f32_e32 v46, v46, v53
	v_mul_f32_e32 v46, v46, v38
	v_mul_f32_e32 v38, v42, v54
	v_mul_f32_e32 v42, 0xbfb8aa3b, v47
	v_exp_f32_e32 v42, v42
	v_mul_f32_e32 v52, 0xbfb8aa3b, v43
	v_mul_f32_e32 v53, v38, v34
	v_exp_f32_e32 v52, v52
	v_add_f32_e32 v34, 1.0, v42
	v_rcp_f32_e32 v34, v34
	v_mul_f32_e32 v42, 0xbfb8aa3b, v48
	v_exp_f32_e32 v42, v42
	v_add_f32_e32 v38, 1.0, v52
	v_mul_f32_e32 v34, v47, v34
	v_rcp_f32_e32 v38, v38
	v_mul_f32_e32 v34, v34, v39
	v_add_f32_e32 v39, 1.0, v42
	v_rcp_f32_e32 v39, v39
	v_mul_f32_e32 v38, v43, v38
	v_mul_f32_e32 v42, 0xbfb8aa3b, v44
	v_mul_f32_e32 v43, v38, v35
	v_mul_f32_e32 v35, v48, v39
	v_exp_f32_e32 v42, v42
	v_mul_f32_e32 v35, v35, v40
	v_mul_f32_e32 v39, 0xbfb8aa3b, v49
	v_mul_f32_e32 v40, 0xbfb8aa3b, v45
	v_exp_f32_e32 v39, v39
	v_exp_f32_e32 v40, v40
	v_add_f32_e32 v38, 1.0, v42
	v_rcp_f32_e32 v38, v38
	v_add_f32_e32 v39, 1.0, v39
	v_add_f32_e32 v40, 1.0, v40
	v_rcp_f32_e32 v39, v39
	v_rcp_f32_e32 v40, v40
	v_mul_f32_e32 v38, v44, v38
	v_mul_f32_e32 v42, v38, v36
	v_mul_f32_e32 v36, v49, v39
	v_mul_f32_e32 v38, v45, v40
	v_mul_f32_e32 v36, v36, v41
	v_mul_f32_e32 v37, v38, v37
	v_lshl_add_u64 v[38:39], v[50:51], 0, v[114:115]
	v_cvt_pk_bf16_f32 v34, v46, v34
	v_cvt_pk_bf16_f32 v35, v35, v36
	v_cvt_pk_bf16_f32 v36, v53, v43
	v_cvt_pk_bf16_f32 v37, v42, v37
	global_store_dwordx4 v[38:39], v[34:37], off
	s_nop 1
	v_mul_f32_e32 v34, 0xbfb8aa3b, v30
	v_exp_f32_e32 v34, v34
	v_mul_f32_e32 v35, 0xbfb8aa3b, v26
	v_exp_f32_e32 v35, v35
	v_add_u32_e32 v36, 0xa0, v147
	v_add_f32_e32 v34, 1.0, v34
	v_rcp_f32_e32 v37, v34
	v_add_f32_e32 v34, 1.0, v35
	v_rcp_f32_e32 v38, v34
	v_mad_i64_i32 v[34:35], s[62:63], v36, s90, v[134:135]
	v_mul_f32_e32 v30, v30, v37
	v_mul_f32_e32 v30, v30, v22
	v_mul_f32_e32 v22, v26, v38
	v_mul_f32_e32 v26, 0xbfb8aa3b, v31
	v_exp_f32_e32 v26, v26
	v_mul_f32_e32 v36, 0xbfb8aa3b, v27
	v_mul_f32_e32 v37, v22, v18
	v_exp_f32_e32 v36, v36
	v_add_f32_e32 v18, 1.0, v26
	v_rcp_f32_e32 v18, v18
	v_mul_f32_e32 v26, 0xbfb8aa3b, v32
	v_exp_f32_e32 v26, v26
	v_add_f32_e32 v22, 1.0, v36
	v_mul_f32_e32 v18, v31, v18
	v_rcp_f32_e32 v22, v22
	v_mul_f32_e32 v18, v18, v23
	v_add_f32_e32 v23, 1.0, v26
	v_rcp_f32_e32 v23, v23
	v_mul_f32_e32 v22, v27, v22
	v_mul_f32_e32 v26, 0xbfb8aa3b, v28
	v_mul_f32_e32 v27, v22, v19
	v_mul_f32_e32 v19, v32, v23
	v_exp_f32_e32 v26, v26
	v_mul_f32_e32 v19, v19, v24
	v_mul_f32_e32 v23, 0xbfb8aa3b, v33
	v_mul_f32_e32 v24, 0xbfb8aa3b, v29
	v_exp_f32_e32 v23, v23
	v_exp_f32_e32 v24, v24
	v_add_f32_e32 v22, 1.0, v26
	v_rcp_f32_e32 v22, v22
	v_add_f32_e32 v23, 1.0, v23
	v_add_f32_e32 v24, 1.0, v24
	v_rcp_f32_e32 v23, v23
	v_rcp_f32_e32 v24, v24
	v_mul_f32_e32 v22, v28, v22
	v_mul_f32_e32 v26, v22, v20
	v_mul_f32_e32 v20, v33, v23
	v_mul_f32_e32 v22, v29, v24
	v_mul_f32_e32 v20, v20, v25
	v_mul_f32_e32 v21, v22, v21
	v_lshl_add_u64 v[22:23], v[34:35], 0, v[114:115]
	v_cvt_pk_bf16_f32 v18, v30, v18
	v_cvt_pk_bf16_f32 v19, v19, v20
	v_cvt_pk_bf16_f32 v20, v37, v27
	v_cvt_pk_bf16_f32 v21, v26, v21
	global_store_dwordx4 v[22:23], v[18:21], off
	s_nop 1
	v_mul_f32_e32 v18, 0xbfb8aa3b, v14
	v_exp_f32_e32 v18, v18
	v_mul_f32_e32 v19, 0xbfb8aa3b, v10
	v_exp_f32_e32 v19, v19
	v_add_u32_e32 v20, 0xb0, v147
	v_add_f32_e32 v18, 1.0, v18
	v_rcp_f32_e32 v21, v18
	v_add_f32_e32 v18, 1.0, v19
	v_rcp_f32_e32 v22, v18
	v_mad_i64_i32 v[18:19], s[62:63], v20, s90, v[134:135]
	v_mul_f32_e32 v14, v14, v21
	v_mul_f32_e32 v14, v14, v6
	v_mul_f32_e32 v6, v10, v22
	v_mul_f32_e32 v10, 0xbfb8aa3b, v15
	v_exp_f32_e32 v10, v10
	v_mul_f32_e32 v20, 0xbfb8aa3b, v11
	v_mul_f32_e32 v21, v6, v2
	v_exp_f32_e32 v20, v20
	v_add_f32_e32 v2, 1.0, v10
	v_rcp_f32_e32 v2, v2
	v_mul_f32_e32 v10, 0xbfb8aa3b, v16
	v_exp_f32_e32 v10, v10
	v_add_f32_e32 v6, 1.0, v20
	v_mul_f32_e32 v2, v15, v2
	v_rcp_f32_e32 v6, v6
	v_mul_f32_e32 v2, v2, v7
	v_add_f32_e32 v7, 1.0, v10
	v_rcp_f32_e32 v7, v7
	v_mul_f32_e32 v6, v11, v6
	v_mul_f32_e32 v10, 0xbfb8aa3b, v12
	v_mul_f32_e32 v11, v6, v3
	v_mul_f32_e32 v3, v16, v7
	v_exp_f32_e32 v10, v10
	v_mul_f32_e32 v3, v3, v8
	v_mul_f32_e32 v7, 0xbfb8aa3b, v17
	v_mul_f32_e32 v8, 0xbfb8aa3b, v13
	v_exp_f32_e32 v7, v7
	v_exp_f32_e32 v8, v8
	v_add_f32_e32 v6, 1.0, v10
	v_rcp_f32_e32 v6, v6
	v_add_f32_e32 v7, 1.0, v7
	v_add_f32_e32 v8, 1.0, v8
	v_rcp_f32_e32 v7, v7
	v_rcp_f32_e32 v8, v8
	v_mul_f32_e32 v6, v12, v6
	v_mul_f32_e32 v10, v6, v4
	v_mul_f32_e32 v4, v17, v7
	v_mul_f32_e32 v6, v13, v8
	v_mul_f32_e32 v4, v4, v9
	v_mul_f32_e32 v5, v6, v5
	v_lshl_add_u64 v[6:7], v[18:19], 0, v[114:115]
	s_mov_b64 s[62:63], s[16:17]
	v_cvt_pk_bf16_f32 v2, v14, v2
	v_cvt_pk_bf16_f32 v3, v3, v4
	v_cvt_pk_bf16_f32 v4, v21, v11
	v_cvt_pk_bf16_f32 v5, v10, v5
	global_store_dwordx4 v[6:7], v[2:5], off
	s_cbranch_vccz .LBB0_135
	s_waitcnt vmcnt(0)
	s_cmpk_gt_u32 s3, 0xff
	s_cbranch_scc1 .LBB0_142
	s_barrier

; #define PG8_STAGE(bufoff, gbase, voff) do { _Pragma("unroll") for (int _i = 0; _i < 2; ++_i) \
;         asm volatile("s_mov_b32 m0, %2\n\ts_nop 0\n\tglobal_load_lds_dwordx4 %0, %1" :: "v"((voff)[_i]), "s"((const char*)(gbase)), "s"(ldsbase + (unsigned)(bufoff) + ldsw + (unsigned)_i * 8192u) : "memory", "m0"); } while (0)
; #define PG8_LDA(dst, b, h) do { _Pragma("unroll") for (int m = 0; m < 4; ++m) _Pragma("unroll") for (int k = 0; k < 2; ++k) dst[m][k] = *(const PG8_LAS bf16x8*)(lds + PG8_SA(b, h) + aoff + m * 2048 + k * 1024); } while (0)
; #define PG8_LDB(dst, b, h) do { _Pragma("unroll") for (int n = 0; n < 2; ++n) _Pragma("unroll") for (int k = 0; k < 2; ++k) dst[n][k] = *(const PG8_LAS bf16x8*)(lds + PG8_SB(b, h) + boff + n * 2048 + k * 1024); } while (0)
; #define PG8_MMA(ai, bj, At, Bt) do { __builtin_amdgcn_s_setprio(1); _Pragma("unroll") for (int m = 0; m < 4; ++m) _Pragma("unroll") for (int n = 0; n < 2; ++n) _Pragma("unroll") for (int k = 0; k < 2; ++k) \
;         acc[ai][bj][m][n] = __builtin_amdgcn_mfma_f32_16x16x32_bf16(Bt[n][k], At[m][k], acc[ai][bj][m][n], 0, 0, 0); __builtin_amdgcn_s_setprio(0); } while (0)
; template <class Epi, class Sched, bool ALIGN_EPI = false, bool SP2 = false>
; __device__ __forceinline__ void gemm_phase(PG8_LAS unsigned char* lds, const Gemm g, const Sched& S, const Epi& E) {
;     ...
;             const bool last = (t == nt - 2);
;             const char* a1 = cA + (size_t)(t + 1) * kstep;
;             const char* a2 = last ? nA : cA + (size_t)(t + 2) * kstep; const char* b2 = last ? nB : cB + (size_t)(t + 2) * kstep;
;             const char* a3 = a2 + kstep; const char* b3 = b2 + kstep;
;             if (last && has_next) S.a_ready(nxt);
;             if constexpr (epi_has_mid<Epi>::value) { if (t == Epi::MID_T) E.mid(acc, cur, wr, wc, fr, fq); }
;             if constexpr (SP2) {
;             PG8_LDB(B0, 0, 0); PG8_LDB(B1, 0, 1); PG8_SCHED; PG8_LDA(At, 0, 0); PG8_STAGE(PG8_SA(1, 1), a1 + hstep, voffA);
;             PG8_WAIT_V(8); PG8_WAIT_L(0); PG8_BAR; PG8_MMA(0, 0, At, B0); PG8_MMA(0, 1, At, B1); PG8_BAR; PG8_SCHED;
;             PG8_LDA(At, 0, 1); PG8_STAGE(PG8_SB(0, 0), b2, voffB); PG8_STAGE(PG8_SB(0, 1), b2 + hstep, voffB); PG8_STAGE(PG8_SA(0, 0), a2, voffA);
;             PG8_WAIT_V(8); PG8_WAIT_L(0); PG8_BAR; PG8_MMA(1, 0, At, B0); PG8_MMA(1, 1, At, B1); PG8_BAR; PG8_SCHED;
.LBB0_234:
	ds_read_b128 v[134:137], v145
	ds_read_b128 v[152:155], v145 offset:1024
	ds_read_b128 v[156:159], v145 offset:2048
	ds_read_b128 v[160:163], v145 offset:3072
	ds_read_b128 v[164:167], v146
	ds_read_b128 v[168:171], v146 offset:1024
	ds_read_b128 v[172:175], v146 offset:2048
	ds_read_b128 v[176:179], v146 offset:3072
	s_cmpk_eq_i32 s57, 0xa8
	s_cselect_b32 s76, s4, s53
	s_cselect_b32 s77, s5, s54
	s_cselect_b32 s66, s46, s55
	s_cselect_b32 s67, s47, s56
	s_add_u32 s62, s76, 0x80
	s_addc_u32 s63, s77, 0
	ds_read_b128 v[180:183], v147
	ds_read_b128 v[184:187], v147 offset:1024
	ds_read_b128 v[188:191], v147 offset:2048
	ds_read_b128 v[192:195], v147 offset:3072
	ds_read_b128 v[196:199], v147 offset:4096
	ds_read_b128 v[200:203], v147 offset:5120
	ds_read_b128 v[204:207], v147 offset:6144
	ds_read_b128 v[208:211], v147 offset:7168
	s_mov_b32 m0, s94
	s_nop 0
	global_load_lds_dwordx4 v1, s[50:51]
	s_nop 0
	s_mov_b32 m0, s95
	s_nop 0
	global_load_lds_dwordx4 v141, s[50:51]
	s_waitcnt vmcnt(8)
	s_waitcnt lgkmcnt(0)
	s_barrier
	s_setprio 1
	s_waitcnt lgkmcnt(7)
	v_mfma_f32_16x16x32_bf16 v[126:129], v[134:137], v[180:183], v[126:129]
	v_mfma_f32_16x16x32_bf16 v[122:125], v[156:159], v[180:183], v[122:125]
	s_waitcnt lgkmcnt(5)
	v_mfma_f32_16x16x32_bf16 v[110:113], v[134:137], v[188:191], v[110:113]
	v_mfma_f32_16x16x32_bf16 v[106:109], v[156:159], v[188:191], v[106:109]
	s_waitcnt lgkmcnt(3)
	v_mfma_f32_16x16x32_bf16 v[94:97], v[134:137], v[196:199], v[94:97]
	v_mfma_f32_16x16x32_bf16 v[90:93], v[156:159], v[196:199], v[90:93]
	s_waitcnt lgkmcnt(1)
	v_mfma_f32_16x16x32_bf16 v[78:81], v[134:137], v[204:207], v[78:81]
	v_mfma_f32_16x16x32_bf16 v[74:77], v[156:159], v[204:207], v[74:77]
	v_mfma_f32_16x16x32_bf16 v[126:129], v[152:155], v[184:187], v[126:129]
	v_mfma_f32_16x16x32_bf16 v[122:125], v[160:163], v[184:187], v[122:125]
	v_mfma_f32_16x16x32_bf16 v[110:113], v[152:155], v[192:195], v[110:113]
	v_mfma_f32_16x16x32_bf16 v[106:109], v[160:163], v[192:195], v[106:109]
	v_mfma_f32_16x16x32_bf16 v[94:97], v[152:155], v[200:203], v[94:97]
	v_mfma_f32_16x16x32_bf16 v[90:93], v[160:163], v[200:203], v[90:93]
	s_waitcnt lgkmcnt(0)
	v_mfma_f32_16x16x32_bf16 v[78:81], v[152:155], v[208:211], v[78:81]
	v_mfma_f32_16x16x32_bf16 v[74:77], v[160:163], v[208:211], v[74:77]
	s_setprio 0
	s_setprio 1
	v_mfma_f32_16x16x32_bf16 v[118:121], v[164:167], v[180:183], v[118:121]
	v_mfma_f32_16x16x32_bf16 v[114:117], v[172:175], v[180:183], v[114:117]
	v_mfma_f32_16x16x32_bf16 v[102:105], v[164:167], v[188:191], v[102:105]
	v_mfma_f32_16x16x32_bf16 v[98:101], v[172:175], v[188:191], v[98:101]
	v_mfma_f32_16x16x32_bf16 v[86:89], v[164:167], v[196:199], v[86:89]
	v_mfma_f32_16x16x32_bf16 v[82:85], v[172:175], v[196:199], v[82:85]
	v_mfma_f32_16x16x32_bf16 v[70:73], v[164:167], v[204:207], v[70:73]
	v_mfma_f32_16x16x32_bf16 v[66:69], v[172:175], v[204:207], v[66:69]
	v_mfma_f32_16x16x32_bf16 v[118:121], v[168:171], v[184:187], v[118:121]
	v_mfma_f32_16x16x32_bf16 v[114:117], v[176:179], v[184:187], v[114:117]
	v_mfma_f32_16x16x32_bf16 v[102:105], v[168:171], v[192:195], v[102:105]
	v_mfma_f32_16x16x32_bf16 v[98:101], v[176:179], v[192:195], v[98:101]
	v_mfma_f32_16x16x32_bf16 v[86:89], v[168:171], v[200:203], v[86:89]
	v_mfma_f32_16x16x32_bf16 v[82:85], v[176:179], v[200:203], v[82:85]
	v_mfma_f32_16x16x32_bf16 v[70:73], v[168:171], v[208:211], v[70:73]
	s_setprio 2
	s_barrier
	v_mfma_f32_16x16x32_bf16 v[66:69], v[176:179], v[208:211], v[66:69]
	s_setprio 0
	ds_read_b128 v[180:183], v147 offset:16384
	ds_read_b128 v[184:187], v147 offset:17408
	ds_read_b128 v[188:191], v147 offset:18432
	ds_read_b128 v[192:195], v147 offset:19456
	ds_read_b128 v[196:199], v147 offset:20480
	ds_read_b128 v[200:203], v147 offset:21504
	ds_read_b128 v[204:207], v147 offset:22528
	ds_read_b128 v[252:255], v147 offset:23552
	s_mov_b32 m0, s64
	s_nop 0
	global_load_lds_dwordx4 v140, s[66:67]
	s_add_u32 s58, s66, 0x2b0000
	s_mov_b32 m0, s65
	s_nop 0
	global_load_lds_dwordx4 v142, s[66:67]
	s_addc_u32 s59, s67, 0
	s_mov_b32 m0, s82
	s_nop 0
	global_load_lds_dwordx4 v140, s[58:59]
	s_nop 0
	s_mov_b32 m0, s83
	s_nop 0
	global_load_lds_dwordx4 v142, s[58:59]
	s_nop 0
	s_mov_b32 m0, s35
	s_nop 0
	global_load_lds_dwordx4 v1, s[76:77]
	s_nop 0
	s_mov_b32 m0, s84
	s_nop 0
	global_load_lds_dwordx4 v141, s[76:77]
	s_waitcnt vmcnt(8)
	s_waitcnt lgkmcnt(0)
	s_barrier
	s_setprio 1
	s_waitcnt lgkmcnt(7)
	v_mfma_f32_16x16x32_bf16 v[62:65], v[134:137], v[180:183], v[62:65]
	v_mfma_f32_16x16x32_bf16 v[58:61], v[156:159], v[180:183], v[58:61]
	s_waitcnt lgkmcnt(5)
	v_mfma_f32_16x16x32_bf16 v[46:49], v[134:137], v[188:191], v[46:49]
	v_mfma_f32_16x16x32_bf16 v[42:45], v[156:159], v[188:191], v[42:45]
	s_waitcnt lgkmcnt(3)
	v_mfma_f32_16x16x32_bf16 v[30:33], v[134:137], v[196:199], v[30:33]
	v_mfma_f32_16x16x32_bf16 v[26:29], v[156:159], v[196:199], v[26:29]
	s_waitcnt lgkmcnt(1)
	v_mfma_f32_16x16x32_bf16 v[14:17], v[134:137], v[204:207], v[14:17]
	v_mfma_f32_16x16x32_bf16 v[10:13], v[156:159], v[204:207], v[10:13]
	v_mfma_f32_16x16x32_bf16 v[62:65], v[152:155], v[184:187], v[62:65]
	v_mfma_f32_16x16x32_bf16 v[58:61], v[160:163], v[184:187], v[58:61]
	v_mfma_f32_16x16x32_bf16 v[46:49], v[152:155], v[192:195], v[46:49]
	v_mfma_f32_16x16x32_bf16 v[42:45], v[160:163], v[192:195], v[42:45]
	v_mfma_f32_16x16x32_bf16 v[30:33], v[152:155], v[200:203], v[30:33]
	v_mfma_f32_16x16x32_bf16 v[26:29], v[160:163], v[200:203], v[26:29]
	s_waitcnt lgkmcnt(0)
	v_mfma_f32_16x16x32_bf16 v[14:17], v[152:155], v[252:255], v[14:17]
	v_mfma_f32_16x16x32_bf16 v[10:13], v[160:163], v[252:255], v[10:13]
	s_setprio 0
	s_setprio 1
	v_mfma_f32_16x16x32_bf16 v[54:57], v[164:167], v[180:183], v[54:57]
	v_mfma_f32_16x16x32_bf16 v[50:53], v[172:175], v[180:183], v[50:53]
	v_mfma_f32_16x16x32_bf16 v[38:41], v[164:167], v[188:191], v[38:41]
	v_mfma_f32_16x16x32_bf16 v[34:37], v[172:175], v[188:191], v[34:37]
	v_mfma_f32_16x16x32_bf16 v[22:25], v[164:167], v[196:199], v[22:25]
	v_mfma_f32_16x16x32_bf16 v[18:21], v[172:175], v[196:199], v[18:21]
	v_mfma_f32_16x16x32_bf16 v[6:9], v[164:167], v[204:207], v[6:9]
	v_mfma_f32_16x16x32_bf16 v[2:5], v[172:175], v[204:207], v[2:5]
	v_mfma_f32_16x16x32_bf16 v[54:57], v[168:171], v[184:187], v[54:57]
	v_mfma_f32_16x16x32_bf16 v[50:53], v[176:179], v[184:187], v[50:53]
	v_mfma_f32_16x16x32_bf16 v[38:41], v[168:171], v[192:195], v[38:41]
	v_mfma_f32_16x16x32_bf16 v[34:37], v[176:179], v[192:195], v[34:37]
	v_mfma_f32_16x16x32_bf16 v[22:25], v[168:171], v[200:203], v[22:25]
	v_mfma_f32_16x16x32_bf16 v[18:21], v[176:179], v[200:203], v[18:21]
	v_mfma_f32_16x16x32_bf16 v[6:9], v[168:171], v[252:255], v[6:9]
	s_setprio 2
	s_barrier
; #define PG8_STAGE(bufoff, gbase, voff) do { _Pragma("unroll") for (int _i = 0; _i < 2; ++_i) \
;         asm volatile("s_mov_b32 m0, %2\n\ts_nop 0\n\tglobal_load_lds_dwordx4 %0, %1" :: "v"((voff)[_i]), "s"((const char*)(gbase)), "s"(ldsbase + (unsigned)(bufoff) + ldsw + (unsigned)_i * 8192u) : "memory", "m0"); } while (0)
; #define PG8_LDA(dst, b, h) do { _Pragma("unroll") for (int m = 0; m < 4; ++m) _Pragma("unroll") for (int k = 0; k < 2; ++k) dst[m][k] = *(const PG8_LAS bf16x8*)(lds + PG8_SA(b, h) + aoff + m * 2048 + k * 1024); } while (0)
; #define PG8_LDB(dst, b, h) do { _Pragma("unroll") for (int n = 0; n < 2; ++n) _Pragma("unroll") for (int k = 0; k < 2; ++k) dst[n][k] = *(const PG8_LAS bf16x8*)(lds + PG8_SB(b, h) + boff + n * 2048 + k * 1024); } while (0)
; #define PG8_MMA(ai, bj, At, Bt) do { __builtin_amdgcn_s_setprio(1); _Pragma("unroll") for (int m = 0; m < 4; ++m) _Pragma("unroll") for (int n = 0; n < 2; ++n) _Pragma("unroll") for (int k = 0; k < 2; ++k) \
;         acc[ai][bj][m][n] = __builtin_amdgcn_mfma_f32_16x16x32_bf16(Bt[n][k], At[m][k], acc[ai][bj][m][n], 0, 0, 0); __builtin_amdgcn_s_setprio(0); } while (0)
; #define PG8_WAIT_V(n) asm volatile("s_waitcnt vmcnt(" #n ")" ::: "memory")
; #define PG8_WAIT_L(n) asm volatile("s_waitcnt lgkmcnt(" #n ")" ::: "memory")
; #define PG8_BAR __builtin_amdgcn_s_barrier()
; #define PG8_SCHED __builtin_amdgcn_sched_barrier(0)
; template <class Epi, class Sched, bool ALIGN_EPI = false, bool SP2 = false>
; __device__ __forceinline__ void gemm_phase(PG8_LAS unsigned char* lds, const Gemm g, const Sched& S, const Epi& E) {
;     ...
;             PG8_LDB(B0, 1, 0); PG8_LDB(B1, 1, 1); PG8_SCHED; PG8_LDA(At, 1, 0); PG8_STAGE(PG8_SA(0, 1), a2 + hstep, voffA);
;             PG8_WAIT_V(8); PG8_WAIT_L(0); PG8_BAR; PG8_MMA(0, 0, At, B0); PG8_MMA(0, 1, At, B1); PG8_BAR; PG8_SCHED;
	v_mfma_f32_16x16x32_bf16 v[2:5], v[176:179], v[252:255], v[2:5]
	s_setprio 0
	ds_read_b128 v[134:137], v148
	ds_read_b128 v[152:155], v148 offset:1024
	ds_read_b128 v[156:159], v148 offset:2048
	ds_read_b128 v[160:163], v148 offset:3072
	ds_read_b128 v[164:167], v149
	ds_read_b128 v[168:171], v149 offset:1024
	ds_read_b128 v[172:175], v149 offset:2048
	ds_read_b128 v[248:251], v149 offset:3072
	ds_read_b128 v[180:183], v147 offset:32768
	ds_read_b128 v[184:187], v147 offset:33792
	ds_read_b128 v[188:191], v147 offset:34816
	ds_read_b128 v[192:195], v147 offset:35840
	ds_read_b128 v[196:199], v147 offset:36864
	ds_read_b128 v[200:203], v147 offset:37888
	ds_read_b128 v[204:207], v147 offset:38912
	ds_read_b128 v[208:211], v147 offset:39936
	s_add_u32 s58, s76, 0x2b0000
	s_addc_u32 s59, s77, 0
	s_mov_b32 m0, s85
	s_nop 0
	global_load_lds_dwordx4 v1, s[58:59]
	s_nop 0
	s_mov_b32 m0, s86
	s_nop 0
	global_load_lds_dwordx4 v141, s[58:59]
	s_waitcnt vmcnt(8)
	s_waitcnt lgkmcnt(0)
	s_barrier
	s_setprio 1
	s_waitcnt lgkmcnt(7)
	v_mfma_f32_16x16x32_bf16 v[126:129], v[134:137], v[180:183], v[126:129]
	v_mfma_f32_16x16x32_bf16 v[122:125], v[156:159], v[180:183], v[122:125]
	s_waitcnt lgkmcnt(5)
	v_mfma_f32_16x16x32_bf16 v[110:113], v[134:137], v[188:191], v[110:113]
	v_mfma_f32_16x16x32_bf16 v[106:109], v[156:159], v[188:191], v[106:109]
	s_waitcnt lgkmcnt(3)
	v_mfma_f32_16x16x32_bf16 v[94:97], v[134:137], v[196:199], v[94:97]
	v_mfma_f32_16x16x32_bf16 v[90:93], v[156:159], v[196:199], v[90:93]
	s_waitcnt lgkmcnt(1)
	v_mfma_f32_16x16x32_bf16 v[78:81], v[134:137], v[204:207], v[78:81]
	v_mfma_f32_16x16x32_bf16 v[74:77], v[156:159], v[204:207], v[74:77]
	v_mfma_f32_16x16x32_bf16 v[126:129], v[152:155], v[184:187], v[126:129]
	v_mfma_f32_16x16x32_bf16 v[122:125], v[160:163], v[184:187], v[122:125]
	v_mfma_f32_16x16x32_bf16 v[110:113], v[152:155], v[192:195], v[110:113]
	v_mfma_f32_16x16x32_bf16 v[106:109], v[160:163], v[192:195], v[106:109]
	v_mfma_f32_16x16x32_bf16 v[94:97], v[152:155], v[200:203], v[94:97]
	v_mfma_f32_16x16x32_bf16 v[90:93], v[160:163], v[200:203], v[90:93]
	s_waitcnt lgkmcnt(0)
	v_mfma_f32_16x16x32_bf16 v[78:81], v[152:155], v[208:211], v[78:81]
	v_mfma_f32_16x16x32_bf16 v[74:77], v[160:163], v[208:211], v[74:77]
	s_setprio 0
	s_setprio 1
	v_mfma_f32_16x16x32_bf16 v[118:121], v[164:167], v[180:183], v[118:121]
	v_mfma_f32_16x16x32_bf16 v[114:117], v[172:175], v[180:183], v[114:117]
	v_mfma_f32_16x16x32_bf16 v[102:105], v[164:167], v[188:191], v[102:105]
	v_mfma_f32_16x16x32_bf16 v[98:101], v[172:175], v[188:191], v[98:101]
	v_mfma_f32_16x16x32_bf16 v[86:89], v[164:167], v[196:199], v[86:89]
	v_mfma_f32_16x16x32_bf16 v[82:85], v[172:175], v[196:199], v[82:85]
	v_mfma_f32_16x16x32_bf16 v[70:73], v[164:167], v[204:207], v[70:73]
	v_mfma_f32_16x16x32_bf16 v[66:69], v[172:175], v[204:207], v[66:69]
	v_mfma_f32_16x16x32_bf16 v[118:121], v[168:171], v[184:187], v[118:121]
	v_mfma_f32_16x16x32_bf16 v[114:117], v[248:251], v[184:187], v[114:117]
	v_mfma_f32_16x16x32_bf16 v[102:105], v[168:171], v[192:195], v[102:105]
	v_mfma_f32_16x16x32_bf16 v[98:101], v[248:251], v[192:195], v[98:101]
	v_mfma_f32_16x16x32_bf16 v[86:89], v[168:171], v[200:203], v[86:89]
	v_mfma_f32_16x16x32_bf16 v[82:85], v[248:251], v[200:203], v[82:85]
	v_mfma_f32_16x16x32_bf16 v[70:73], v[168:171], v[208:211], v[70:73]
	s_setprio 2
	s_barrier
; #define PG8_STAGE(bufoff, gbase, voff) do { _Pragma("unroll") for (int _i = 0; _i < 2; ++_i) \
;         asm volatile("s_mov_b32 m0, %2\n\ts_nop 0\n\tglobal_load_lds_dwordx4 %0, %1" :: "v"((voff)[_i]), "s"((const char*)(gbase)), "s"(ldsbase + (unsigned)(bufoff) + ldsw + (unsigned)_i * 8192u) : "memory", "m0"); } while (0)
; #define PG8_LDA(dst, b, h) do { _Pragma("unroll") for (int m = 0; m < 4; ++m) _Pragma("unroll") for (int k = 0; k < 2; ++k) dst[m][k] = *(const PG8_LAS bf16x8*)(lds + PG8_SA(b, h) + aoff + m * 2048 + k * 1024); } while (0)
; #define PG8_MMA(ai, bj, At, Bt) do { __builtin_amdgcn_s_setprio(1); _Pragma("unroll") for (int m = 0; m < 4; ++m) _Pragma("unroll") for (int n = 0; n < 2; ++n) _Pragma("unroll") for (int k = 0; k < 2; ++k) \
;         acc[ai][bj][m][n] = __builtin_amdgcn_mfma_f32_16x16x32_bf16(Bt[n][k], At[m][k], acc[ai][bj][m][n], 0, 0, 0); __builtin_amdgcn_s_setprio(0); } while (0)
; #define PG8_WAIT_V(n) asm volatile("s_waitcnt vmcnt(" #n ")" ::: "memory")
; #define PG8_WAIT_L(n) asm volatile("s_waitcnt lgkmcnt(" #n ")" ::: "memory")
; #define PG8_BAR __builtin_amdgcn_s_barrier()
; #define PG8_SCHED __builtin_amdgcn_sched_barrier(0)
; template <class Epi, class Sched, bool ALIGN_EPI = false, bool SP2 = false>
; __device__ __forceinline__ void gemm_phase(PG8_LAS unsigned char* lds, const Gemm g, const Sched& S, const Epi& E) {
;     ...
;             PG8_LDA(At, 1, 1); PG8_STAGE(PG8_SB(1, 0), b3, voffB); PG8_STAGE(PG8_SB(1, 1), b3 + hstep, voffB); PG8_STAGE(PG8_SA(1, 0), a3, voffA);
;             PG8_WAIT_V(8); PG8_WAIT_L(0); PG8_BAR; PG8_MMA(1, 0, At, B0); PG8_MMA(1, 1, At, B1); PG8_BAR; PG8_SCHED;
	v_mfma_f32_16x16x32_bf16 v[66:69], v[248:251], v[208:211], v[66:69]
	s_setprio 0
	ds_read_b128 v[180:183], v147 offset:49152
	ds_read_b128 v[184:187], v147 offset:50176
	ds_read_b128 v[188:191], v147 offset:51200
	ds_read_b128 v[192:195], v147 offset:52224
	ds_read_b128 v[196:199], v147 offset:53248
	ds_read_b128 v[200:203], v147 offset:54272
	ds_read_b128 v[204:207], v147 offset:55296
	ds_read_b128 v[252:255], v147 offset:56320
	s_add_u32 s58, s66, 0x80
	s_addc_u32 s59, s67, 0
	s_mov_b32 m0, s88
	s_nop 0
	global_load_lds_dwordx4 v140, s[58:59]
	s_nop 0
	s_mov_b32 m0, s89
	s_nop 0
	global_load_lds_dwordx4 v142, s[58:59]
	s_add_u32 s58, s66, 0x2b0080
	s_addc_u32 s59, s67, 0
	s_mov_b32 m0, s92
	s_nop 0
	global_load_lds_dwordx4 v140, s[58:59]
	s_nop 0
	s_mov_b32 m0, s93
	s_nop 0
	global_load_lds_dwordx4 v142, s[58:59]
	s_nop 0
	s_mov_b32 m0, s90
	s_nop 0
	global_load_lds_dwordx4 v1, s[62:63]
	s_nop 0
	s_mov_b32 m0, s91
	s_nop 0
	global_load_lds_dwordx4 v141, s[62:63]
	s_waitcnt vmcnt(8)
	s_waitcnt lgkmcnt(0)
	s_barrier
	s_setprio 1
	s_waitcnt lgkmcnt(7)
	v_mfma_f32_16x16x32_bf16 v[62:65], v[134:137], v[180:183], v[62:65]
	v_mfma_f32_16x16x32_bf16 v[58:61], v[156:159], v[180:183], v[58:61]
	s_waitcnt lgkmcnt(5)
	v_mfma_f32_16x16x32_bf16 v[46:49], v[134:137], v[188:191], v[46:49]
	v_mfma_f32_16x16x32_bf16 v[42:45], v[156:159], v[188:191], v[42:45]
	s_waitcnt lgkmcnt(3)
	v_mfma_f32_16x16x32_bf16 v[30:33], v[134:137], v[196:199], v[30:33]
	v_mfma_f32_16x16x32_bf16 v[26:29], v[156:159], v[196:199], v[26:29]
	s_waitcnt lgkmcnt(1)
	v_mfma_f32_16x16x32_bf16 v[14:17], v[134:137], v[204:207], v[14:17]
	v_mfma_f32_16x16x32_bf16 v[10:13], v[156:159], v[204:207], v[10:13]
	v_mfma_f32_16x16x32_bf16 v[62:65], v[152:155], v[184:187], v[62:65]
	v_mfma_f32_16x16x32_bf16 v[58:61], v[160:163], v[184:187], v[58:61]
	v_mfma_f32_16x16x32_bf16 v[46:49], v[152:155], v[192:195], v[46:49]
	v_mfma_f32_16x16x32_bf16 v[42:45], v[160:163], v[192:195], v[42:45]
	v_mfma_f32_16x16x32_bf16 v[30:33], v[152:155], v[200:203], v[30:33]
	v_mfma_f32_16x16x32_bf16 v[26:29], v[160:163], v[200:203], v[26:29]
	s_waitcnt lgkmcnt(0)
	v_mfma_f32_16x16x32_bf16 v[14:17], v[152:155], v[252:255], v[14:17]
	v_mfma_f32_16x16x32_bf16 v[10:13], v[160:163], v[252:255], v[10:13]
	s_setprio 0
	s_setprio 1
	v_mfma_f32_16x16x32_bf16 v[54:57], v[164:167], v[180:183], v[54:57]
	v_mfma_f32_16x16x32_bf16 v[50:53], v[172:175], v[180:183], v[50:53]
	v_mfma_f32_16x16x32_bf16 v[38:41], v[164:167], v[188:191], v[38:41]
	v_mfma_f32_16x16x32_bf16 v[34:37], v[172:175], v[188:191], v[34:37]
	v_mfma_f32_16x16x32_bf16 v[22:25], v[164:167], v[196:199], v[22:25]
	v_mfma_f32_16x16x32_bf16 v[18:21], v[172:175], v[196:199], v[18:21]
	v_mfma_f32_16x16x32_bf16 v[6:9], v[164:167], v[204:207], v[6:9]
	v_mfma_f32_16x16x32_bf16 v[2:5], v[172:175], v[204:207], v[2:5]
	v_mfma_f32_16x16x32_bf16 v[54:57], v[168:171], v[184:187], v[54:57]
	v_mfma_f32_16x16x32_bf16 v[50:53], v[248:251], v[184:187], v[50:53]
	v_mfma_f32_16x16x32_bf16 v[38:41], v[168:171], v[192:195], v[38:41]
	v_mfma_f32_16x16x32_bf16 v[34:37], v[248:251], v[192:195], v[34:37]
	v_mfma_f32_16x16x32_bf16 v[22:25], v[168:171], v[200:203], v[22:25]
	v_mfma_f32_16x16x32_bf16 v[18:21], v[248:251], v[200:203], v[18:21]
	v_mfma_f32_16x16x32_bf16 v[6:9], v[168:171], v[252:255], v[6:9]
	s_setprio 2
	s_barrier
	v_mfma_f32_16x16x32_bf16 v[2:5], v[248:251], v[252:255], v[2:5]
	s_setprio 0
	s_add_i32 s57, s57, 2
	s_add_u32 s53, s53, 0x100
	s_addc_u32 s54, s54, 0
	s_add_u32 s55, s55, 0x100
	s_addc_u32 s56, s56, 0
	s_add_u32 s50, s50, 0x100
	s_addc_u32 s51, s51, 0
	s_cmpk_gt_u32 s57, 0xa9
	s_cbranch_scc0 .LBB0_234
	s_and_b64 vcc, exec, s[16:17]
	s_cbranch_vccz .LBB0_237
	s_barrier

; #define PG8_STAGE(bufoff, gbase, voff) do { _Pragma("unroll") for (int _i = 0; _i < 2; ++_i) \
;         asm volatile("s_mov_b32 m0, %2\n\ts_nop 0\n\tglobal_load_lds_dwordx4 %0, %1" :: "v"((voff)[_i]), "s"((const char*)(gbase)), "s"(ldsbase + (unsigned)(bufoff) + ldsw + (unsigned)_i * 8192u) : "memory", "m0"); } while (0)
; #define PG8_LDA(dst, b, h) do { _Pragma("unroll") for (int m = 0; m < 4; ++m) _Pragma("unroll") for (int k = 0; k < 2; ++k) dst[m][k] = *(const PG8_LAS bf16x8*)(lds + PG8_SA(b, h) + aoff + m * 2048 + k * 1024); } while (0)
; #define PG8_LDB(dst, b, h) do { _Pragma("unroll") for (int n = 0; n < 2; ++n) _Pragma("unroll") for (int k = 0; k < 2; ++k) dst[n][k] = *(const PG8_LAS bf16x8*)(lds + PG8_SB(b, h) + boff + n * 2048 + k * 1024); } while (0)
; #define PG8_MMA(ai, bj, At, Bt) do { __builtin_amdgcn_s_setprio(1); _Pragma("unroll") for (int m = 0; m < 4; ++m) _Pragma("unroll") for (int n = 0; n < 2; ++n) _Pragma("unroll") for (int k = 0; k < 2; ++k) \
;         acc[ai][bj][m][n] = __builtin_amdgcn_mfma_f32_16x16x32_bf16(Bt[n][k], At[m][k], acc[ai][bj][m][n], 0, 0, 0); __builtin_amdgcn_s_setprio(0); } while (0)
; template <class Epi, class Sched, bool ALIGN_EPI = false, bool SP2 = false>
; __device__ __forceinline__ void gemm_phase(PG8_LAS unsigned char* lds, const Gemm g, const Sched& S, const Epi& E) {
;     ...
;             const bool last = (t == nt - 2);
;             const char* a1 = cA + (size_t)(t + 1) * kstep;
;             const char* a2 = last ? nA : cA + (size_t)(t + 2) * kstep; const char* b2 = last ? nB : cB + (size_t)(t + 2) * kstep;
;             const char* a3 = a2 + kstep; const char* b3 = b2 + kstep;
;             if (last && has_next) S.a_ready(nxt);
;             if constexpr (epi_has_mid<Epi>::value) { if (t == Epi::MID_T) E.mid(acc, cur, wr, wc, fr, fq); }
;             if constexpr (SP2) {
;             PG8_LDB(B0, 0, 0); PG8_LDB(B1, 0, 1); PG8_SCHED; PG8_LDA(At, 0, 0); PG8_STAGE(PG8_SA(1, 1), a1 + hstep, voffA);
;             PG8_WAIT_V(8); PG8_WAIT_L(0); PG8_BAR; PG8_MMA(0, 0, At, B0); PG8_MMA(0, 1, At, B1); PG8_BAR; PG8_SCHED;
;             PG8_LDA(At, 0, 1); PG8_STAGE(PG8_SB(0, 0), b2, voffB); PG8_STAGE(PG8_SB(0, 1), b2 + hstep, voffB); PG8_STAGE(PG8_SA(0, 0), a2, voffA);
;             PG8_WAIT_V(8); PG8_WAIT_L(0); PG8_BAR; PG8_MMA(1, 0, At, B0); PG8_MMA(1, 1, At, B1); PG8_BAR; PG8_SCHED;
.LBB0_325:
	v_add_u32_e32 v138, 0x10000, v151
	ds_read_b128 v[154:157], v138
	ds_read_b128 v[158:161], v138 offset:1024
	ds_read_b128 v[162:165], v138 offset:2048
	ds_read_b128 v[166:169], v138 offset:3072
	v_add_u32_e32 v138, 0x14000, v151
	s_add_u32 s8, s82, 0x100
	ds_read_b128 v[170:173], v138
	ds_read_b128 v[174:177], v138 offset:1024
	ds_read_b128 v[178:181], v138 offset:2048
	ds_read_b128 v[182:185], v138 offset:3072
	s_addc_u32 s9, s83, 0
	s_and_b64 s[60:61], s[62:63], exec
	s_cselect_b32 s84, s54, s8
	s_cselect_b32 s85, s19, s9
	s_cselect_b32 s63, s17, s57
	s_cselect_b32 s62, s55, s56
	s_add_u32 s66, s84, 0x80
	s_addc_u32 s67, s85, 0
	s_add_u32 s76, s62, 0x80
	s_addc_u32 s77, s63, 0
	ds_read_b128 v[186:189], v152
	ds_read_b128 v[190:193], v152 offset:1024
	ds_read_b128 v[194:197], v152 offset:2048
	ds_read_b128 v[198:201], v152 offset:3072
	ds_read_b128 v[202:205], v152 offset:4096
	ds_read_b128 v[206:209], v152 offset:5120
	ds_read_b128 v[210:213], v152 offset:6144
	ds_read_b128 v[214:217], v152 offset:7168
	s_add_u32 s60, s82, 0x100080
	s_addc_u32 s61, s83, 0
	s_mov_b32 m0, s97
	s_nop 0
	global_load_lds_dwordx4 v141, s[60:61]
	s_nop 0
	s_mov_b32 m0, s70
	s_nop 0
	global_load_lds_dwordx4 v143, s[60:61]
	s_waitcnt vmcnt(8)
	s_waitcnt lgkmcnt(0)
	s_barrier
	s_setprio 1
	s_waitcnt lgkmcnt(7)
	v_mfma_f32_16x16x32_bf16 v[126:129], v[154:157], v[186:189], v[126:129]
	v_mfma_f32_16x16x32_bf16 v[122:125], v[162:165], v[186:189], v[122:125]
	s_waitcnt lgkmcnt(5)
	v_mfma_f32_16x16x32_bf16 v[110:113], v[154:157], v[194:197], v[110:113]
	v_mfma_f32_16x16x32_bf16 v[106:109], v[162:165], v[194:197], v[106:109]
	s_waitcnt lgkmcnt(3)
	v_mfma_f32_16x16x32_bf16 v[94:97], v[154:157], v[202:205], v[94:97]
	v_mfma_f32_16x16x32_bf16 v[90:93], v[162:165], v[202:205], v[90:93]
	s_waitcnt lgkmcnt(1)
	v_mfma_f32_16x16x32_bf16 v[78:81], v[154:157], v[210:213], v[78:81]
	v_mfma_f32_16x16x32_bf16 v[74:77], v[162:165], v[210:213], v[74:77]
	v_mfma_f32_16x16x32_bf16 v[126:129], v[158:161], v[190:193], v[126:129]
	v_mfma_f32_16x16x32_bf16 v[122:125], v[166:169], v[190:193], v[122:125]
	v_mfma_f32_16x16x32_bf16 v[110:113], v[158:161], v[198:201], v[110:113]
	v_mfma_f32_16x16x32_bf16 v[106:109], v[166:169], v[198:201], v[106:109]
	v_mfma_f32_16x16x32_bf16 v[94:97], v[158:161], v[206:209], v[94:97]
	v_mfma_f32_16x16x32_bf16 v[90:93], v[166:169], v[206:209], v[90:93]
	s_waitcnt lgkmcnt(0)
	v_mfma_f32_16x16x32_bf16 v[78:81], v[158:161], v[214:217], v[78:81]
	v_mfma_f32_16x16x32_bf16 v[74:77], v[166:169], v[214:217], v[74:77]
	s_setprio 0
	s_setprio 1
	v_mfma_f32_16x16x32_bf16 v[118:121], v[170:173], v[186:189], v[118:121]
	v_mfma_f32_16x16x32_bf16 v[114:117], v[178:181], v[186:189], v[114:117]
	v_mfma_f32_16x16x32_bf16 v[102:105], v[170:173], v[194:197], v[102:105]
	v_mfma_f32_16x16x32_bf16 v[98:101], v[178:181], v[194:197], v[98:101]
	v_mfma_f32_16x16x32_bf16 v[86:89], v[170:173], v[202:205], v[86:89]
	v_mfma_f32_16x16x32_bf16 v[82:85], v[178:181], v[202:205], v[82:85]
	v_mfma_f32_16x16x32_bf16 v[70:73], v[170:173], v[210:213], v[70:73]
	v_mfma_f32_16x16x32_bf16 v[66:69], v[178:181], v[210:213], v[66:69]
	v_mfma_f32_16x16x32_bf16 v[118:121], v[174:177], v[190:193], v[118:121]
	v_mfma_f32_16x16x32_bf16 v[114:117], v[182:185], v[190:193], v[114:117]
	v_mfma_f32_16x16x32_bf16 v[102:105], v[174:177], v[198:201], v[102:105]
	v_mfma_f32_16x16x32_bf16 v[98:101], v[182:185], v[198:201], v[98:101]
	v_mfma_f32_16x16x32_bf16 v[86:89], v[174:177], v[206:209], v[86:89]
	v_mfma_f32_16x16x32_bf16 v[82:85], v[182:185], v[206:209], v[82:85]
	v_mfma_f32_16x16x32_bf16 v[70:73], v[174:177], v[214:217], v[70:73]
	s_setprio 2
	s_barrier
	v_mfma_f32_16x16x32_bf16 v[66:69], v[182:185], v[214:217], v[66:69]
	s_setprio 0
	ds_read_b128 v[186:189], v152 offset:16384
	ds_read_b128 v[190:193], v152 offset:17408
	ds_read_b128 v[194:197], v152 offset:18432
	ds_read_b128 v[198:201], v152 offset:19456
	ds_read_b128 v[202:205], v152 offset:20480
	ds_read_b128 v[206:209], v152 offset:21504
	ds_read_b128 v[210:213], v152 offset:22528
	ds_read_b128 v[252:255], v152 offset:23552
	s_mov_b32 m0, s68
	s_nop 0
	global_load_lds_dwordx4 v142, s[62:63]
	s_add_u32 s60, s62, 0x100000
	s_mov_b32 m0, s69
	s_nop 0
	global_load_lds_dwordx4 v144, s[62:63]
	s_addc_u32 s61, s63, 0
	s_mov_b32 m0, s81
	s_nop 0
	global_load_lds_dwordx4 v142, s[60:61]
	s_nop 0
	s_mov_b32 m0, s86
	s_nop 0
	global_load_lds_dwordx4 v144, s[60:61]
	s_nop 0
	s_mov_b32 m0, s65
	s_nop 0
	global_load_lds_dwordx4 v141, s[84:85]
	s_nop 0
	s_mov_b32 m0, s87
	s_nop 0
	global_load_lds_dwordx4 v143, s[84:85]
	s_waitcnt vmcnt(8)
	s_waitcnt lgkmcnt(0)
	s_barrier
; #define PG8_STAGE(bufoff, gbase, voff) do { _Pragma("unroll") for (int _i = 0; _i < 2; ++_i) \
;         asm volatile("s_mov_b32 m0, %2\n\ts_nop 0\n\tglobal_load_lds_dwordx4 %0, %1" :: "v"((voff)[_i]), "s"((const char*)(gbase)), "s"(ldsbase + (unsigned)(bufoff) + ldsw + (unsigned)_i * 8192u) : "memory", "m0"); } while (0)
; #define PG8_LDA(dst, b, h) do { _Pragma("unroll") for (int m = 0; m < 4; ++m) _Pragma("unroll") for (int k = 0; k < 2; ++k) dst[m][k] = *(const PG8_LAS bf16x8*)(lds + PG8_SA(b, h) + aoff + m * 2048 + k * 1024); } while (0)
; #define PG8_LDB(dst, b, h) do { _Pragma("unroll") for (int n = 0; n < 2; ++n) _Pragma("unroll") for (int k = 0; k < 2; ++k) dst[n][k] = *(const PG8_LAS bf16x8*)(lds + PG8_SB(b, h) + boff + n * 2048 + k * 1024); } while (0)
; #define PG8_MMA(ai, bj, At, Bt) do { __builtin_amdgcn_s_setprio(1); _Pragma("unroll") for (int m = 0; m < 4; ++m) _Pragma("unroll") for (int n = 0; n < 2; ++n) _Pragma("unroll") for (int k = 0; k < 2; ++k) \
;         acc[ai][bj][m][n] = __builtin_amdgcn_mfma_f32_16x16x32_bf16(Bt[n][k], At[m][k], acc[ai][bj][m][n], 0, 0, 0); __builtin_amdgcn_s_setprio(0); } while (0)
; #define PG8_WAIT_V(n) asm volatile("s_waitcnt vmcnt(" #n ")" ::: "memory")
; #define PG8_WAIT_L(n) asm volatile("s_waitcnt lgkmcnt(" #n ")" ::: "memory")
; #define PG8_BAR __builtin_amdgcn_s_barrier()
; #define PG8_SCHED __builtin_amdgcn_sched_barrier(0)
; template <class Epi, class Sched, bool ALIGN_EPI = false, bool SP2 = false>
; __device__ __forceinline__ void gemm_phase(PG8_LAS unsigned char* lds, const Gemm g, const Sched& S, const Epi& E) {
;     ...
;             PG8_WAIT_V(8); PG8_WAIT_L(0); PG8_BAR; PG8_MMA(1, 0, At, B0); PG8_MMA(1, 1, At, B1); PG8_BAR; PG8_SCHED;
;             PG8_LDB(B0, 1, 0); PG8_LDB(B1, 1, 1); PG8_SCHED; PG8_LDA(At, 1, 0); PG8_STAGE(PG8_SA(0, 1), a2 + hstep, voffA);
;             PG8_WAIT_V(8); PG8_WAIT_L(0); PG8_BAR; PG8_MMA(0, 0, At, B0); PG8_MMA(0, 1, At, B1); PG8_BAR; PG8_SCHED;
	s_setprio 1
	s_waitcnt lgkmcnt(7)
	v_mfma_f32_16x16x32_bf16 v[62:65], v[154:157], v[186:189], v[62:65]
	v_mfma_f32_16x16x32_bf16 v[58:61], v[162:165], v[186:189], v[58:61]
	s_waitcnt lgkmcnt(5)
	v_mfma_f32_16x16x32_bf16 v[46:49], v[154:157], v[194:197], v[46:49]
	v_mfma_f32_16x16x32_bf16 v[42:45], v[162:165], v[194:197], v[42:45]
	s_waitcnt lgkmcnt(3)
	v_mfma_f32_16x16x32_bf16 v[30:33], v[154:157], v[202:205], v[30:33]
	v_mfma_f32_16x16x32_bf16 v[26:29], v[162:165], v[202:205], v[26:29]
	s_waitcnt lgkmcnt(1)
	v_mfma_f32_16x16x32_bf16 v[14:17], v[154:157], v[210:213], v[14:17]
	v_mfma_f32_16x16x32_bf16 v[10:13], v[162:165], v[210:213], v[10:13]
	v_mfma_f32_16x16x32_bf16 v[62:65], v[158:161], v[190:193], v[62:65]
	v_mfma_f32_16x16x32_bf16 v[58:61], v[166:169], v[190:193], v[58:61]
	v_mfma_f32_16x16x32_bf16 v[46:49], v[158:161], v[198:201], v[46:49]
	v_mfma_f32_16x16x32_bf16 v[42:45], v[166:169], v[198:201], v[42:45]
	v_mfma_f32_16x16x32_bf16 v[30:33], v[158:161], v[206:209], v[30:33]
	v_mfma_f32_16x16x32_bf16 v[26:29], v[166:169], v[206:209], v[26:29]
	s_waitcnt lgkmcnt(0)
	v_mfma_f32_16x16x32_bf16 v[14:17], v[158:161], v[252:255], v[14:17]
	v_mfma_f32_16x16x32_bf16 v[10:13], v[166:169], v[252:255], v[10:13]
	s_setprio 0
	s_setprio 1
	v_mfma_f32_16x16x32_bf16 v[54:57], v[170:173], v[186:189], v[54:57]
	v_mfma_f32_16x16x32_bf16 v[50:53], v[178:181], v[186:189], v[50:53]
	v_mfma_f32_16x16x32_bf16 v[38:41], v[170:173], v[194:197], v[38:41]
	v_mfma_f32_16x16x32_bf16 v[34:37], v[178:181], v[194:197], v[34:37]
	v_mfma_f32_16x16x32_bf16 v[22:25], v[170:173], v[202:205], v[22:25]
	v_mfma_f32_16x16x32_bf16 v[18:21], v[178:181], v[202:205], v[18:21]
	v_mfma_f32_16x16x32_bf16 v[6:9], v[170:173], v[210:213], v[6:9]
	v_mfma_f32_16x16x32_bf16 v[2:5], v[178:181], v[210:213], v[2:5]
	v_mfma_f32_16x16x32_bf16 v[54:57], v[174:177], v[190:193], v[54:57]
	v_mfma_f32_16x16x32_bf16 v[50:53], v[182:185], v[190:193], v[50:53]
	v_mfma_f32_16x16x32_bf16 v[38:41], v[174:177], v[198:201], v[38:41]
	v_mfma_f32_16x16x32_bf16 v[34:37], v[182:185], v[198:201], v[34:37]
	v_mfma_f32_16x16x32_bf16 v[22:25], v[174:177], v[206:209], v[22:25]
	v_mfma_f32_16x16x32_bf16 v[18:21], v[182:185], v[206:209], v[18:21]
	v_mfma_f32_16x16x32_bf16 v[6:9], v[174:177], v[252:255], v[6:9]
	s_setprio 2
	s_barrier
	v_mfma_f32_16x16x32_bf16 v[2:5], v[182:185], v[252:255], v[2:5]
	s_setprio 0
	v_add_u32_e32 v138, 0x18000, v151
	ds_read_b128 v[154:157], v138
	ds_read_b128 v[158:161], v138 offset:1024
	ds_read_b128 v[162:165], v138 offset:2048
	ds_read_b128 v[166:169], v138 offset:3072
	v_add_u32_e32 v138, 0x1c000, v151
	ds_read_b128 v[170:173], v138
	ds_read_b128 v[174:177], v138 offset:1024
	ds_read_b128 v[178:181], v138 offset:2048
	ds_read_b128 v[248:251], v138 offset:3072
	ds_read_b128 v[186:189], v152 offset:32768
	ds_read_b128 v[190:193], v152 offset:33792
	ds_read_b128 v[194:197], v152 offset:34816
	ds_read_b128 v[198:201], v152 offset:35840
	ds_read_b128 v[202:205], v152 offset:36864
	ds_read_b128 v[206:209], v152 offset:37888
	ds_read_b128 v[210:213], v152 offset:38912
	ds_read_b128 v[214:217], v152 offset:39936
	s_add_u32 s60, s84, 0x100000
	s_addc_u32 s61, s85, 0
	s_mov_b32 m0, s88
	s_nop 0
	global_load_lds_dwordx4 v141, s[60:61]
	s_nop 0
	s_mov_b32 m0, s89
	s_nop 0
	global_load_lds_dwordx4 v143, s[60:61]
	s_waitcnt vmcnt(8)
	s_waitcnt lgkmcnt(0)
	s_barrier
	s_setprio 1
	s_waitcnt lgkmcnt(7)
	v_mfma_f32_16x16x32_bf16 v[126:129], v[154:157], v[186:189], v[126:129]
	v_mfma_f32_16x16x32_bf16 v[122:125], v[162:165], v[186:189], v[122:125]
	s_waitcnt lgkmcnt(5)
	v_mfma_f32_16x16x32_bf16 v[110:113], v[154:157], v[194:197], v[110:113]
	v_mfma_f32_16x16x32_bf16 v[106:109], v[162:165], v[194:197], v[106:109]
	s_waitcnt lgkmcnt(3)
	v_mfma_f32_16x16x32_bf16 v[94:97], v[154:157], v[202:205], v[94:97]
	v_mfma_f32_16x16x32_bf16 v[90:93], v[162:165], v[202:205], v[90:93]
	s_waitcnt lgkmcnt(1)
	v_mfma_f32_16x16x32_bf16 v[78:81], v[154:157], v[210:213], v[78:81]
	v_mfma_f32_16x16x32_bf16 v[74:77], v[162:165], v[210:213], v[74:77]
	v_mfma_f32_16x16x32_bf16 v[126:129], v[158:161], v[190:193], v[126:129]
	v_mfma_f32_16x16x32_bf16 v[122:125], v[166:169], v[190:193], v[122:125]
	v_mfma_f32_16x16x32_bf16 v[110:113], v[158:161], v[198:201], v[110:113]
	v_mfma_f32_16x16x32_bf16 v[106:109], v[166:169], v[198:201], v[106:109]
	v_mfma_f32_16x16x32_bf16 v[94:97], v[158:161], v[206:209], v[94:97]
	v_mfma_f32_16x16x32_bf16 v[90:93], v[166:169], v[206:209], v[90:93]
	s_waitcnt lgkmcnt(0)
	v_mfma_f32_16x16x32_bf16 v[78:81], v[158:161], v[214:217], v[78:81]
	v_mfma_f32_16x16x32_bf16 v[74:77], v[166:169], v[214:217], v[74:77]
	s_setprio 0
	s_setprio 1
	v_mfma_f32_16x16x32_bf16 v[118:121], v[170:173], v[186:189], v[118:121]
	v_mfma_f32_16x16x32_bf16 v[114:117], v[178:181], v[186:189], v[114:117]
	v_mfma_f32_16x16x32_bf16 v[102:105], v[170:173], v[194:197], v[102:105]
	v_mfma_f32_16x16x32_bf16 v[98:101], v[178:181], v[194:197], v[98:101]
	v_mfma_f32_16x16x32_bf16 v[86:89], v[170:173], v[202:205], v[86:89]
	v_mfma_f32_16x16x32_bf16 v[82:85], v[178:181], v[202:205], v[82:85]
	v_mfma_f32_16x16x32_bf16 v[70:73], v[170:173], v[210:213], v[70:73]
	v_mfma_f32_16x16x32_bf16 v[66:69], v[178:181], v[210:213], v[66:69]
	v_mfma_f32_16x16x32_bf16 v[118:121], v[174:177], v[190:193], v[118:121]
	v_mfma_f32_16x16x32_bf16 v[114:117], v[248:251], v[190:193], v[114:117]
	v_mfma_f32_16x16x32_bf16 v[102:105], v[174:177], v[198:201], v[102:105]
	v_mfma_f32_16x16x32_bf16 v[98:101], v[248:251], v[198:201], v[98:101]
	v_mfma_f32_16x16x32_bf16 v[86:89], v[174:177], v[206:209], v[86:89]
	v_mfma_f32_16x16x32_bf16 v[82:85], v[248:251], v[206:209], v[82:85]
	v_mfma_f32_16x16x32_bf16 v[70:73], v[174:177], v[214:217], v[70:73]
	s_setprio 2
	s_barrier
; #define PG8_STAGE(bufoff, gbase, voff) do { _Pragma("unroll") for (int _i = 0; _i < 2; ++_i) \
;         asm volatile("s_mov_b32 m0, %2\n\ts_nop 0\n\tglobal_load_lds_dwordx4 %0, %1" :: "v"((voff)[_i]), "s"((const char*)(gbase)), "s"(ldsbase + (unsigned)(bufoff) + ldsw + (unsigned)_i * 8192u) : "memory", "m0"); } while (0)
; #define PG8_LDA(dst, b, h) do { _Pragma("unroll") for (int m = 0; m < 4; ++m) _Pragma("unroll") for (int k = 0; k < 2; ++k) dst[m][k] = *(const PG8_LAS bf16x8*)(lds + PG8_SA(b, h) + aoff + m * 2048 + k * 1024); } while (0)
; #define PG8_MMA(ai, bj, At, Bt) do { __builtin_amdgcn_s_setprio(1); _Pragma("unroll") for (int m = 0; m < 4; ++m) _Pragma("unroll") for (int n = 0; n < 2; ++n) _Pragma("unroll") for (int k = 0; k < 2; ++k) \
;         acc[ai][bj][m][n] = __builtin_amdgcn_mfma_f32_16x16x32_bf16(Bt[n][k], At[m][k], acc[ai][bj][m][n], 0, 0, 0); __builtin_amdgcn_s_setprio(0); } while (0)
; #define PG8_WAIT_V(n) asm volatile("s_waitcnt vmcnt(" #n ")" ::: "memory")
; #define PG8_WAIT_L(n) asm volatile("s_waitcnt lgkmcnt(" #n ")" ::: "memory")
; #define PG8_BAR __builtin_amdgcn_s_barrier()
; #define PG8_SCHED __builtin_amdgcn_sched_barrier(0)
; template <class Epi, class Sched, bool ALIGN_EPI = false, bool SP2 = false>
; __device__ __forceinline__ void gemm_phase(PG8_LAS unsigned char* lds, const Gemm g, const Sched& S, const Epi& E) {
;     ...
;             PG8_LDA(At, 1, 1); PG8_STAGE(PG8_SB(1, 0), b3, voffB); PG8_STAGE(PG8_SB(1, 1), b3 + hstep, voffB); PG8_STAGE(PG8_SA(1, 0), a3, voffA);
;             PG8_WAIT_V(8); PG8_WAIT_L(0); PG8_BAR; PG8_MMA(1, 0, At, B0); PG8_MMA(1, 1, At, B1); PG8_BAR; PG8_SCHED;
	v_mfma_f32_16x16x32_bf16 v[66:69], v[248:251], v[214:217], v[66:69]
	s_setprio 0
	ds_read_b128 v[186:189], v152 offset:49152
	ds_read_b128 v[190:193], v152 offset:50176
	ds_read_b128 v[194:197], v152 offset:51200
	ds_read_b128 v[198:201], v152 offset:52224
	ds_read_b128 v[202:205], v152 offset:53248
	ds_read_b128 v[206:209], v152 offset:54272
	ds_read_b128 v[210:213], v152 offset:55296
	ds_read_b128 v[252:255], v152 offset:56320
	s_mov_b32 m0, s90
	s_nop 0
	global_load_lds_dwordx4 v142, s[76:77]
	s_add_u32 s60, s62, 0x100080
	s_mov_b32 m0, s91
	s_nop 0
	global_load_lds_dwordx4 v144, s[76:77]
	s_addc_u32 s61, s63, 0
	s_mov_b32 m0, s95
	s_nop 0
	global_load_lds_dwordx4 v142, s[60:61]
	s_nop 0
	s_mov_b32 m0, s96
	s_nop 0
	global_load_lds_dwordx4 v144, s[60:61]
	s_nop 0
	s_mov_b32 m0, s92
	s_nop 0
	global_load_lds_dwordx4 v141, s[66:67]
	s_nop 0
	s_mov_b32 m0, s94
	s_nop 0
	global_load_lds_dwordx4 v143, s[66:67]
	s_waitcnt vmcnt(8)
	s_waitcnt lgkmcnt(0)
	s_barrier
	s_setprio 1
	s_waitcnt lgkmcnt(7)
	v_mfma_f32_16x16x32_bf16 v[62:65], v[154:157], v[186:189], v[62:65]
	v_mfma_f32_16x16x32_bf16 v[58:61], v[162:165], v[186:189], v[58:61]
	s_waitcnt lgkmcnt(5)
	v_mfma_f32_16x16x32_bf16 v[46:49], v[154:157], v[194:197], v[46:49]
	v_mfma_f32_16x16x32_bf16 v[42:45], v[162:165], v[194:197], v[42:45]
	s_waitcnt lgkmcnt(3)
	v_mfma_f32_16x16x32_bf16 v[30:33], v[154:157], v[202:205], v[30:33]
	v_mfma_f32_16x16x32_bf16 v[26:29], v[162:165], v[202:205], v[26:29]
	s_waitcnt lgkmcnt(1)
	v_mfma_f32_16x16x32_bf16 v[14:17], v[154:157], v[210:213], v[14:17]
	v_mfma_f32_16x16x32_bf16 v[10:13], v[162:165], v[210:213], v[10:13]
	v_mfma_f32_16x16x32_bf16 v[62:65], v[158:161], v[190:193], v[62:65]
	v_mfma_f32_16x16x32_bf16 v[58:61], v[166:169], v[190:193], v[58:61]
	v_mfma_f32_16x16x32_bf16 v[46:49], v[158:161], v[198:201], v[46:49]
	v_mfma_f32_16x16x32_bf16 v[42:45], v[166:169], v[198:201], v[42:45]
	v_mfma_f32_16x16x32_bf16 v[30:33], v[158:161], v[206:209], v[30:33]
	v_mfma_f32_16x16x32_bf16 v[26:29], v[166:169], v[206:209], v[26:29]
	s_waitcnt lgkmcnt(0)
	v_mfma_f32_16x16x32_bf16 v[14:17], v[158:161], v[252:255], v[14:17]
	v_mfma_f32_16x16x32_bf16 v[10:13], v[166:169], v[252:255], v[10:13]
	s_setprio 0
	s_setprio 1
	v_mfma_f32_16x16x32_bf16 v[54:57], v[170:173], v[186:189], v[54:57]
	v_mfma_f32_16x16x32_bf16 v[50:53], v[178:181], v[186:189], v[50:53]
	v_mfma_f32_16x16x32_bf16 v[38:41], v[170:173], v[194:197], v[38:41]
	v_mfma_f32_16x16x32_bf16 v[34:37], v[178:181], v[194:197], v[34:37]
	v_mfma_f32_16x16x32_bf16 v[22:25], v[170:173], v[202:205], v[22:25]
	v_mfma_f32_16x16x32_bf16 v[18:21], v[178:181], v[202:205], v[18:21]
	v_mfma_f32_16x16x32_bf16 v[6:9], v[170:173], v[210:213], v[6:9]
	v_mfma_f32_16x16x32_bf16 v[2:5], v[178:181], v[210:213], v[2:5]
	v_mfma_f32_16x16x32_bf16 v[54:57], v[174:177], v[190:193], v[54:57]
	v_mfma_f32_16x16x32_bf16 v[50:53], v[248:251], v[190:193], v[50:53]
	v_mfma_f32_16x16x32_bf16 v[38:41], v[174:177], v[198:201], v[38:41]
	v_mfma_f32_16x16x32_bf16 v[34:37], v[248:251], v[198:201], v[34:37]
	v_mfma_f32_16x16x32_bf16 v[22:25], v[174:177], v[206:209], v[22:25]
	v_mfma_f32_16x16x32_bf16 v[18:21], v[248:251], v[206:209], v[18:21]
	v_mfma_f32_16x16x32_bf16 v[6:9], v[174:177], v[252:255], v[6:9]
	s_setprio 2
	s_barrier
	v_mfma_f32_16x16x32_bf16 v[2:5], v[248:251], v[252:255], v[2:5]
	s_setprio 0
	s_add_i32 s58, s58, 2
	s_add_u32 s56, s56, 0x100
	s_addc_u32 s57, s57, 0
	s_cmp_gt_u32 s58, 61
	s_cbranch_scc1 .LBB0_316
	s_mov_b64 s[82:83], s[8:9]
	s_branch .LBB0_320

; #define PG8_STAGE(bufoff, gbase, voff) do { _Pragma("unroll") for (int _i = 0; _i < 2; ++_i) \
;         asm volatile("s_mov_b32 m0, %2\n\ts_nop 0\n\tglobal_load_lds_dwordx4 %0, %1" :: "v"((voff)[_i]), "s"((const char*)(gbase)), "s"(ldsbase + (unsigned)(bufoff) + ldsw + (unsigned)_i * 8192u) : "memory", "m0"); } while (0)
; #define PG8_LDA(dst, b, h) do { _Pragma("unroll") for (int m = 0; m < 4; ++m) _Pragma("unroll") for (int k = 0; k < 2; ++k) dst[m][k] = *(const PG8_LAS bf16x8*)(lds + PG8_SA(b, h) + aoff + m * 2048 + k * 1024); } while (0)
; #define PG8_LDB(dst, b, h) do { _Pragma("unroll") for (int n = 0; n < 2; ++n) _Pragma("unroll") for (int k = 0; k < 2; ++k) dst[n][k] = *(const PG8_LAS bf16x8*)(lds + PG8_SB(b, h) + boff + n * 2048 + k * 1024); } while (0)
; #define PG8_MMA(ai, bj, At, Bt) do { __builtin_amdgcn_s_setprio(1); _Pragma("unroll") for (int m = 0; m < 4; ++m) _Pragma("unroll") for (int n = 0; n < 2; ++n) _Pragma("unroll") for (int k = 0; k < 2; ++k) \
;         acc[ai][bj][m][n] = __builtin_amdgcn_mfma_f32_16x16x32_bf16(Bt[n][k], At[m][k], acc[ai][bj][m][n], 0, 0, 0); __builtin_amdgcn_s_setprio(0); } while (0)
; template <class Epi, class Sched, bool ALIGN_EPI = false, bool SP2 = false>
; __device__ __forceinline__ void gemm_phase(PG8_LAS unsigned char* lds, const Gemm g, const Sched& S, const Epi& E) {
;     ...
;             const bool last = (t == nt - 2);
;             const char* a1 = cA + (size_t)(t + 1) * kstep;
;             const char* a2 = last ? nA : cA + (size_t)(t + 2) * kstep; const char* b2 = last ? nB : cB + (size_t)(t + 2) * kstep;
;             const char* a3 = a2 + kstep; const char* b3 = b2 + kstep;
;             if (last && has_next) S.a_ready(nxt);
;             if constexpr (epi_has_mid<Epi>::value) { if (t == Epi::MID_T) E.mid(acc, cur, wr, wc, fr, fq); }
;             if constexpr (SP2) {
;             PG8_LDB(B0, 0, 0); PG8_LDB(B1, 0, 1); PG8_SCHED; PG8_LDA(At, 0, 0); PG8_STAGE(PG8_SA(1, 1), a1 + hstep, voffA);
;             PG8_WAIT_V(8); PG8_WAIT_L(0); PG8_BAR; PG8_MMA(0, 0, At, B0); PG8_MMA(0, 1, At, B1); PG8_BAR; PG8_SCHED;
;             PG8_LDA(At, 0, 1); PG8_STAGE(PG8_SB(0, 0), b2, voffB); PG8_STAGE(PG8_SB(0, 1), b2 + hstep, voffB); PG8_STAGE(PG8_SA(0, 0), a2, voffA);
;             PG8_WAIT_V(8); PG8_WAIT_L(0); PG8_BAR; PG8_MMA(1, 0, At, B0); PG8_MMA(1, 1, At, B1); PG8_BAR; PG8_SCHED;
.LBB0_620:
	v_add_u32_e32 v3, 0x10000, v199
	ds_read_b128 v[134:137], v3
	ds_read_b128 v[138:141], v3 offset:1024
	ds_read_b128 v[142:145], v3 offset:2048
	ds_read_b128 v[146:149], v3 offset:3072
	v_add_u32_e32 v3, 0x14000, v199
	s_add_u32 s44, s42, 0x100
	ds_read_b128 v[158:161], v3
	ds_read_b128 v[162:165], v3 offset:1024
	ds_read_b128 v[166:169], v3 offset:2048
	ds_read_b128 v[170:173], v3 offset:3072
	s_addc_u32 s45, s43, 0
	s_cmp_eq_u32 s92, 60
	s_cselect_b32 s56, s88, s44
	s_cselect_b32 s57, s23, s45
	s_cselect_b32 s47, s19, s91
	s_cselect_b32 s46, s89, s90
	s_add_u32 s50, s56, 0x80
	s_addc_u32 s51, s57, 0
	s_add_u32 s54, s46, 0x80
	s_addc_u32 s55, s47, 0
	ds_read_b128 v[174:177], v200
	ds_read_b128 v[178:181], v200 offset:1024
	ds_read_b128 v[182:185], v200 offset:2048
	ds_read_b128 v[186:189], v200 offset:3072
	ds_read_b128 v[190:193], v200 offset:4096
	ds_read_b128 v[202:205], v200 offset:5120
	ds_read_b128 v[206:209], v200 offset:6144
	ds_read_b128 v[210:213], v200 offset:7168
	s_add_u32 s42, s42, 0x100080
	s_addc_u32 s43, s43, 0
	s_mov_b32 m0, s85
	s_nop 0
	global_load_lds_dwordx4 v1, s[42:43]
	s_nop 0
	s_mov_b32 m0, s86
	s_nop 0
	global_load_lds_dwordx4 v195, s[42:43]
	s_waitcnt vmcnt(8)
	s_waitcnt lgkmcnt(0)
	s_barrier
	s_setprio 1
	s_waitcnt lgkmcnt(7)
	v_mfma_f32_16x16x32_bf16 v[130:133], v[134:137], v[174:177], v[130:133]
	v_mfma_f32_16x16x32_bf16 v[126:129], v[142:145], v[174:177], v[126:129]
	s_waitcnt lgkmcnt(5)
	v_mfma_f32_16x16x32_bf16 v[122:125], v[134:137], v[182:185], v[122:125]
	v_mfma_f32_16x16x32_bf16 v[118:121], v[142:145], v[182:185], v[118:121]
	s_waitcnt lgkmcnt(3)
	v_mfma_f32_16x16x32_bf16 v[114:117], v[134:137], v[190:193], v[114:117]
	v_mfma_f32_16x16x32_bf16 v[110:113], v[142:145], v[190:193], v[110:113]
	s_waitcnt lgkmcnt(1)
	v_mfma_f32_16x16x32_bf16 v[106:109], v[134:137], v[206:209], v[106:109]
	v_mfma_f32_16x16x32_bf16 v[102:105], v[142:145], v[206:209], v[102:105]
	v_mfma_f32_16x16x32_bf16 v[130:133], v[138:141], v[178:181], v[130:133]
	v_mfma_f32_16x16x32_bf16 v[126:129], v[146:149], v[178:181], v[126:129]
	v_mfma_f32_16x16x32_bf16 v[122:125], v[138:141], v[186:189], v[122:125]
	v_mfma_f32_16x16x32_bf16 v[118:121], v[146:149], v[186:189], v[118:121]
	v_mfma_f32_16x16x32_bf16 v[114:117], v[138:141], v[202:205], v[114:117]
	v_mfma_f32_16x16x32_bf16 v[110:113], v[146:149], v[202:205], v[110:113]
	s_waitcnt lgkmcnt(0)
	v_mfma_f32_16x16x32_bf16 v[106:109], v[138:141], v[210:213], v[106:109]
	v_mfma_f32_16x16x32_bf16 v[102:105], v[146:149], v[210:213], v[102:105]
	s_setprio 0
	s_setprio 1
	v_mfma_f32_16x16x32_bf16 v[66:69], v[158:161], v[174:177], v[66:69]
	v_mfma_f32_16x16x32_bf16 v[62:65], v[166:169], v[174:177], v[62:65]
	v_mfma_f32_16x16x32_bf16 v[58:61], v[158:161], v[182:185], v[58:61]
	v_mfma_f32_16x16x32_bf16 v[54:57], v[166:169], v[182:185], v[54:57]
	v_mfma_f32_16x16x32_bf16 v[50:53], v[158:161], v[190:193], v[50:53]
	v_mfma_f32_16x16x32_bf16 v[46:49], v[166:169], v[190:193], v[46:49]
	v_mfma_f32_16x16x32_bf16 v[42:45], v[158:161], v[206:209], v[42:45]
	v_mfma_f32_16x16x32_bf16 v[38:41], v[166:169], v[206:209], v[38:41]
	v_mfma_f32_16x16x32_bf16 v[66:69], v[162:165], v[178:181], v[66:69]
	v_mfma_f32_16x16x32_bf16 v[62:65], v[170:173], v[178:181], v[62:65]
	v_mfma_f32_16x16x32_bf16 v[58:61], v[162:165], v[186:189], v[58:61]
	v_mfma_f32_16x16x32_bf16 v[54:57], v[170:173], v[186:189], v[54:57]
	v_mfma_f32_16x16x32_bf16 v[50:53], v[162:165], v[202:205], v[50:53]
	v_mfma_f32_16x16x32_bf16 v[46:49], v[170:173], v[202:205], v[46:49]
	v_mfma_f32_16x16x32_bf16 v[42:45], v[162:165], v[210:213], v[42:45]
	s_setprio 2
	s_barrier
	v_mfma_f32_16x16x32_bf16 v[38:41], v[170:173], v[210:213], v[38:41]
	s_setprio 0
	ds_read_b128 v[174:177], v200 offset:16384
	ds_read_b128 v[178:181], v200 offset:17408
	ds_read_b128 v[182:185], v200 offset:18432
	ds_read_b128 v[186:189], v200 offset:19456
	ds_read_b128 v[190:193], v200 offset:20480
	ds_read_b128 v[202:205], v200 offset:21504
	ds_read_b128 v[206:209], v200 offset:22528
	ds_read_b128 v[252:255], v200 offset:23552
	s_mov_b32 m0, s63
	s_nop 0
	global_load_lds_dwordx4 v194, s[46:47]
	s_add_u32 s42, s46, 0x100000
	s_mov_b32 m0, s64
	s_nop 0
	global_load_lds_dwordx4 v196, s[46:47]
	s_addc_u32 s43, s47, 0
	s_mov_b32 m0, s65
	s_nop 0
	global_load_lds_dwordx4 v194, s[42:43]
	s_nop 0
	s_mov_b32 m0, s66
	s_nop 0
	global_load_lds_dwordx4 v196, s[42:43]
	s_nop 0
	s_mov_b32 m0, s62
	s_nop 0
	global_load_lds_dwordx4 v1, s[56:57]
	s_nop 0
	s_mov_b32 m0, s67
	s_nop 0
	global_load_lds_dwordx4 v195, s[56:57]
	s_waitcnt vmcnt(8)
	s_waitcnt lgkmcnt(0)
	s_barrier
; #define PG8_STAGE(bufoff, gbase, voff) do { _Pragma("unroll") for (int _i = 0; _i < 2; ++_i) \
;         asm volatile("s_mov_b32 m0, %2\n\ts_nop 0\n\tglobal_load_lds_dwordx4 %0, %1" :: "v"((voff)[_i]), "s"((const char*)(gbase)), "s"(ldsbase + (unsigned)(bufoff) + ldsw + (unsigned)_i * 8192u) : "memory", "m0"); } while (0)
; #define PG8_LDA(dst, b, h) do { _Pragma("unroll") for (int m = 0; m < 4; ++m) _Pragma("unroll") for (int k = 0; k < 2; ++k) dst[m][k] = *(const PG8_LAS bf16x8*)(lds + PG8_SA(b, h) + aoff + m * 2048 + k * 1024); } while (0)
; #define PG8_LDB(dst, b, h) do { _Pragma("unroll") for (int n = 0; n < 2; ++n) _Pragma("unroll") for (int k = 0; k < 2; ++k) dst[n][k] = *(const PG8_LAS bf16x8*)(lds + PG8_SB(b, h) + boff + n * 2048 + k * 1024); } while (0)
; #define PG8_MMA(ai, bj, At, Bt) do { __builtin_amdgcn_s_setprio(1); _Pragma("unroll") for (int m = 0; m < 4; ++m) _Pragma("unroll") for (int n = 0; n < 2; ++n) _Pragma("unroll") for (int k = 0; k < 2; ++k) \
;         acc[ai][bj][m][n] = __builtin_amdgcn_mfma_f32_16x16x32_bf16(Bt[n][k], At[m][k], acc[ai][bj][m][n], 0, 0, 0); __builtin_amdgcn_s_setprio(0); } while (0)
; #define PG8_WAIT_V(n) asm volatile("s_waitcnt vmcnt(" #n ")" ::: "memory")
; #define PG8_WAIT_L(n) asm volatile("s_waitcnt lgkmcnt(" #n ")" ::: "memory")
; #define PG8_BAR __builtin_amdgcn_s_barrier()
; #define PG8_SCHED __builtin_amdgcn_sched_barrier(0)
; template <class Epi, class Sched, bool ALIGN_EPI = false, bool SP2 = false>
; __device__ __forceinline__ void gemm_phase(PG8_LAS unsigned char* lds, const Gemm g, const Sched& S, const Epi& E) {
;     ...
;             PG8_WAIT_V(8); PG8_WAIT_L(0); PG8_BAR; PG8_MMA(1, 0, At, B0); PG8_MMA(1, 1, At, B1); PG8_BAR; PG8_SCHED;
;             PG8_LDB(B0, 1, 0); PG8_LDB(B1, 1, 1); PG8_SCHED; PG8_LDA(At, 1, 0); PG8_STAGE(PG8_SA(0, 1), a2 + hstep, voffA);
;             PG8_WAIT_V(8); PG8_WAIT_L(0); PG8_BAR; PG8_MMA(0, 0, At, B0); PG8_MMA(0, 1, At, B1); PG8_BAR; PG8_SCHED;
	s_setprio 1
	s_waitcnt lgkmcnt(7)
	v_mfma_f32_16x16x32_bf16 v[98:101], v[134:137], v[174:177], v[98:101]
	v_mfma_f32_16x16x32_bf16 v[94:97], v[142:145], v[174:177], v[94:97]
	s_waitcnt lgkmcnt(5)
	v_mfma_f32_16x16x32_bf16 v[90:93], v[134:137], v[182:185], v[90:93]
	v_mfma_f32_16x16x32_bf16 v[86:89], v[142:145], v[182:185], v[86:89]
	s_waitcnt lgkmcnt(3)
	v_mfma_f32_16x16x32_bf16 v[82:85], v[134:137], v[190:193], v[82:85]
	v_mfma_f32_16x16x32_bf16 v[78:81], v[142:145], v[190:193], v[78:81]
	s_waitcnt lgkmcnt(1)
	v_mfma_f32_16x16x32_bf16 v[74:77], v[134:137], v[206:209], v[74:77]
	v_mfma_f32_16x16x32_bf16 v[70:73], v[142:145], v[206:209], v[70:73]
	v_mfma_f32_16x16x32_bf16 v[98:101], v[138:141], v[178:181], v[98:101]
	v_mfma_f32_16x16x32_bf16 v[94:97], v[146:149], v[178:181], v[94:97]
	v_mfma_f32_16x16x32_bf16 v[90:93], v[138:141], v[186:189], v[90:93]
	v_mfma_f32_16x16x32_bf16 v[86:89], v[146:149], v[186:189], v[86:89]
	v_mfma_f32_16x16x32_bf16 v[82:85], v[138:141], v[202:205], v[82:85]
	v_mfma_f32_16x16x32_bf16 v[78:81], v[146:149], v[202:205], v[78:81]
	s_waitcnt lgkmcnt(0)
	v_mfma_f32_16x16x32_bf16 v[74:77], v[138:141], v[252:255], v[74:77]
	v_mfma_f32_16x16x32_bf16 v[70:73], v[146:149], v[252:255], v[70:73]
	s_setprio 0
	s_setprio 1
	v_mfma_f32_16x16x32_bf16 v[34:37], v[158:161], v[174:177], v[34:37]
	v_mfma_f32_16x16x32_bf16 v[30:33], v[166:169], v[174:177], v[30:33]
	v_mfma_f32_16x16x32_bf16 v[26:29], v[158:161], v[182:185], v[26:29]
	v_mfma_f32_16x16x32_bf16 v[22:25], v[166:169], v[182:185], v[22:25]
	v_mfma_f32_16x16x32_bf16 v[18:21], v[158:161], v[190:193], v[18:21]
	v_mfma_f32_16x16x32_bf16 v[14:17], v[166:169], v[190:193], v[14:17]
	v_mfma_f32_16x16x32_bf16 v[10:13], v[158:161], v[206:209], v[10:13]
	v_mfma_f32_16x16x32_bf16 v[4:7], v[166:169], v[206:209], v[6:9]
	v_mfma_f32_16x16x32_bf16 v[34:37], v[162:165], v[178:181], v[34:37]
	v_mfma_f32_16x16x32_bf16 v[30:33], v[170:173], v[178:181], v[30:33]
	v_mfma_f32_16x16x32_bf16 v[26:29], v[162:165], v[186:189], v[26:29]
	v_mfma_f32_16x16x32_bf16 v[22:25], v[170:173], v[186:189], v[22:25]
	v_mfma_f32_16x16x32_bf16 v[18:21], v[162:165], v[202:205], v[18:21]
	v_mfma_f32_16x16x32_bf16 v[14:17], v[170:173], v[202:205], v[14:17]
	v_mfma_f32_16x16x32_bf16 v[10:13], v[162:165], v[252:255], v[10:13]
	s_setprio 2
	s_barrier
	v_mfma_f32_16x16x32_bf16 v[4:7], v[170:173], v[252:255], v[4:7]
	s_setprio 0
	v_add_u32_e32 v3, 0x18000, v199
	ds_read_b128 v[134:137], v3
	ds_read_b128 v[138:141], v3 offset:1024
	ds_read_b128 v[142:145], v3 offset:2048
	ds_read_b128 v[146:149], v3 offset:3072
	v_add_u32_e32 v3, 0x1c000, v199
	ds_read_b128 v[158:161], v3
	ds_read_b128 v[162:165], v3 offset:1024
	ds_read_b128 v[166:169], v3 offset:2048
	ds_read_b128 v[248:251], v3 offset:3072
	ds_read_b128 v[174:177], v200 offset:32768
	ds_read_b128 v[178:181], v200 offset:33792
	ds_read_b128 v[182:185], v200 offset:34816
	ds_read_b128 v[186:189], v200 offset:35840
	ds_read_b128 v[190:193], v200 offset:36864
	ds_read_b128 v[202:205], v200 offset:37888
	ds_read_b128 v[206:209], v200 offset:38912
	ds_read_b128 v[210:213], v200 offset:39936
	s_add_u32 s42, s56, 0x100000
	s_addc_u32 s43, s57, 0
	s_mov_b32 m0, s76
	s_nop 0
	global_load_lds_dwordx4 v1, s[42:43]
	s_nop 0
	s_mov_b32 m0, s77
	s_nop 0
	global_load_lds_dwordx4 v195, s[42:43]
	s_waitcnt vmcnt(8)
	s_waitcnt lgkmcnt(0)
	s_barrier
	s_setprio 1
	s_waitcnt lgkmcnt(7)
	v_mfma_f32_16x16x32_bf16 v[130:133], v[134:137], v[174:177], v[130:133]
	v_mfma_f32_16x16x32_bf16 v[126:129], v[142:145], v[174:177], v[126:129]
	s_waitcnt lgkmcnt(5)
	v_mfma_f32_16x16x32_bf16 v[122:125], v[134:137], v[182:185], v[122:125]
	v_mfma_f32_16x16x32_bf16 v[118:121], v[142:145], v[182:185], v[118:121]
	s_waitcnt lgkmcnt(3)
	v_mfma_f32_16x16x32_bf16 v[114:117], v[134:137], v[190:193], v[114:117]
	v_mfma_f32_16x16x32_bf16 v[110:113], v[142:145], v[190:193], v[110:113]
	s_waitcnt lgkmcnt(1)
	v_mfma_f32_16x16x32_bf16 v[106:109], v[134:137], v[206:209], v[106:109]
	v_mfma_f32_16x16x32_bf16 v[102:105], v[142:145], v[206:209], v[102:105]
	v_mfma_f32_16x16x32_bf16 v[130:133], v[138:141], v[178:181], v[130:133]
	v_mfma_f32_16x16x32_bf16 v[126:129], v[146:149], v[178:181], v[126:129]
	v_mfma_f32_16x16x32_bf16 v[122:125], v[138:141], v[186:189], v[122:125]
	v_mfma_f32_16x16x32_bf16 v[118:121], v[146:149], v[186:189], v[118:121]
	v_mfma_f32_16x16x32_bf16 v[114:117], v[138:141], v[202:205], v[114:117]
	v_mfma_f32_16x16x32_bf16 v[110:113], v[146:149], v[202:205], v[110:113]
	s_waitcnt lgkmcnt(0)
	v_mfma_f32_16x16x32_bf16 v[106:109], v[138:141], v[210:213], v[106:109]
	v_mfma_f32_16x16x32_bf16 v[102:105], v[146:149], v[210:213], v[102:105]
	s_setprio 0
	s_setprio 1
	v_mfma_f32_16x16x32_bf16 v[66:69], v[158:161], v[174:177], v[66:69]
	v_mfma_f32_16x16x32_bf16 v[62:65], v[166:169], v[174:177], v[62:65]
	v_mfma_f32_16x16x32_bf16 v[58:61], v[158:161], v[182:185], v[58:61]
	v_mfma_f32_16x16x32_bf16 v[54:57], v[166:169], v[182:185], v[54:57]
	v_mfma_f32_16x16x32_bf16 v[50:53], v[158:161], v[190:193], v[50:53]
	v_mfma_f32_16x16x32_bf16 v[46:49], v[166:169], v[190:193], v[46:49]
	v_mfma_f32_16x16x32_bf16 v[42:45], v[158:161], v[206:209], v[42:45]
	v_mfma_f32_16x16x32_bf16 v[38:41], v[166:169], v[206:209], v[38:41]
	v_mfma_f32_16x16x32_bf16 v[66:69], v[162:165], v[178:181], v[66:69]
	v_mfma_f32_16x16x32_bf16 v[62:65], v[248:251], v[178:181], v[62:65]
	v_mfma_f32_16x16x32_bf16 v[58:61], v[162:165], v[186:189], v[58:61]
	v_mfma_f32_16x16x32_bf16 v[54:57], v[248:251], v[186:189], v[54:57]
	v_mfma_f32_16x16x32_bf16 v[50:53], v[162:165], v[202:205], v[50:53]
	v_mfma_f32_16x16x32_bf16 v[46:49], v[248:251], v[202:205], v[46:49]
	v_mfma_f32_16x16x32_bf16 v[42:45], v[162:165], v[210:213], v[42:45]
	s_setprio 2
	s_barrier
; #define PG8_STAGE(bufoff, gbase, voff) do { _Pragma("unroll") for (int _i = 0; _i < 2; ++_i) \
;         asm volatile("s_mov_b32 m0, %2\n\ts_nop 0\n\tglobal_load_lds_dwordx4 %0, %1" :: "v"((voff)[_i]), "s"((const char*)(gbase)), "s"(ldsbase + (unsigned)(bufoff) + ldsw + (unsigned)_i * 8192u) : "memory", "m0"); } while (0)
; #define PG8_LDA(dst, b, h) do { _Pragma("unroll") for (int m = 0; m < 4; ++m) _Pragma("unroll") for (int k = 0; k < 2; ++k) dst[m][k] = *(const PG8_LAS bf16x8*)(lds + PG8_SA(b, h) + aoff + m * 2048 + k * 1024); } while (0)
; #define PG8_MMA(ai, bj, At, Bt) do { __builtin_amdgcn_s_setprio(1); _Pragma("unroll") for (int m = 0; m < 4; ++m) _Pragma("unroll") for (int n = 0; n < 2; ++n) _Pragma("unroll") for (int k = 0; k < 2; ++k) \
;         acc[ai][bj][m][n] = __builtin_amdgcn_mfma_f32_16x16x32_bf16(Bt[n][k], At[m][k], acc[ai][bj][m][n], 0, 0, 0); __builtin_amdgcn_s_setprio(0); } while (0)
; #define PG8_WAIT_V(n) asm volatile("s_waitcnt vmcnt(" #n ")" ::: "memory")
; #define PG8_WAIT_L(n) asm volatile("s_waitcnt lgkmcnt(" #n ")" ::: "memory")
; #define PG8_BAR __builtin_amdgcn_s_barrier()
; #define PG8_SCHED __builtin_amdgcn_sched_barrier(0)
; template <class Epi, class Sched, bool ALIGN_EPI = false, bool SP2 = false>
; __device__ __forceinline__ void gemm_phase(PG8_LAS unsigned char* lds, const Gemm g, const Sched& S, const Epi& E) {
;     ...
;             if constexpr (epi_has_mid<Epi>::value) { if (t == Epi::MID_T) E.mid(acc, cur, wr, wc, fr, fq); }
;     ...
;             PG8_LDA(At, 1, 1); PG8_STAGE(PG8_SB(1, 0), b3, voffB); PG8_STAGE(PG8_SB(1, 1), b3 + hstep, voffB); PG8_STAGE(PG8_SA(1, 0), a3, voffA);
;             PG8_WAIT_V(8); PG8_WAIT_L(0); PG8_BAR; PG8_MMA(1, 0, At, B0); PG8_MMA(1, 1, At, B1); PG8_BAR; PG8_SCHED;
	v_mfma_f32_16x16x32_bf16 v[38:41], v[248:251], v[210:213], v[38:41]
	s_setprio 0
	ds_read_b128 v[174:177], v200 offset:49152
	ds_read_b128 v[178:181], v200 offset:50176
	ds_read_b128 v[182:185], v200 offset:51200
	ds_read_b128 v[186:189], v200 offset:52224
	ds_read_b128 v[190:193], v200 offset:53248
	ds_read_b128 v[202:205], v200 offset:54272
	ds_read_b128 v[206:209], v200 offset:55296
	ds_read_b128 v[252:255], v200 offset:56320
	s_mov_b32 m0, s78
	s_nop 0
	global_load_lds_dwordx4 v194, s[54:55]
	s_add_u32 s42, s46, 0x100080
	s_mov_b32 m0, s79
	s_nop 0
	global_load_lds_dwordx4 v196, s[54:55]
	s_addc_u32 s43, s47, 0
	s_mov_b32 m0, s83
	s_nop 0
	global_load_lds_dwordx4 v194, s[42:43]
	s_nop 0
	s_mov_b32 m0, s84
	s_nop 0
	global_load_lds_dwordx4 v196, s[42:43]
	s_nop 0
	s_mov_b32 m0, s80
	s_nop 0
	global_load_lds_dwordx4 v1, s[50:51]
	s_nop 0
	s_mov_b32 m0, s82
	s_nop 0
	global_load_lds_dwordx4 v195, s[50:51]
	s_waitcnt vmcnt(8)
	s_waitcnt lgkmcnt(0)
	s_barrier
	s_setprio 1
	s_waitcnt lgkmcnt(7)
	v_mfma_f32_16x16x32_bf16 v[98:101], v[134:137], v[174:177], v[98:101]
	v_mfma_f32_16x16x32_bf16 v[94:97], v[142:145], v[174:177], v[94:97]
	s_waitcnt lgkmcnt(5)
	v_mfma_f32_16x16x32_bf16 v[90:93], v[134:137], v[182:185], v[90:93]
	v_mfma_f32_16x16x32_bf16 v[86:89], v[142:145], v[182:185], v[86:89]
	s_waitcnt lgkmcnt(3)
	v_mfma_f32_16x16x32_bf16 v[82:85], v[134:137], v[190:193], v[82:85]
	v_mfma_f32_16x16x32_bf16 v[78:81], v[142:145], v[190:193], v[78:81]
	s_waitcnt lgkmcnt(1)
	v_mfma_f32_16x16x32_bf16 v[74:77], v[134:137], v[206:209], v[74:77]
	v_mfma_f32_16x16x32_bf16 v[70:73], v[142:145], v[206:209], v[70:73]
	v_mfma_f32_16x16x32_bf16 v[98:101], v[138:141], v[178:181], v[98:101]
	v_mfma_f32_16x16x32_bf16 v[94:97], v[146:149], v[178:181], v[94:97]
	v_mfma_f32_16x16x32_bf16 v[90:93], v[138:141], v[186:189], v[90:93]
	v_mfma_f32_16x16x32_bf16 v[86:89], v[146:149], v[186:189], v[86:89]
	v_mfma_f32_16x16x32_bf16 v[82:85], v[138:141], v[202:205], v[82:85]
	v_mfma_f32_16x16x32_bf16 v[78:81], v[146:149], v[202:205], v[78:81]
	s_waitcnt lgkmcnt(0)
	v_mfma_f32_16x16x32_bf16 v[74:77], v[138:141], v[252:255], v[74:77]
	v_mfma_f32_16x16x32_bf16 v[70:73], v[146:149], v[252:255], v[70:73]
	s_setprio 0
	s_setprio 1
	v_mfma_f32_16x16x32_bf16 v[34:37], v[158:161], v[174:177], v[34:37]
	v_mfma_f32_16x16x32_bf16 v[30:33], v[166:169], v[174:177], v[30:33]
	v_mfma_f32_16x16x32_bf16 v[26:29], v[158:161], v[182:185], v[26:29]
	v_mfma_f32_16x16x32_bf16 v[22:25], v[166:169], v[182:185], v[22:25]
	v_mfma_f32_16x16x32_bf16 v[18:21], v[158:161], v[190:193], v[18:21]
	v_mfma_f32_16x16x32_bf16 v[14:17], v[166:169], v[190:193], v[14:17]
	v_mfma_f32_16x16x32_bf16 v[8:11], v[158:161], v[206:209], v[10:13]
	v_mfma_f32_16x16x32_bf16 v[4:7], v[166:169], v[206:209], v[4:7]
	v_mfma_f32_16x16x32_bf16 v[34:37], v[162:165], v[178:181], v[34:37]
	v_mfma_f32_16x16x32_bf16 v[30:33], v[248:251], v[178:181], v[30:33]
	v_mfma_f32_16x16x32_bf16 v[26:29], v[162:165], v[186:189], v[26:29]
	v_mfma_f32_16x16x32_bf16 v[22:25], v[248:251], v[186:189], v[22:25]
	v_mfma_f32_16x16x32_bf16 v[18:21], v[162:165], v[202:205], v[18:21]
	v_mfma_f32_16x16x32_bf16 v[14:17], v[248:251], v[202:205], v[14:17]
	v_mfma_f32_16x16x32_bf16 v[10:13], v[162:165], v[252:255], v[8:11]
	s_setprio 2
	s_barrier
	v_mfma_f32_16x16x32_bf16 v[6:9], v[248:251], v[252:255], v[4:7]
	s_setprio 0
	s_add_i32 s92, s92, 2
	s_add_u32 s90, s90, 0x100
	s_addc_u32 s91, s91, 0
	s_cmp_gt_u32 s92, 61
	s_cbranch_scc1 .LBB0_622
	s_mov_b64 s[42:43], s[44:45]
	s_cmp_lg_u32 s92, 30
	s_cbranch_scc0 .LBB0_619
	s_branch .LBB0_620

; #define PG8_STAGE(bufoff, gbase, voff) do { _Pragma("unroll") for (int _i = 0; _i < 2; ++_i) \
;         asm volatile("s_mov_b32 m0, %2\n\ts_nop 0\n\tglobal_load_lds_dwordx4 %0, %1" :: "v"((voff)[_i]), "s"((const char*)(gbase)), "s"(ldsbase + (unsigned)(bufoff) + ldsw + (unsigned)_i * 8192u) : "memory", "m0"); } while (0)
; #define PG8_LDA(dst, b, h) do { _Pragma("unroll") for (int m = 0; m < 4; ++m) _Pragma("unroll") for (int k = 0; k < 2; ++k) dst[m][k] = *(const PG8_LAS bf16x8*)(lds + PG8_SA(b, h) + aoff + m * 2048 + k * 1024); } while (0)
; #define PG8_LDB(dst, b, h) do { _Pragma("unroll") for (int n = 0; n < 2; ++n) _Pragma("unroll") for (int k = 0; k < 2; ++k) dst[n][k] = *(const PG8_LAS bf16x8*)(lds + PG8_SB(b, h) + boff + n * 2048 + k * 1024); } while (0)
; #define PG8_MMA(ai, bj, At, Bt) do { __builtin_amdgcn_s_setprio(1); _Pragma("unroll") for (int m = 0; m < 4; ++m) _Pragma("unroll") for (int n = 0; n < 2; ++n) _Pragma("unroll") for (int k = 0; k < 2; ++k) \
;         acc[ai][bj][m][n] = __builtin_amdgcn_mfma_f32_16x16x32_bf16(Bt[n][k], At[m][k], acc[ai][bj][m][n], 0, 0, 0); __builtin_amdgcn_s_setprio(0); } while (0)
; #define PG8_WAIT_V(n) asm volatile("s_waitcnt vmcnt(" #n ")" ::: "memory")
; #define PG8_WAIT_L(n) asm volatile("s_waitcnt lgkmcnt(" #n ")" ::: "memory")
; #define PG8_BAR __builtin_amdgcn_s_barrier()
; #define PG8_SCHED __builtin_amdgcn_sched_barrier(0)
; template <class Epi, class Sched, bool ALIGN_EPI = false, bool SP2 = false>
; __device__ __forceinline__ void gemm_phase(PG8_LAS unsigned char* lds, const Gemm g, const Sched& S, const Epi& E) {
;     ...
;             PG8_LDB(B0, 0, 0); PG8_LDB(B1, 0, 1); PG8_SCHED; PG8_LDA(At, 0, 0); PG8_STAGE(PG8_SA(1, 1), a1 + hstep, voffA);
;             PG8_WAIT_V(8); PG8_WAIT_L(0); PG8_BAR; PG8_MMA(0, 0, At, B0); PG8_MMA(0, 1, At, B1); PG8_BAR; PG8_SCHED;
;             PG8_LDA(At, 0, 1); PG8_STAGE(PG8_SB(0, 0), b2, voffB); PG8_STAGE(PG8_SB(0, 1), b2 + hstep, voffB); PG8_STAGE(PG8_SA(0, 0), a2, voffA);
;             PG8_WAIT_V(8); PG8_WAIT_L(0); PG8_BAR; PG8_MMA(1, 0, At, B0); PG8_MMA(1, 1, At, B1); PG8_BAR; PG8_SCHED;
.LBB0_698:
	ds_read_b128 v[134:137], v145
	ds_read_b128 v[152:155], v145 offset:1024
	ds_read_b128 v[156:159], v145 offset:2048
	ds_read_b128 v[160:163], v145 offset:3072
	ds_read_b128 v[164:167], v146
	ds_read_b128 v[168:171], v146 offset:1024
	ds_read_b128 v[172:175], v146 offset:2048
	ds_read_b128 v[176:179], v146 offset:3072
	s_cmp_eq_u32 s69, 60
	s_cselect_b32 s48, s41, s53
	s_cselect_b32 s49, s19, s58
	s_cselect_b32 s46, s52, s59
	s_cselect_b32 s47, s17, s68
	s_add_u32 s44, s48, 0x80
	s_addc_u32 s45, s49, 0
	ds_read_b128 v[180:183], v147
	ds_read_b128 v[184:187], v147 offset:1024
	ds_read_b128 v[188:191], v147 offset:2048
	ds_read_b128 v[192:195], v147 offset:3072
	ds_read_b128 v[196:199], v147 offset:4096
	ds_read_b128 v[200:203], v147 offset:5120
	ds_read_b128 v[204:207], v147 offset:6144
	ds_read_b128 v[208:211], v147 offset:7168
	s_mov_b32 m0, s67
	s_nop 0
	global_load_lds_dwordx4 v1, s[42:43]
	s_nop 0
	s_mov_b32 m0, s74
	s_nop 0
	global_load_lds_dwordx4 v141, s[42:43]
	s_waitcnt vmcnt(8)
	s_waitcnt lgkmcnt(0)
	s_barrier
	s_setprio 1
	s_waitcnt lgkmcnt(7)
	v_mfma_f32_16x16x32_bf16 v[126:129], v[134:137], v[180:183], v[126:129]
	v_mfma_f32_16x16x32_bf16 v[122:125], v[156:159], v[180:183], v[122:125]
	s_waitcnt lgkmcnt(5)
	v_mfma_f32_16x16x32_bf16 v[110:113], v[134:137], v[188:191], v[110:113]
	v_mfma_f32_16x16x32_bf16 v[106:109], v[156:159], v[188:191], v[106:109]
	s_waitcnt lgkmcnt(3)
	v_mfma_f32_16x16x32_bf16 v[94:97], v[134:137], v[196:199], v[94:97]
	v_mfma_f32_16x16x32_bf16 v[90:93], v[156:159], v[196:199], v[90:93]
	s_waitcnt lgkmcnt(1)
	v_mfma_f32_16x16x32_bf16 v[78:81], v[134:137], v[204:207], v[78:81]
	v_mfma_f32_16x16x32_bf16 v[74:77], v[156:159], v[204:207], v[74:77]
	v_mfma_f32_16x16x32_bf16 v[126:129], v[152:155], v[184:187], v[126:129]
	v_mfma_f32_16x16x32_bf16 v[122:125], v[160:163], v[184:187], v[122:125]
	v_mfma_f32_16x16x32_bf16 v[110:113], v[152:155], v[192:195], v[110:113]
	v_mfma_f32_16x16x32_bf16 v[106:109], v[160:163], v[192:195], v[106:109]
	v_mfma_f32_16x16x32_bf16 v[94:97], v[152:155], v[200:203], v[94:97]
	v_mfma_f32_16x16x32_bf16 v[90:93], v[160:163], v[200:203], v[90:93]
	s_waitcnt lgkmcnt(0)
	v_mfma_f32_16x16x32_bf16 v[78:81], v[152:155], v[208:211], v[78:81]
	v_mfma_f32_16x16x32_bf16 v[74:77], v[160:163], v[208:211], v[74:77]
	s_setprio 0
	s_setprio 1
	v_mfma_f32_16x16x32_bf16 v[118:121], v[164:167], v[180:183], v[118:121]
	v_mfma_f32_16x16x32_bf16 v[114:117], v[172:175], v[180:183], v[114:117]
	v_mfma_f32_16x16x32_bf16 v[102:105], v[164:167], v[188:191], v[102:105]
	v_mfma_f32_16x16x32_bf16 v[98:101], v[172:175], v[188:191], v[98:101]
	v_mfma_f32_16x16x32_bf16 v[86:89], v[164:167], v[196:199], v[86:89]
	v_mfma_f32_16x16x32_bf16 v[82:85], v[172:175], v[196:199], v[82:85]
	v_mfma_f32_16x16x32_bf16 v[70:73], v[164:167], v[204:207], v[70:73]
	v_mfma_f32_16x16x32_bf16 v[66:69], v[172:175], v[204:207], v[66:69]
	v_mfma_f32_16x16x32_bf16 v[118:121], v[168:171], v[184:187], v[118:121]
	v_mfma_f32_16x16x32_bf16 v[114:117], v[176:179], v[184:187], v[114:117]
	v_mfma_f32_16x16x32_bf16 v[102:105], v[168:171], v[192:195], v[102:105]
	v_mfma_f32_16x16x32_bf16 v[98:101], v[176:179], v[192:195], v[98:101]
	v_mfma_f32_16x16x32_bf16 v[86:89], v[168:171], v[200:203], v[86:89]
	v_mfma_f32_16x16x32_bf16 v[82:85], v[176:179], v[200:203], v[82:85]
	v_mfma_f32_16x16x32_bf16 v[70:73], v[168:171], v[208:211], v[70:73]
	s_setprio 2
	s_barrier
	v_mfma_f32_16x16x32_bf16 v[66:69], v[176:179], v[208:211], v[66:69]
	s_setprio 0
	ds_read_b128 v[180:183], v147 offset:16384
	ds_read_b128 v[184:187], v147 offset:17408
	ds_read_b128 v[188:191], v147 offset:18432
	ds_read_b128 v[192:195], v147 offset:19456
	ds_read_b128 v[196:199], v147 offset:20480
	ds_read_b128 v[200:203], v147 offset:21504
	ds_read_b128 v[204:207], v147 offset:22528
	ds_read_b128 v[252:255], v147 offset:23552
	s_mov_b32 m0, s35
	s_nop 0
	global_load_lds_dwordx4 v140, s[46:47]
	s_add_u32 s70, s46, 0x100000
	s_mov_b32 m0, s50
	s_nop 0
	global_load_lds_dwordx4 v142, s[46:47]
	s_addc_u32 s71, s47, 0
	s_mov_b32 m0, s51
	s_nop 0
	global_load_lds_dwordx4 v140, s[70:71]
	s_nop 0
	s_mov_b32 m0, s54
	s_nop 0
	global_load_lds_dwordx4 v142, s[70:71]
	s_nop 0
	s_mov_b32 m0, s3
	s_nop 0
	global_load_lds_dwordx4 v1, s[48:49]
	s_nop 0
	s_mov_b32 m0, s55
	s_nop 0
	global_load_lds_dwordx4 v141, s[48:49]
	s_waitcnt vmcnt(8)
	s_waitcnt lgkmcnt(0)
	s_barrier
	s_setprio 1
	s_waitcnt lgkmcnt(7)
	v_mfma_f32_16x16x32_bf16 v[62:65], v[134:137], v[180:183], v[62:65]
	v_mfma_f32_16x16x32_bf16 v[58:61], v[156:159], v[180:183], v[58:61]
	s_waitcnt lgkmcnt(5)
	v_mfma_f32_16x16x32_bf16 v[46:49], v[134:137], v[188:191], v[46:49]
	v_mfma_f32_16x16x32_bf16 v[42:45], v[156:159], v[188:191], v[42:45]
	s_waitcnt lgkmcnt(3)
	v_mfma_f32_16x16x32_bf16 v[30:33], v[134:137], v[196:199], v[30:33]
	v_mfma_f32_16x16x32_bf16 v[26:29], v[156:159], v[196:199], v[26:29]
	s_waitcnt lgkmcnt(1)
	v_mfma_f32_16x16x32_bf16 v[14:17], v[134:137], v[204:207], v[14:17]
	v_mfma_f32_16x16x32_bf16 v[10:13], v[156:159], v[204:207], v[10:13]
	v_mfma_f32_16x16x32_bf16 v[62:65], v[152:155], v[184:187], v[62:65]
	v_mfma_f32_16x16x32_bf16 v[58:61], v[160:163], v[184:187], v[58:61]
	v_mfma_f32_16x16x32_bf16 v[46:49], v[152:155], v[192:195], v[46:49]
	v_mfma_f32_16x16x32_bf16 v[42:45], v[160:163], v[192:195], v[42:45]
	v_mfma_f32_16x16x32_bf16 v[30:33], v[152:155], v[200:203], v[30:33]
	v_mfma_f32_16x16x32_bf16 v[26:29], v[160:163], v[200:203], v[26:29]
	s_waitcnt lgkmcnt(0)
	v_mfma_f32_16x16x32_bf16 v[14:17], v[152:155], v[252:255], v[14:17]
	v_mfma_f32_16x16x32_bf16 v[10:13], v[160:163], v[252:255], v[10:13]
	s_setprio 0
	s_setprio 1
	v_mfma_f32_16x16x32_bf16 v[54:57], v[164:167], v[180:183], v[54:57]
	v_mfma_f32_16x16x32_bf16 v[50:53], v[172:175], v[180:183], v[50:53]
	v_mfma_f32_16x16x32_bf16 v[38:41], v[164:167], v[188:191], v[38:41]
	v_mfma_f32_16x16x32_bf16 v[34:37], v[172:175], v[188:191], v[34:37]
	v_mfma_f32_16x16x32_bf16 v[22:25], v[164:167], v[196:199], v[22:25]
	v_mfma_f32_16x16x32_bf16 v[18:21], v[172:175], v[196:199], v[18:21]
	v_mfma_f32_16x16x32_bf16 v[6:9], v[164:167], v[204:207], v[6:9]
	v_mfma_f32_16x16x32_bf16 v[2:5], v[172:175], v[204:207], v[2:5]
	v_mfma_f32_16x16x32_bf16 v[54:57], v[168:171], v[184:187], v[54:57]
	v_mfma_f32_16x16x32_bf16 v[50:53], v[176:179], v[184:187], v[50:53]
	v_mfma_f32_16x16x32_bf16 v[38:41], v[168:171], v[192:195], v[38:41]
	v_mfma_f32_16x16x32_bf16 v[34:37], v[176:179], v[192:195], v[34:37]
	v_mfma_f32_16x16x32_bf16 v[22:25], v[168:171], v[200:203], v[22:25]
	v_mfma_f32_16x16x32_bf16 v[18:21], v[176:179], v[200:203], v[18:21]
	v_mfma_f32_16x16x32_bf16 v[6:9], v[168:171], v[252:255], v[6:9]
	s_setprio 2
	s_barrier
; #define PG8_STAGE(bufoff, gbase, voff) do { _Pragma("unroll") for (int _i = 0; _i < 2; ++_i) \
;         asm volatile("s_mov_b32 m0, %2\n\ts_nop 0\n\tglobal_load_lds_dwordx4 %0, %1" :: "v"((voff)[_i]), "s"((const char*)(gbase)), "s"(ldsbase + (unsigned)(bufoff) + ldsw + (unsigned)_i * 8192u) : "memory", "m0"); } while (0)
; #define PG8_LDA(dst, b, h) do { _Pragma("unroll") for (int m = 0; m < 4; ++m) _Pragma("unroll") for (int k = 0; k < 2; ++k) dst[m][k] = *(const PG8_LAS bf16x8*)(lds + PG8_SA(b, h) + aoff + m * 2048 + k * 1024); } while (0)
; #define PG8_LDB(dst, b, h) do { _Pragma("unroll") for (int n = 0; n < 2; ++n) _Pragma("unroll") for (int k = 0; k < 2; ++k) dst[n][k] = *(const PG8_LAS bf16x8*)(lds + PG8_SB(b, h) + boff + n * 2048 + k * 1024); } while (0)
; #define PG8_MMA(ai, bj, At, Bt) do { __builtin_amdgcn_s_setprio(1); _Pragma("unroll") for (int m = 0; m < 4; ++m) _Pragma("unroll") for (int n = 0; n < 2; ++n) _Pragma("unroll") for (int k = 0; k < 2; ++k) \
;         acc[ai][bj][m][n] = __builtin_amdgcn_mfma_f32_16x16x32_bf16(Bt[n][k], At[m][k], acc[ai][bj][m][n], 0, 0, 0); __builtin_amdgcn_s_setprio(0); } while (0)
; #define PG8_WAIT_V(n) asm volatile("s_waitcnt vmcnt(" #n ")" ::: "memory")
; #define PG8_WAIT_L(n) asm volatile("s_waitcnt lgkmcnt(" #n ")" ::: "memory")
; #define PG8_BAR __builtin_amdgcn_s_barrier()
; #define PG8_SCHED __builtin_amdgcn_sched_barrier(0)
; template <class Epi, class Sched, bool ALIGN_EPI = false, bool SP2 = false>
; __device__ __forceinline__ void gemm_phase(PG8_LAS unsigned char* lds, const Gemm g, const Sched& S, const Epi& E) {
;     ...
;             PG8_LDB(B0, 1, 0); PG8_LDB(B1, 1, 1); PG8_SCHED; PG8_LDA(At, 1, 0); PG8_STAGE(PG8_SA(0, 1), a2 + hstep, voffA);
;             PG8_WAIT_V(8); PG8_WAIT_L(0); PG8_BAR; PG8_MMA(0, 0, At, B0); PG8_MMA(0, 1, At, B1); PG8_BAR; PG8_SCHED;
	v_mfma_f32_16x16x32_bf16 v[2:5], v[176:179], v[252:255], v[2:5]
	s_setprio 0
	ds_read_b128 v[134:137], v148
	ds_read_b128 v[152:155], v148 offset:1024
	ds_read_b128 v[156:159], v148 offset:2048
	ds_read_b128 v[160:163], v148 offset:3072
	ds_read_b128 v[164:167], v149
	ds_read_b128 v[168:171], v149 offset:1024
	ds_read_b128 v[172:175], v149 offset:2048
	ds_read_b128 v[248:251], v149 offset:3072
	ds_read_b128 v[180:183], v147 offset:32768
	ds_read_b128 v[184:187], v147 offset:33792
	ds_read_b128 v[188:191], v147 offset:34816
	ds_read_b128 v[192:195], v147 offset:35840
	ds_read_b128 v[196:199], v147 offset:36864
	ds_read_b128 v[200:203], v147 offset:37888
	ds_read_b128 v[204:207], v147 offset:38912
	ds_read_b128 v[208:211], v147 offset:39936
	s_add_u32 s48, s48, 0x100000
	s_addc_u32 s49, s49, 0
	s_mov_b32 m0, s56
	s_nop 0
	global_load_lds_dwordx4 v1, s[48:49]
	s_nop 0
	s_mov_b32 m0, s57
	s_nop 0
	global_load_lds_dwordx4 v141, s[48:49]
	s_waitcnt vmcnt(8)
	s_waitcnt lgkmcnt(0)
	s_barrier
	s_setprio 1
	s_waitcnt lgkmcnt(7)
	v_mfma_f32_16x16x32_bf16 v[126:129], v[134:137], v[180:183], v[126:129]
	v_mfma_f32_16x16x32_bf16 v[122:125], v[156:159], v[180:183], v[122:125]
	s_waitcnt lgkmcnt(5)
	v_mfma_f32_16x16x32_bf16 v[110:113], v[134:137], v[188:191], v[110:113]
	v_mfma_f32_16x16x32_bf16 v[106:109], v[156:159], v[188:191], v[106:109]
	s_waitcnt lgkmcnt(3)
	v_mfma_f32_16x16x32_bf16 v[94:97], v[134:137], v[196:199], v[94:97]
	v_mfma_f32_16x16x32_bf16 v[90:93], v[156:159], v[196:199], v[90:93]
	s_waitcnt lgkmcnt(1)
	v_mfma_f32_16x16x32_bf16 v[78:81], v[134:137], v[204:207], v[78:81]
	v_mfma_f32_16x16x32_bf16 v[74:77], v[156:159], v[204:207], v[74:77]
	v_mfma_f32_16x16x32_bf16 v[126:129], v[152:155], v[184:187], v[126:129]
	v_mfma_f32_16x16x32_bf16 v[122:125], v[160:163], v[184:187], v[122:125]
	v_mfma_f32_16x16x32_bf16 v[110:113], v[152:155], v[192:195], v[110:113]
	v_mfma_f32_16x16x32_bf16 v[106:109], v[160:163], v[192:195], v[106:109]
	v_mfma_f32_16x16x32_bf16 v[94:97], v[152:155], v[200:203], v[94:97]
	v_mfma_f32_16x16x32_bf16 v[90:93], v[160:163], v[200:203], v[90:93]
	s_waitcnt lgkmcnt(0)
	v_mfma_f32_16x16x32_bf16 v[78:81], v[152:155], v[208:211], v[78:81]
	v_mfma_f32_16x16x32_bf16 v[74:77], v[160:163], v[208:211], v[74:77]
	s_setprio 0
	s_setprio 1
	v_mfma_f32_16x16x32_bf16 v[118:121], v[164:167], v[180:183], v[118:121]
	v_mfma_f32_16x16x32_bf16 v[114:117], v[172:175], v[180:183], v[114:117]
	v_mfma_f32_16x16x32_bf16 v[102:105], v[164:167], v[188:191], v[102:105]
	v_mfma_f32_16x16x32_bf16 v[98:101], v[172:175], v[188:191], v[98:101]
	v_mfma_f32_16x16x32_bf16 v[86:89], v[164:167], v[196:199], v[86:89]
	v_mfma_f32_16x16x32_bf16 v[82:85], v[172:175], v[196:199], v[82:85]
	v_mfma_f32_16x16x32_bf16 v[70:73], v[164:167], v[204:207], v[70:73]
	v_mfma_f32_16x16x32_bf16 v[66:69], v[172:175], v[204:207], v[66:69]
	v_mfma_f32_16x16x32_bf16 v[118:121], v[168:171], v[184:187], v[118:121]
	v_mfma_f32_16x16x32_bf16 v[114:117], v[248:251], v[184:187], v[114:117]
	v_mfma_f32_16x16x32_bf16 v[102:105], v[168:171], v[192:195], v[102:105]
	v_mfma_f32_16x16x32_bf16 v[98:101], v[248:251], v[192:195], v[98:101]
	v_mfma_f32_16x16x32_bf16 v[86:89], v[168:171], v[200:203], v[86:89]
	v_mfma_f32_16x16x32_bf16 v[82:85], v[248:251], v[200:203], v[82:85]
	v_mfma_f32_16x16x32_bf16 v[70:73], v[168:171], v[208:211], v[70:73]
	s_setprio 2
	s_barrier
; #define PG8_STAGE(bufoff, gbase, voff) do { _Pragma("unroll") for (int _i = 0; _i < 2; ++_i) \
;         asm volatile("s_mov_b32 m0, %2\n\ts_nop 0\n\tglobal_load_lds_dwordx4 %0, %1" :: "v"((voff)[_i]), "s"((const char*)(gbase)), "s"(ldsbase + (unsigned)(bufoff) + ldsw + (unsigned)_i * 8192u) : "memory", "m0"); } while (0)
; #define PG8_LDA(dst, b, h) do { _Pragma("unroll") for (int m = 0; m < 4; ++m) _Pragma("unroll") for (int k = 0; k < 2; ++k) dst[m][k] = *(const PG8_LAS bf16x8*)(lds + PG8_SA(b, h) + aoff + m * 2048 + k * 1024); } while (0)
; #define PG8_MMA(ai, bj, At, Bt) do { __builtin_amdgcn_s_setprio(1); _Pragma("unroll") for (int m = 0; m < 4; ++m) _Pragma("unroll") for (int n = 0; n < 2; ++n) _Pragma("unroll") for (int k = 0; k < 2; ++k) \
;         acc[ai][bj][m][n] = __builtin_amdgcn_mfma_f32_16x16x32_bf16(Bt[n][k], At[m][k], acc[ai][bj][m][n], 0, 0, 0); __builtin_amdgcn_s_setprio(0); } while (0)
; #define PG8_WAIT_V(n) asm volatile("s_waitcnt vmcnt(" #n ")" ::: "memory")
; #define PG8_WAIT_L(n) asm volatile("s_waitcnt lgkmcnt(" #n ")" ::: "memory")
; #define PG8_BAR __builtin_amdgcn_s_barrier()
; #define PG8_SCHED __builtin_amdgcn_sched_barrier(0)
; template <class Epi, class Sched, bool ALIGN_EPI = false, bool SP2 = false>
; __device__ __forceinline__ void gemm_phase(PG8_LAS unsigned char* lds, const Gemm g, const Sched& S, const Epi& E) {
;     ...
;             PG8_LDA(At, 1, 1); PG8_STAGE(PG8_SB(1, 0), b3, voffB); PG8_STAGE(PG8_SB(1, 1), b3 + hstep, voffB); PG8_STAGE(PG8_SA(1, 0), a3, voffA);
;             PG8_WAIT_V(8); PG8_WAIT_L(0); PG8_BAR; PG8_MMA(1, 0, At, B0); PG8_MMA(1, 1, At, B1); PG8_BAR; PG8_SCHED;
	v_mfma_f32_16x16x32_bf16 v[66:69], v[248:251], v[208:211], v[66:69]
	s_setprio 0
	ds_read_b128 v[180:183], v147 offset:49152
	ds_read_b128 v[184:187], v147 offset:50176
	ds_read_b128 v[188:191], v147 offset:51200
	ds_read_b128 v[192:195], v147 offset:52224
	ds_read_b128 v[196:199], v147 offset:53248
	ds_read_b128 v[200:203], v147 offset:54272
	ds_read_b128 v[204:207], v147 offset:55296
	ds_read_b128 v[252:255], v147 offset:56320
	s_add_u32 s48, s46, 0x80
	s_addc_u32 s49, s47, 0
	s_mov_b32 m0, s61
	s_nop 0
	global_load_lds_dwordx4 v140, s[48:49]
	s_add_u32 s46, s46, 0x100080
	s_mov_b32 m0, s62
	s_nop 0
	global_load_lds_dwordx4 v142, s[48:49]
	s_addc_u32 s47, s47, 0
	s_mov_b32 m0, s65
	s_nop 0
	global_load_lds_dwordx4 v140, s[46:47]
	s_nop 0
	s_mov_b32 m0, s66
	s_nop 0
	global_load_lds_dwordx4 v142, s[46:47]
	s_nop 0
	s_mov_b32 m0, s63
	s_nop 0
	global_load_lds_dwordx4 v1, s[44:45]
	s_nop 0
	s_mov_b32 m0, s64
	s_nop 0
	global_load_lds_dwordx4 v141, s[44:45]
	s_waitcnt vmcnt(8)
	s_waitcnt lgkmcnt(0)
	s_barrier
	s_setprio 1
	s_waitcnt lgkmcnt(7)
	v_mfma_f32_16x16x32_bf16 v[62:65], v[134:137], v[180:183], v[62:65]
	v_mfma_f32_16x16x32_bf16 v[58:61], v[156:159], v[180:183], v[58:61]
	s_waitcnt lgkmcnt(5)
	v_mfma_f32_16x16x32_bf16 v[46:49], v[134:137], v[188:191], v[46:49]
	v_mfma_f32_16x16x32_bf16 v[42:45], v[156:159], v[188:191], v[42:45]
	s_waitcnt lgkmcnt(3)
	v_mfma_f32_16x16x32_bf16 v[30:33], v[134:137], v[196:199], v[30:33]
	v_mfma_f32_16x16x32_bf16 v[26:29], v[156:159], v[196:199], v[26:29]
	s_waitcnt lgkmcnt(1)
	v_mfma_f32_16x16x32_bf16 v[14:17], v[134:137], v[204:207], v[14:17]
	v_mfma_f32_16x16x32_bf16 v[10:13], v[156:159], v[204:207], v[10:13]
	v_mfma_f32_16x16x32_bf16 v[62:65], v[152:155], v[184:187], v[62:65]
	v_mfma_f32_16x16x32_bf16 v[58:61], v[160:163], v[184:187], v[58:61]
	v_mfma_f32_16x16x32_bf16 v[46:49], v[152:155], v[192:195], v[46:49]
	v_mfma_f32_16x16x32_bf16 v[42:45], v[160:163], v[192:195], v[42:45]
	v_mfma_f32_16x16x32_bf16 v[30:33], v[152:155], v[200:203], v[30:33]
	v_mfma_f32_16x16x32_bf16 v[26:29], v[160:163], v[200:203], v[26:29]
	s_waitcnt lgkmcnt(0)
	v_mfma_f32_16x16x32_bf16 v[14:17], v[152:155], v[252:255], v[14:17]
	v_mfma_f32_16x16x32_bf16 v[10:13], v[160:163], v[252:255], v[10:13]
	s_setprio 0
	s_setprio 1
	v_mfma_f32_16x16x32_bf16 v[54:57], v[164:167], v[180:183], v[54:57]
	v_mfma_f32_16x16x32_bf16 v[50:53], v[172:175], v[180:183], v[50:53]
	v_mfma_f32_16x16x32_bf16 v[38:41], v[164:167], v[188:191], v[38:41]
	v_mfma_f32_16x16x32_bf16 v[34:37], v[172:175], v[188:191], v[34:37]
	v_mfma_f32_16x16x32_bf16 v[22:25], v[164:167], v[196:199], v[22:25]
	v_mfma_f32_16x16x32_bf16 v[18:21], v[172:175], v[196:199], v[18:21]
	v_mfma_f32_16x16x32_bf16 v[6:9], v[164:167], v[204:207], v[6:9]
	v_mfma_f32_16x16x32_bf16 v[2:5], v[172:175], v[204:207], v[2:5]
	v_mfma_f32_16x16x32_bf16 v[54:57], v[168:171], v[184:187], v[54:57]
	v_mfma_f32_16x16x32_bf16 v[50:53], v[248:251], v[184:187], v[50:53]
	v_mfma_f32_16x16x32_bf16 v[38:41], v[168:171], v[192:195], v[38:41]
	v_mfma_f32_16x16x32_bf16 v[34:37], v[248:251], v[192:195], v[34:37]
	v_mfma_f32_16x16x32_bf16 v[22:25], v[168:171], v[200:203], v[22:25]
	v_mfma_f32_16x16x32_bf16 v[18:21], v[248:251], v[200:203], v[18:21]
	v_mfma_f32_16x16x32_bf16 v[6:9], v[168:171], v[252:255], v[6:9]
	s_setprio 2
	s_barrier
	v_mfma_f32_16x16x32_bf16 v[2:5], v[248:251], v[252:255], v[2:5]
	s_setprio 0
	s_add_i32 s69, s69, 2
	s_add_u32 s53, s53, 0x100
	s_addc_u32 s58, s58, 0
	s_add_u32 s59, s59, 0x100
	s_addc_u32 s68, s68, 0
	s_add_u32 s42, s42, 0x100
	s_addc_u32 s43, s43, 0
	s_cmp_gt_u32 s69, 61
	s_cbranch_scc0 .LBB0_698
	s_and_b64 vcc, exec, s[14:15]
	s_cbranch_vccz .LBB0_701
	s_barrier

; #define PG8_STAGE(bufoff, gbase, voff) do { _Pragma("unroll") for (int _i = 0; _i < 2; ++_i) \
;         asm volatile("s_mov_b32 m0, %2\n\ts_nop 0\n\tglobal_load_lds_dwordx4 %0, %1" :: "v"((voff)[_i]), "s"((const char*)(gbase)), "s"(ldsbase + (unsigned)(bufoff) + ldsw + (unsigned)_i * 8192u) : "memory", "m0"); } while (0)
; #define PG8_LDA(dst, b, h) do { _Pragma("unroll") for (int m = 0; m < 4; ++m) _Pragma("unroll") for (int k = 0; k < 2; ++k) dst[m][k] = *(const PG8_LAS bf16x8*)(lds + PG8_SA(b, h) + aoff + m * 2048 + k * 1024); } while (0)
; #define PG8_LDB(dst, b, h) do { _Pragma("unroll") for (int n = 0; n < 2; ++n) _Pragma("unroll") for (int k = 0; k < 2; ++k) dst[n][k] = *(const PG8_LAS bf16x8*)(lds + PG8_SB(b, h) + boff + n * 2048 + k * 1024); } while (0)
; #define PG8_MMA(ai, bj, At, Bt) do { __builtin_amdgcn_s_setprio(1); _Pragma("unroll") for (int m = 0; m < 4; ++m) _Pragma("unroll") for (int n = 0; n < 2; ++n) _Pragma("unroll") for (int k = 0; k < 2; ++k) \
;         acc[ai][bj][m][n] = __builtin_amdgcn_mfma_f32_16x16x32_bf16(Bt[n][k], At[m][k], acc[ai][bj][m][n], 0, 0, 0); __builtin_amdgcn_s_setprio(0); } while (0)
; #define PG8_WAIT_V(n) asm volatile("s_waitcnt vmcnt(" #n ")" ::: "memory")
; #define PG8_WAIT_L(n) asm volatile("s_waitcnt lgkmcnt(" #n ")" ::: "memory")
; #define PG8_BAR __builtin_amdgcn_s_barrier()
; #define PG8_SCHED __builtin_amdgcn_sched_barrier(0)
; template <class Epi, class Sched, bool ALIGN_EPI = false, bool SP2 = false>
; __device__ __forceinline__ void gemm_phase(PG8_LAS unsigned char* lds, const Gemm g, const Sched& S, const Epi& E) {
;     ...
;             PG8_LDB(B0, 0, 0); PG8_LDB(B1, 0, 1); PG8_SCHED; PG8_LDA(At, 0, 0); PG8_STAGE(PG8_SA(1, 1), a1 + hstep, voffA);
;             PG8_WAIT_V(8); PG8_WAIT_L(0); PG8_BAR; PG8_MMA(0, 0, At, B0); PG8_MMA(0, 1, At, B1); PG8_BAR; PG8_SCHED;
;             PG8_LDA(At, 0, 1); PG8_STAGE(PG8_SB(0, 0), b2, voffB); PG8_STAGE(PG8_SB(0, 1), b2 + hstep, voffB); PG8_STAGE(PG8_SA(0, 0), a2, voffA);
;             PG8_WAIT_V(8); PG8_WAIT_L(0); PG8_BAR; PG8_MMA(1, 0, At, B0); PG8_MMA(1, 1, At, B1); PG8_BAR; PG8_SCHED;
.LBB0_789:
	v_add_u32_e32 v164, 0x10000, v149
	v_add_u32_e32 v180, 0x14000, v149
	s_add_u32 s8, s40, 0x100
	s_waitcnt lgkmcnt(0)
	ds_read_b128 v[152:155], v164
	ds_read_b128 v[156:159], v164 offset:1024
	ds_read_b128 v[160:163], v164 offset:2048
	ds_read_b128 v[164:167], v164 offset:3072
	ds_read_b128 v[168:171], v180
	ds_read_b128 v[172:175], v180 offset:1024
	ds_read_b128 v[176:179], v180 offset:2048
	ds_read_b128 v[180:183], v180 offset:3072
	s_addc_u32 s9, s41, 0
	s_and_b64 s[38:39], s[38:39], exec
	s_cselect_b32 s46, s59, s8
	s_cselect_b32 s47, s17, s9
	s_cselect_b32 s39, s15, s75
	s_cselect_b32 s38, s71, s74
	s_add_u32 s42, s46, 0x80
	s_addc_u32 s43, s47, 0
	s_add_u32 s44, s38, 0x80
	s_addc_u32 s45, s39, 0
	ds_read_b128 v[184:187], v150
	ds_read_b128 v[188:191], v150 offset:1024
	ds_read_b128 v[192:195], v150 offset:2048
	ds_read_b128 v[196:199], v150 offset:3072
	ds_read_b128 v[200:203], v150 offset:4096
	ds_read_b128 v[204:207], v150 offset:5120
	ds_read_b128 v[208:211], v150 offset:6144
	ds_read_b128 v[212:215], v150 offset:7168
	s_add_u32 s40, s40, 0x100080
	s_addc_u32 s41, s41, 0
	s_mov_b32 m0, s64
	s_nop 0
	global_load_lds_dwordx4 v139, s[40:41]
	s_nop 0
	s_mov_b32 m0, s65
	s_nop 0
	global_load_lds_dwordx4 v141, s[40:41]
	s_waitcnt vmcnt(8)
	s_waitcnt lgkmcnt(0)
	s_barrier
	s_setprio 1
	s_waitcnt lgkmcnt(7)
	v_mfma_f32_16x16x32_bf16 v[126:129], v[152:155], v[184:187], v[126:129]
	v_mfma_f32_16x16x32_bf16 v[122:125], v[160:163], v[184:187], v[122:125]
	s_waitcnt lgkmcnt(5)
	v_mfma_f32_16x16x32_bf16 v[110:113], v[152:155], v[192:195], v[110:113]
	v_mfma_f32_16x16x32_bf16 v[106:109], v[160:163], v[192:195], v[106:109]
	s_waitcnt lgkmcnt(3)
	v_mfma_f32_16x16x32_bf16 v[94:97], v[152:155], v[200:203], v[94:97]
	v_mfma_f32_16x16x32_bf16 v[90:93], v[160:163], v[200:203], v[90:93]
	s_waitcnt lgkmcnt(1)
	v_mfma_f32_16x16x32_bf16 v[78:81], v[152:155], v[208:211], v[78:81]
	v_mfma_f32_16x16x32_bf16 v[74:77], v[160:163], v[208:211], v[74:77]
	v_mfma_f32_16x16x32_bf16 v[126:129], v[156:159], v[188:191], v[126:129]
	v_mfma_f32_16x16x32_bf16 v[122:125], v[164:167], v[188:191], v[122:125]
	v_mfma_f32_16x16x32_bf16 v[110:113], v[156:159], v[196:199], v[110:113]
	v_mfma_f32_16x16x32_bf16 v[106:109], v[164:167], v[196:199], v[106:109]
	v_mfma_f32_16x16x32_bf16 v[94:97], v[156:159], v[204:207], v[94:97]
	v_mfma_f32_16x16x32_bf16 v[90:93], v[164:167], v[204:207], v[90:93]
	s_waitcnt lgkmcnt(0)
	v_mfma_f32_16x16x32_bf16 v[78:81], v[156:159], v[212:215], v[78:81]
	v_mfma_f32_16x16x32_bf16 v[74:77], v[164:167], v[212:215], v[74:77]
	s_setprio 0
	s_setprio 1
	v_mfma_f32_16x16x32_bf16 v[118:121], v[168:171], v[184:187], v[118:121]
	v_mfma_f32_16x16x32_bf16 v[114:117], v[176:179], v[184:187], v[114:117]
	v_mfma_f32_16x16x32_bf16 v[102:105], v[168:171], v[192:195], v[102:105]
	v_mfma_f32_16x16x32_bf16 v[98:101], v[176:179], v[192:195], v[98:101]
	v_mfma_f32_16x16x32_bf16 v[86:89], v[168:171], v[200:203], v[86:89]
	v_mfma_f32_16x16x32_bf16 v[82:85], v[176:179], v[200:203], v[82:85]
	v_mfma_f32_16x16x32_bf16 v[70:73], v[168:171], v[208:211], v[70:73]
	v_mfma_f32_16x16x32_bf16 v[66:69], v[176:179], v[208:211], v[66:69]
	v_mfma_f32_16x16x32_bf16 v[118:121], v[172:175], v[188:191], v[118:121]
	v_mfma_f32_16x16x32_bf16 v[114:117], v[180:183], v[188:191], v[114:117]
	v_mfma_f32_16x16x32_bf16 v[102:105], v[172:175], v[196:199], v[102:105]
	v_mfma_f32_16x16x32_bf16 v[98:101], v[180:183], v[196:199], v[98:101]
	v_mfma_f32_16x16x32_bf16 v[86:89], v[172:175], v[204:207], v[86:89]
	v_mfma_f32_16x16x32_bf16 v[82:85], v[180:183], v[204:207], v[82:85]
	v_mfma_f32_16x16x32_bf16 v[70:73], v[172:175], v[212:215], v[70:73]
	s_setprio 2
	s_barrier
	v_mfma_f32_16x16x32_bf16 v[66:69], v[180:183], v[212:215], v[66:69]
	s_setprio 0
	ds_read_b128 v[184:187], v150 offset:16384
	ds_read_b128 v[188:191], v150 offset:17408
	ds_read_b128 v[192:195], v150 offset:18432
	ds_read_b128 v[196:199], v150 offset:19456
	ds_read_b128 v[200:203], v150 offset:20480
	ds_read_b128 v[204:207], v150 offset:21504
	ds_read_b128 v[208:211], v150 offset:22528
	ds_read_b128 v[252:255], v150 offset:23552
	s_mov_b32 m0, s49
	s_nop 0
	global_load_lds_dwordx4 v140, s[38:39]
	s_add_u32 s40, s38, 0x100000
	s_mov_b32 m0, s50
	s_nop 0
	global_load_lds_dwordx4 v142, s[38:39]
	s_addc_u32 s41, s39, 0
	s_mov_b32 m0, s51
	s_nop 0
	global_load_lds_dwordx4 v140, s[40:41]
	s_nop 0
	s_mov_b32 m0, s52
	s_nop 0
	global_load_lds_dwordx4 v142, s[40:41]
	s_nop 0
	s_mov_b32 m0, s37
	s_nop 0
	global_load_lds_dwordx4 v139, s[46:47]
	s_nop 0
	s_mov_b32 m0, s53
	s_nop 0
	global_load_lds_dwordx4 v141, s[46:47]
	s_waitcnt vmcnt(8)
	s_waitcnt lgkmcnt(0)
	s_barrier
; #define PG8_STAGE(bufoff, gbase, voff) do { _Pragma("unroll") for (int _i = 0; _i < 2; ++_i) \
;         asm volatile("s_mov_b32 m0, %2\n\ts_nop 0\n\tglobal_load_lds_dwordx4 %0, %1" :: "v"((voff)[_i]), "s"((const char*)(gbase)), "s"(ldsbase + (unsigned)(bufoff) + ldsw + (unsigned)_i * 8192u) : "memory", "m0"); } while (0)
; #define PG8_LDA(dst, b, h) do { _Pragma("unroll") for (int m = 0; m < 4; ++m) _Pragma("unroll") for (int k = 0; k < 2; ++k) dst[m][k] = *(const PG8_LAS bf16x8*)(lds + PG8_SA(b, h) + aoff + m * 2048 + k * 1024); } while (0)
; #define PG8_LDB(dst, b, h) do { _Pragma("unroll") for (int n = 0; n < 2; ++n) _Pragma("unroll") for (int k = 0; k < 2; ++k) dst[n][k] = *(const PG8_LAS bf16x8*)(lds + PG8_SB(b, h) + boff + n * 2048 + k * 1024); } while (0)
; #define PG8_MMA(ai, bj, At, Bt) do { __builtin_amdgcn_s_setprio(1); _Pragma("unroll") for (int m = 0; m < 4; ++m) _Pragma("unroll") for (int n = 0; n < 2; ++n) _Pragma("unroll") for (int k = 0; k < 2; ++k) \
;         acc[ai][bj][m][n] = __builtin_amdgcn_mfma_f32_16x16x32_bf16(Bt[n][k], At[m][k], acc[ai][bj][m][n], 0, 0, 0); __builtin_amdgcn_s_setprio(0); } while (0)
; #define PG8_WAIT_V(n) asm volatile("s_waitcnt vmcnt(" #n ")" ::: "memory")
; #define PG8_WAIT_L(n) asm volatile("s_waitcnt lgkmcnt(" #n ")" ::: "memory")
; #define PG8_BAR __builtin_amdgcn_s_barrier()
; #define PG8_SCHED __builtin_amdgcn_sched_barrier(0)
; template <class Epi, class Sched, bool ALIGN_EPI = false, bool SP2 = false>
; __device__ __forceinline__ void gemm_phase(PG8_LAS unsigned char* lds, const Gemm g, const Sched& S, const Epi& E) {
;     ...
;             PG8_WAIT_V(8); PG8_WAIT_L(0); PG8_BAR; PG8_MMA(1, 0, At, B0); PG8_MMA(1, 1, At, B1); PG8_BAR; PG8_SCHED;
;             PG8_LDB(B0, 1, 0); PG8_LDB(B1, 1, 1); PG8_SCHED; PG8_LDA(At, 1, 0); PG8_STAGE(PG8_SA(0, 1), a2 + hstep, voffA);
;             PG8_WAIT_V(8); PG8_WAIT_L(0); PG8_BAR; PG8_MMA(0, 0, At, B0); PG8_MMA(0, 1, At, B1); PG8_BAR; PG8_SCHED;
	s_setprio 1
	s_waitcnt lgkmcnt(7)
	v_mfma_f32_16x16x32_bf16 v[62:65], v[152:155], v[184:187], v[62:65]
	v_mfma_f32_16x16x32_bf16 v[58:61], v[160:163], v[184:187], v[58:61]
	s_waitcnt lgkmcnt(5)
	v_mfma_f32_16x16x32_bf16 v[46:49], v[152:155], v[192:195], v[46:49]
	v_mfma_f32_16x16x32_bf16 v[42:45], v[160:163], v[192:195], v[42:45]
	s_waitcnt lgkmcnt(3)
	v_mfma_f32_16x16x32_bf16 v[30:33], v[152:155], v[200:203], v[30:33]
	v_mfma_f32_16x16x32_bf16 v[26:29], v[160:163], v[200:203], v[26:29]
	s_waitcnt lgkmcnt(1)
	v_mfma_f32_16x16x32_bf16 v[14:17], v[152:155], v[208:211], v[14:17]
	v_mfma_f32_16x16x32_bf16 v[10:13], v[160:163], v[208:211], v[10:13]
	v_mfma_f32_16x16x32_bf16 v[62:65], v[156:159], v[188:191], v[62:65]
	v_mfma_f32_16x16x32_bf16 v[58:61], v[164:167], v[188:191], v[58:61]
	v_mfma_f32_16x16x32_bf16 v[46:49], v[156:159], v[196:199], v[46:49]
	v_mfma_f32_16x16x32_bf16 v[42:45], v[164:167], v[196:199], v[42:45]
	v_mfma_f32_16x16x32_bf16 v[30:33], v[156:159], v[204:207], v[30:33]
	v_mfma_f32_16x16x32_bf16 v[26:29], v[164:167], v[204:207], v[26:29]
	s_waitcnt lgkmcnt(0)
	v_mfma_f32_16x16x32_bf16 v[14:17], v[156:159], v[252:255], v[14:17]
	v_mfma_f32_16x16x32_bf16 v[10:13], v[164:167], v[252:255], v[10:13]
	s_setprio 0
	s_setprio 1
	v_mfma_f32_16x16x32_bf16 v[54:57], v[168:171], v[184:187], v[54:57]
	v_mfma_f32_16x16x32_bf16 v[50:53], v[176:179], v[184:187], v[50:53]
	v_mfma_f32_16x16x32_bf16 v[38:41], v[168:171], v[192:195], v[38:41]
	v_mfma_f32_16x16x32_bf16 v[34:37], v[176:179], v[192:195], v[34:37]
	v_mfma_f32_16x16x32_bf16 v[22:25], v[168:171], v[200:203], v[22:25]
	v_mfma_f32_16x16x32_bf16 v[18:21], v[176:179], v[200:203], v[18:21]
	v_mfma_f32_16x16x32_bf16 v[6:9], v[168:171], v[208:211], v[6:9]
	v_mfma_f32_16x16x32_bf16 v[2:5], v[176:179], v[208:211], v[2:5]
	v_mfma_f32_16x16x32_bf16 v[54:57], v[172:175], v[188:191], v[54:57]
	v_mfma_f32_16x16x32_bf16 v[50:53], v[180:183], v[188:191], v[50:53]
	v_mfma_f32_16x16x32_bf16 v[38:41], v[172:175], v[196:199], v[38:41]
	v_mfma_f32_16x16x32_bf16 v[34:37], v[180:183], v[196:199], v[34:37]
	v_mfma_f32_16x16x32_bf16 v[22:25], v[172:175], v[204:207], v[22:25]
	v_mfma_f32_16x16x32_bf16 v[18:21], v[180:183], v[204:207], v[18:21]
	v_mfma_f32_16x16x32_bf16 v[6:9], v[172:175], v[252:255], v[6:9]
	s_setprio 2
	s_barrier
	v_mfma_f32_16x16x32_bf16 v[2:5], v[180:183], v[252:255], v[2:5]
	s_setprio 0
	v_add_u32_e32 v164, 0x18000, v149
	v_add_u32_e32 v180, 0x1c000, v149
	ds_read_b128 v[152:155], v164
	ds_read_b128 v[156:159], v164 offset:1024
	ds_read_b128 v[160:163], v164 offset:2048
	ds_read_b128 v[164:167], v164 offset:3072
	ds_read_b128 v[168:171], v180
	ds_read_b128 v[172:175], v180 offset:1024
	ds_read_b128 v[176:179], v180 offset:2048
	ds_read_b128 v[248:251], v180 offset:3072
	ds_read_b128 v[184:187], v150 offset:32768
	ds_read_b128 v[188:191], v150 offset:33792
	ds_read_b128 v[192:195], v150 offset:34816
	ds_read_b128 v[196:199], v150 offset:35840
	ds_read_b128 v[200:203], v150 offset:36864
	ds_read_b128 v[204:207], v150 offset:37888
	ds_read_b128 v[208:211], v150 offset:38912
	ds_read_b128 v[212:215], v150 offset:39936
	s_add_u32 s40, s46, 0x100000
	s_addc_u32 s41, s47, 0
	s_mov_b32 m0, s54
	s_nop 0
	global_load_lds_dwordx4 v139, s[40:41]
	s_nop 0
	s_mov_b32 m0, s55
	s_nop 0
	global_load_lds_dwordx4 v141, s[40:41]
	s_waitcnt vmcnt(8)
	s_waitcnt lgkmcnt(0)
	s_barrier
	s_setprio 1
	s_waitcnt lgkmcnt(7)
	v_mfma_f32_16x16x32_bf16 v[126:129], v[152:155], v[184:187], v[126:129]
	v_mfma_f32_16x16x32_bf16 v[122:125], v[160:163], v[184:187], v[122:125]
	s_waitcnt lgkmcnt(5)
	v_mfma_f32_16x16x32_bf16 v[110:113], v[152:155], v[192:195], v[110:113]
	v_mfma_f32_16x16x32_bf16 v[106:109], v[160:163], v[192:195], v[106:109]
	s_waitcnt lgkmcnt(3)
	v_mfma_f32_16x16x32_bf16 v[94:97], v[152:155], v[200:203], v[94:97]
	v_mfma_f32_16x16x32_bf16 v[90:93], v[160:163], v[200:203], v[90:93]
	s_waitcnt lgkmcnt(1)
	v_mfma_f32_16x16x32_bf16 v[78:81], v[152:155], v[208:211], v[78:81]
	v_mfma_f32_16x16x32_bf16 v[74:77], v[160:163], v[208:211], v[74:77]
	v_mfma_f32_16x16x32_bf16 v[126:129], v[156:159], v[188:191], v[126:129]
	v_mfma_f32_16x16x32_bf16 v[122:125], v[164:167], v[188:191], v[122:125]
	v_mfma_f32_16x16x32_bf16 v[110:113], v[156:159], v[196:199], v[110:113]
	v_mfma_f32_16x16x32_bf16 v[106:109], v[164:167], v[196:199], v[106:109]
	v_mfma_f32_16x16x32_bf16 v[94:97], v[156:159], v[204:207], v[94:97]
	v_mfma_f32_16x16x32_bf16 v[90:93], v[164:167], v[204:207], v[90:93]
	s_waitcnt lgkmcnt(0)
	v_mfma_f32_16x16x32_bf16 v[78:81], v[156:159], v[212:215], v[78:81]
	v_mfma_f32_16x16x32_bf16 v[74:77], v[164:167], v[212:215], v[74:77]
	s_setprio 0
	s_setprio 1
	v_mfma_f32_16x16x32_bf16 v[118:121], v[168:171], v[184:187], v[118:121]
	v_mfma_f32_16x16x32_bf16 v[114:117], v[176:179], v[184:187], v[114:117]
	v_mfma_f32_16x16x32_bf16 v[102:105], v[168:171], v[192:195], v[102:105]
	v_mfma_f32_16x16x32_bf16 v[98:101], v[176:179], v[192:195], v[98:101]
	v_mfma_f32_16x16x32_bf16 v[86:89], v[168:171], v[200:203], v[86:89]
	v_mfma_f32_16x16x32_bf16 v[82:85], v[176:179], v[200:203], v[82:85]
	v_mfma_f32_16x16x32_bf16 v[70:73], v[168:171], v[208:211], v[70:73]
	v_mfma_f32_16x16x32_bf16 v[66:69], v[176:179], v[208:211], v[66:69]
	v_mfma_f32_16x16x32_bf16 v[118:121], v[172:175], v[188:191], v[118:121]
	v_mfma_f32_16x16x32_bf16 v[114:117], v[248:251], v[188:191], v[114:117]
	v_mfma_f32_16x16x32_bf16 v[102:105], v[172:175], v[196:199], v[102:105]
	v_mfma_f32_16x16x32_bf16 v[98:101], v[248:251], v[196:199], v[98:101]
	v_mfma_f32_16x16x32_bf16 v[86:89], v[172:175], v[204:207], v[86:89]
	v_mfma_f32_16x16x32_bf16 v[82:85], v[248:251], v[204:207], v[82:85]
	v_mfma_f32_16x16x32_bf16 v[70:73], v[172:175], v[212:215], v[70:73]
	s_setprio 2
	s_barrier
; #define PG8_STAGE(bufoff, gbase, voff) do { _Pragma("unroll") for (int _i = 0; _i < 2; ++_i) \
;         asm volatile("s_mov_b32 m0, %2\n\ts_nop 0\n\tglobal_load_lds_dwordx4 %0, %1" :: "v"((voff)[_i]), "s"((const char*)(gbase)), "s"(ldsbase + (unsigned)(bufoff) + ldsw + (unsigned)_i * 8192u) : "memory", "m0"); } while (0)
; #define PG8_LDA(dst, b, h) do { _Pragma("unroll") for (int m = 0; m < 4; ++m) _Pragma("unroll") for (int k = 0; k < 2; ++k) dst[m][k] = *(const PG8_LAS bf16x8*)(lds + PG8_SA(b, h) + aoff + m * 2048 + k * 1024); } while (0)
; #define PG8_MMA(ai, bj, At, Bt) do { __builtin_amdgcn_s_setprio(1); _Pragma("unroll") for (int m = 0; m < 4; ++m) _Pragma("unroll") for (int n = 0; n < 2; ++n) _Pragma("unroll") for (int k = 0; k < 2; ++k) \
;         acc[ai][bj][m][n] = __builtin_amdgcn_mfma_f32_16x16x32_bf16(Bt[n][k], At[m][k], acc[ai][bj][m][n], 0, 0, 0); __builtin_amdgcn_s_setprio(0); } while (0)
; #define PG8_WAIT_V(n) asm volatile("s_waitcnt vmcnt(" #n ")" ::: "memory")
; #define PG8_WAIT_L(n) asm volatile("s_waitcnt lgkmcnt(" #n ")" ::: "memory")
; #define PG8_BAR __builtin_amdgcn_s_barrier()
; #define PG8_SCHED __builtin_amdgcn_sched_barrier(0)
; template <class Epi, class Sched, bool ALIGN_EPI = false, bool SP2 = false>
; __device__ __forceinline__ void gemm_phase(PG8_LAS unsigned char* lds, const Gemm g, const Sched& S, const Epi& E) {
;     ...
;             PG8_LDA(At, 1, 1); PG8_STAGE(PG8_SB(1, 0), b3, voffB); PG8_STAGE(PG8_SB(1, 1), b3 + hstep, voffB); PG8_STAGE(PG8_SA(1, 0), a3, voffA);
;             PG8_WAIT_V(8); PG8_WAIT_L(0); PG8_BAR; PG8_MMA(1, 0, At, B0); PG8_MMA(1, 1, At, B1); PG8_BAR; PG8_SCHED;
	v_mfma_f32_16x16x32_bf16 v[66:69], v[248:251], v[212:215], v[66:69]
	s_setprio 0
	ds_read_b128 v[184:187], v150 offset:49152
	ds_read_b128 v[188:191], v150 offset:50176
	ds_read_b128 v[192:195], v150 offset:51200
	ds_read_b128 v[196:199], v150 offset:52224
	ds_read_b128 v[200:203], v150 offset:53248
	ds_read_b128 v[204:207], v150 offset:54272
	ds_read_b128 v[208:211], v150 offset:55296
	ds_read_b128 v[252:255], v150 offset:56320
	s_mov_b32 m0, s56
	s_nop 0
	global_load_lds_dwordx4 v140, s[44:45]
	s_add_u32 s38, s38, 0x100080
	s_mov_b32 m0, s57
	s_nop 0
	global_load_lds_dwordx4 v142, s[44:45]
	s_addc_u32 s39, s39, 0
	s_mov_b32 m0, s62
	s_nop 0
	global_load_lds_dwordx4 v140, s[38:39]
	s_nop 0
	s_mov_b32 m0, s63
	s_nop 0
	global_load_lds_dwordx4 v142, s[38:39]
	s_nop 0
	s_mov_b32 m0, s60
	s_nop 0
	global_load_lds_dwordx4 v139, s[42:43]
	s_nop 0
	s_mov_b32 m0, s61
	s_nop 0
	global_load_lds_dwordx4 v141, s[42:43]
	s_waitcnt vmcnt(8)
	s_waitcnt lgkmcnt(0)
	s_barrier
	s_setprio 1
	s_waitcnt lgkmcnt(7)
	v_mfma_f32_16x16x32_bf16 v[62:65], v[152:155], v[184:187], v[62:65]
	v_mfma_f32_16x16x32_bf16 v[58:61], v[160:163], v[184:187], v[58:61]
	s_waitcnt lgkmcnt(5)
	v_mfma_f32_16x16x32_bf16 v[46:49], v[152:155], v[192:195], v[46:49]
	v_mfma_f32_16x16x32_bf16 v[42:45], v[160:163], v[192:195], v[42:45]
	s_waitcnt lgkmcnt(3)
	v_mfma_f32_16x16x32_bf16 v[30:33], v[152:155], v[200:203], v[30:33]
	v_mfma_f32_16x16x32_bf16 v[26:29], v[160:163], v[200:203], v[26:29]
	s_waitcnt lgkmcnt(1)
	v_mfma_f32_16x16x32_bf16 v[14:17], v[152:155], v[208:211], v[14:17]
	v_mfma_f32_16x16x32_bf16 v[10:13], v[160:163], v[208:211], v[10:13]
	v_mfma_f32_16x16x32_bf16 v[62:65], v[156:159], v[188:191], v[62:65]
	v_mfma_f32_16x16x32_bf16 v[58:61], v[164:167], v[188:191], v[58:61]
	v_mfma_f32_16x16x32_bf16 v[46:49], v[156:159], v[196:199], v[46:49]
	v_mfma_f32_16x16x32_bf16 v[42:45], v[164:167], v[196:199], v[42:45]
	v_mfma_f32_16x16x32_bf16 v[30:33], v[156:159], v[204:207], v[30:33]
	v_mfma_f32_16x16x32_bf16 v[26:29], v[164:167], v[204:207], v[26:29]
	s_waitcnt lgkmcnt(0)
	v_mfma_f32_16x16x32_bf16 v[14:17], v[156:159], v[252:255], v[14:17]
	v_mfma_f32_16x16x32_bf16 v[10:13], v[164:167], v[252:255], v[10:13]
	s_setprio 0
	s_setprio 1
	v_mfma_f32_16x16x32_bf16 v[54:57], v[168:171], v[184:187], v[54:57]
	v_mfma_f32_16x16x32_bf16 v[50:53], v[176:179], v[184:187], v[50:53]
	v_mfma_f32_16x16x32_bf16 v[38:41], v[168:171], v[192:195], v[38:41]
	v_mfma_f32_16x16x32_bf16 v[34:37], v[176:179], v[192:195], v[34:37]
	v_mfma_f32_16x16x32_bf16 v[22:25], v[168:171], v[200:203], v[22:25]
	v_mfma_f32_16x16x32_bf16 v[18:21], v[176:179], v[200:203], v[18:21]
	v_mfma_f32_16x16x32_bf16 v[6:9], v[168:171], v[208:211], v[6:9]
	v_mfma_f32_16x16x32_bf16 v[2:5], v[176:179], v[208:211], v[2:5]
	v_mfma_f32_16x16x32_bf16 v[54:57], v[172:175], v[188:191], v[54:57]
	v_mfma_f32_16x16x32_bf16 v[50:53], v[248:251], v[188:191], v[50:53]
	v_mfma_f32_16x16x32_bf16 v[38:41], v[172:175], v[196:199], v[38:41]
	v_mfma_f32_16x16x32_bf16 v[34:37], v[248:251], v[196:199], v[34:37]
	v_mfma_f32_16x16x32_bf16 v[22:25], v[172:175], v[204:207], v[22:25]
	v_mfma_f32_16x16x32_bf16 v[18:21], v[248:251], v[204:207], v[18:21]
	v_mfma_f32_16x16x32_bf16 v[6:9], v[172:175], v[252:255], v[6:9]
	s_setprio 2
	s_barrier
	v_mfma_f32_16x16x32_bf16 v[2:5], v[248:251], v[252:255], v[2:5]
	s_setprio 0
	s_add_i32 s76, s76, 2
	s_add_u32 s74, s74, 0x100
	s_addc_u32 s75, s75, 0
	s_cmp_gt_u32 s76, 61
	s_cbranch_scc1 .LBB0_780
	s_mov_b64 s[40:41], s[8:9]
	s_branch .LBB0_784

; #define PG8_STAGE(bufoff, gbase, voff) do { _Pragma("unroll") for (int _i = 0; _i < 2; ++_i) \
;         asm volatile("s_mov_b32 m0, %2\n\ts_nop 0\n\tglobal_load_lds_dwordx4 %0, %1" :: "v"((voff)[_i]), "s"((const char*)(gbase)), "s"(ldsbase + (unsigned)(bufoff) + ldsw + (unsigned)_i * 8192u) : "memory", "m0"); } while (0)
; #define PG8_LDA(dst, b, h) do { _Pragma("unroll") for (int m = 0; m < 4; ++m) _Pragma("unroll") for (int k = 0; k < 2; ++k) dst[m][k] = *(const PG8_LAS bf16x8*)(lds + PG8_SA(b, h) + aoff + m * 2048 + k * 1024); } while (0)
; #define PG8_LDB(dst, b, h) do { _Pragma("unroll") for (int n = 0; n < 2; ++n) _Pragma("unroll") for (int k = 0; k < 2; ++k) dst[n][k] = *(const PG8_LAS bf16x8*)(lds + PG8_SB(b, h) + boff + n * 2048 + k * 1024); } while (0)
; #define PG8_MMA(ai, bj, At, Bt) do { __builtin_amdgcn_s_setprio(1); _Pragma("unroll") for (int m = 0; m < 4; ++m) _Pragma("unroll") for (int n = 0; n < 2; ++n) _Pragma("unroll") for (int k = 0; k < 2; ++k) \
;         acc[ai][bj][m][n] = __builtin_amdgcn_mfma_f32_16x16x32_bf16(Bt[n][k], At[m][k], acc[ai][bj][m][n], 0, 0, 0); __builtin_amdgcn_s_setprio(0); } while (0)
; template <class Epi, class Sched, bool ALIGN_EPI = false, bool SP2 = false>
; __device__ __forceinline__ void gemm_phase(PG8_LAS unsigned char* lds, const Gemm g, const Sched& S, const Epi& E) {
;     ...
;             const bool last = (t == nt - 2);
;             const char* a1 = cA + (size_t)(t + 1) * kstep;
;             const char* a2 = last ? nA : cA + (size_t)(t + 2) * kstep; const char* b2 = last ? nB : cB + (size_t)(t + 2) * kstep;
;             const char* a3 = a2 + kstep; const char* b3 = b2 + kstep;
;             if (last && has_next) S.a_ready(nxt);
;             if constexpr (epi_has_mid<Epi>::value) { if (t == Epi::MID_T) E.mid(acc, cur, wr, wc, fr, fq); }
;             if constexpr (SP2) {
;             PG8_LDB(B0, 0, 0); PG8_LDB(B1, 0, 1); PG8_SCHED; PG8_LDA(At, 0, 0); PG8_STAGE(PG8_SA(1, 1), a1 + hstep, voffA);
;             PG8_WAIT_V(8); PG8_WAIT_L(0); PG8_BAR; PG8_MMA(0, 0, At, B0); PG8_MMA(0, 1, At, B1); PG8_BAR; PG8_SCHED;
;             PG8_LDA(At, 0, 1); PG8_STAGE(PG8_SB(0, 0), b2, voffB); PG8_STAGE(PG8_SB(0, 1), b2 + hstep, voffB); PG8_STAGE(PG8_SA(0, 0), a2, voffA);
;             PG8_WAIT_V(8); PG8_WAIT_L(0); PG8_BAR; PG8_MMA(1, 0, At, B0); PG8_MMA(1, 1, At, B1); PG8_BAR; PG8_SCHED;
.LBB0_873:
	ds_read_b128 v[134:137], v145
	ds_read_b128 v[150:153], v145 offset:1024
	ds_read_b128 v[154:157], v145 offset:2048
	ds_read_b128 v[158:161], v145 offset:3072
	ds_read_b128 v[162:165], v146
	ds_read_b128 v[166:169], v146 offset:1024
	ds_read_b128 v[170:173], v146 offset:2048
	ds_read_b128 v[174:177], v146 offset:3072
	s_add_u32 s38, s36, 0x100
	s_addc_u32 s39, s37, 0
	s_cmpk_eq_i32 s69, 0xa8
	s_cselect_b32 s44, s4, s38
	s_cselect_b32 s45, s5, s39
	s_cselect_b32 s42, s22, s67
	s_cselect_b32 s43, s23, s68
	s_add_u32 s40, s44, 0x80
	s_addc_u32 s41, s45, 0
	ds_read_b128 v[178:181], v147
	ds_read_b128 v[182:185], v147 offset:1024
	ds_read_b128 v[186:189], v147 offset:2048
	ds_read_b128 v[190:193], v147 offset:3072
	ds_read_b128 v[194:197], v147 offset:4096
	ds_read_b128 v[198:201], v147 offset:5120
	ds_read_b128 v[202:205], v147 offset:6144
	ds_read_b128 v[206:209], v147 offset:7168
	s_add_u32 s36, s36, 0x2b0080
	s_addc_u32 s37, s37, 0
	s_mov_b32 m0, s60
	s_nop 0
	global_load_lds_dwordx4 v1, s[36:37]
	s_nop 0
	s_mov_b32 m0, s61
	s_nop 0
	global_load_lds_dwordx4 v141, s[36:37]
	s_waitcnt vmcnt(8)
	s_waitcnt lgkmcnt(0)
	s_barrier
	s_setprio 1
	s_waitcnt lgkmcnt(7)
	v_mfma_f32_16x16x32_bf16 v[126:129], v[134:137], v[178:181], v[126:129]
	v_mfma_f32_16x16x32_bf16 v[122:125], v[154:157], v[178:181], v[122:125]
	s_waitcnt lgkmcnt(5)
	v_mfma_f32_16x16x32_bf16 v[110:113], v[134:137], v[186:189], v[110:113]
	v_mfma_f32_16x16x32_bf16 v[106:109], v[154:157], v[186:189], v[106:109]
	s_waitcnt lgkmcnt(3)
	v_mfma_f32_16x16x32_bf16 v[94:97], v[134:137], v[194:197], v[94:97]
	v_mfma_f32_16x16x32_bf16 v[90:93], v[154:157], v[194:197], v[90:93]
	s_waitcnt lgkmcnt(1)
	v_mfma_f32_16x16x32_bf16 v[78:81], v[134:137], v[202:205], v[78:81]
	v_mfma_f32_16x16x32_bf16 v[74:77], v[154:157], v[202:205], v[74:77]
	v_mfma_f32_16x16x32_bf16 v[126:129], v[150:153], v[182:185], v[126:129]
	v_mfma_f32_16x16x32_bf16 v[122:125], v[158:161], v[182:185], v[122:125]
	v_mfma_f32_16x16x32_bf16 v[110:113], v[150:153], v[190:193], v[110:113]
	v_mfma_f32_16x16x32_bf16 v[106:109], v[158:161], v[190:193], v[106:109]
	v_mfma_f32_16x16x32_bf16 v[94:97], v[150:153], v[198:201], v[94:97]
	v_mfma_f32_16x16x32_bf16 v[90:93], v[158:161], v[198:201], v[90:93]
	s_waitcnt lgkmcnt(0)
	v_mfma_f32_16x16x32_bf16 v[78:81], v[150:153], v[206:209], v[78:81]
	v_mfma_f32_16x16x32_bf16 v[74:77], v[158:161], v[206:209], v[74:77]
	s_setprio 0
	s_setprio 1
	v_mfma_f32_16x16x32_bf16 v[118:121], v[162:165], v[178:181], v[118:121]
	v_mfma_f32_16x16x32_bf16 v[114:117], v[170:173], v[178:181], v[114:117]
	v_mfma_f32_16x16x32_bf16 v[102:105], v[162:165], v[186:189], v[102:105]
	v_mfma_f32_16x16x32_bf16 v[98:101], v[170:173], v[186:189], v[98:101]
	v_mfma_f32_16x16x32_bf16 v[86:89], v[162:165], v[194:197], v[86:89]
	v_mfma_f32_16x16x32_bf16 v[82:85], v[170:173], v[194:197], v[82:85]
	v_mfma_f32_16x16x32_bf16 v[70:73], v[162:165], v[202:205], v[70:73]
	v_mfma_f32_16x16x32_bf16 v[66:69], v[170:173], v[202:205], v[66:69]
	v_mfma_f32_16x16x32_bf16 v[118:121], v[166:169], v[182:185], v[118:121]
	v_mfma_f32_16x16x32_bf16 v[114:117], v[174:177], v[182:185], v[114:117]
	v_mfma_f32_16x16x32_bf16 v[102:105], v[166:169], v[190:193], v[102:105]
	v_mfma_f32_16x16x32_bf16 v[98:101], v[174:177], v[190:193], v[98:101]
	v_mfma_f32_16x16x32_bf16 v[86:89], v[166:169], v[198:201], v[86:89]
	v_mfma_f32_16x16x32_bf16 v[82:85], v[174:177], v[198:201], v[82:85]
	v_mfma_f32_16x16x32_bf16 v[70:73], v[166:169], v[206:209], v[70:73]
	s_setprio 2
	s_barrier
	v_mfma_f32_16x16x32_bf16 v[66:69], v[174:177], v[206:209], v[66:69]
	s_setprio 0
	ds_read_b128 v[178:181], v147 offset:16384
	ds_read_b128 v[182:185], v147 offset:17408
	ds_read_b128 v[186:189], v147 offset:18432
	ds_read_b128 v[190:193], v147 offset:19456
	ds_read_b128 v[194:197], v147 offset:20480
	ds_read_b128 v[198:201], v147 offset:21504
	ds_read_b128 v[202:205], v147 offset:22528
	ds_read_b128 v[252:255], v147 offset:23552
	s_mov_b32 m0, s47
	s_nop 0
	global_load_lds_dwordx4 v140, s[42:43]
	s_add_u32 s36, s42, 0x2b0000
	s_mov_b32 m0, s48
	s_nop 0
	global_load_lds_dwordx4 v142, s[42:43]
	s_addc_u32 s37, s43, 0
	s_mov_b32 m0, s49
	s_nop 0
	global_load_lds_dwordx4 v140, s[36:37]
	s_nop 0
	s_mov_b32 m0, s50
	s_nop 0
	global_load_lds_dwordx4 v142, s[36:37]
	s_nop 0
	s_mov_b32 m0, s46
	s_nop 0
	global_load_lds_dwordx4 v1, s[44:45]
	s_nop 0
	s_mov_b32 m0, s51
	s_nop 0
	global_load_lds_dwordx4 v141, s[44:45]
	s_waitcnt vmcnt(8)
	s_waitcnt lgkmcnt(0)
	s_barrier
; #define PG8_STAGE(bufoff, gbase, voff) do { _Pragma("unroll") for (int _i = 0; _i < 2; ++_i) \
;         asm volatile("s_mov_b32 m0, %2\n\ts_nop 0\n\tglobal_load_lds_dwordx4 %0, %1" :: "v"((voff)[_i]), "s"((const char*)(gbase)), "s"(ldsbase + (unsigned)(bufoff) + ldsw + (unsigned)_i * 8192u) : "memory", "m0"); } while (0)
; #define PG8_LDA(dst, b, h) do { _Pragma("unroll") for (int m = 0; m < 4; ++m) _Pragma("unroll") for (int k = 0; k < 2; ++k) dst[m][k] = *(const PG8_LAS bf16x8*)(lds + PG8_SA(b, h) + aoff + m * 2048 + k * 1024); } while (0)
; #define PG8_LDB(dst, b, h) do { _Pragma("unroll") for (int n = 0; n < 2; ++n) _Pragma("unroll") for (int k = 0; k < 2; ++k) dst[n][k] = *(const PG8_LAS bf16x8*)(lds + PG8_SB(b, h) + boff + n * 2048 + k * 1024); } while (0)
; #define PG8_MMA(ai, bj, At, Bt) do { __builtin_amdgcn_s_setprio(1); _Pragma("unroll") for (int m = 0; m < 4; ++m) _Pragma("unroll") for (int n = 0; n < 2; ++n) _Pragma("unroll") for (int k = 0; k < 2; ++k) \
;         acc[ai][bj][m][n] = __builtin_amdgcn_mfma_f32_16x16x32_bf16(Bt[n][k], At[m][k], acc[ai][bj][m][n], 0, 0, 0); __builtin_amdgcn_s_setprio(0); } while (0)
; #define PG8_WAIT_V(n) asm volatile("s_waitcnt vmcnt(" #n ")" ::: "memory")
; #define PG8_WAIT_L(n) asm volatile("s_waitcnt lgkmcnt(" #n ")" ::: "memory")
; #define PG8_BAR __builtin_amdgcn_s_barrier()
; #define PG8_SCHED __builtin_amdgcn_sched_barrier(0)
; template <class Epi, class Sched, bool ALIGN_EPI = false, bool SP2 = false>
; __device__ __forceinline__ void gemm_phase(PG8_LAS unsigned char* lds, const Gemm g, const Sched& S, const Epi& E) {
;     ...
;             PG8_WAIT_V(8); PG8_WAIT_L(0); PG8_BAR; PG8_MMA(1, 0, At, B0); PG8_MMA(1, 1, At, B1); PG8_BAR; PG8_SCHED;
;             PG8_LDB(B0, 1, 0); PG8_LDB(B1, 1, 1); PG8_SCHED; PG8_LDA(At, 1, 0); PG8_STAGE(PG8_SA(0, 1), a2 + hstep, voffA);
;             PG8_WAIT_V(8); PG8_WAIT_L(0); PG8_BAR; PG8_MMA(0, 0, At, B0); PG8_MMA(0, 1, At, B1); PG8_BAR; PG8_SCHED;
	s_setprio 1
	s_waitcnt lgkmcnt(7)
	v_mfma_f32_16x16x32_bf16 v[62:65], v[134:137], v[178:181], v[62:65]
	v_mfma_f32_16x16x32_bf16 v[58:61], v[154:157], v[178:181], v[58:61]
	s_waitcnt lgkmcnt(5)
	v_mfma_f32_16x16x32_bf16 v[46:49], v[134:137], v[186:189], v[46:49]
	v_mfma_f32_16x16x32_bf16 v[42:45], v[154:157], v[186:189], v[42:45]
	s_waitcnt lgkmcnt(3)
	v_mfma_f32_16x16x32_bf16 v[30:33], v[134:137], v[194:197], v[30:33]
	v_mfma_f32_16x16x32_bf16 v[26:29], v[154:157], v[194:197], v[26:29]
	s_waitcnt lgkmcnt(1)
	v_mfma_f32_16x16x32_bf16 v[14:17], v[134:137], v[202:205], v[14:17]
	v_mfma_f32_16x16x32_bf16 v[10:13], v[154:157], v[202:205], v[10:13]
	v_mfma_f32_16x16x32_bf16 v[62:65], v[150:153], v[182:185], v[62:65]
	v_mfma_f32_16x16x32_bf16 v[58:61], v[158:161], v[182:185], v[58:61]
	v_mfma_f32_16x16x32_bf16 v[46:49], v[150:153], v[190:193], v[46:49]
	v_mfma_f32_16x16x32_bf16 v[42:45], v[158:161], v[190:193], v[42:45]
	v_mfma_f32_16x16x32_bf16 v[30:33], v[150:153], v[198:201], v[30:33]
	v_mfma_f32_16x16x32_bf16 v[26:29], v[158:161], v[198:201], v[26:29]
	s_waitcnt lgkmcnt(0)
	v_mfma_f32_16x16x32_bf16 v[14:17], v[150:153], v[252:255], v[14:17]
	v_mfma_f32_16x16x32_bf16 v[10:13], v[158:161], v[252:255], v[10:13]
	s_setprio 0
	s_setprio 1
	v_mfma_f32_16x16x32_bf16 v[54:57], v[162:165], v[178:181], v[54:57]
	v_mfma_f32_16x16x32_bf16 v[50:53], v[170:173], v[178:181], v[50:53]
	v_mfma_f32_16x16x32_bf16 v[38:41], v[162:165], v[186:189], v[38:41]
	v_mfma_f32_16x16x32_bf16 v[34:37], v[170:173], v[186:189], v[34:37]
	v_mfma_f32_16x16x32_bf16 v[22:25], v[162:165], v[194:197], v[22:25]
	v_mfma_f32_16x16x32_bf16 v[18:21], v[170:173], v[194:197], v[18:21]
	v_mfma_f32_16x16x32_bf16 v[6:9], v[162:165], v[202:205], v[6:9]
	v_mfma_f32_16x16x32_bf16 v[2:5], v[170:173], v[202:205], v[2:5]
	v_mfma_f32_16x16x32_bf16 v[54:57], v[166:169], v[182:185], v[54:57]
	v_mfma_f32_16x16x32_bf16 v[50:53], v[174:177], v[182:185], v[50:53]
	v_mfma_f32_16x16x32_bf16 v[38:41], v[166:169], v[190:193], v[38:41]
	v_mfma_f32_16x16x32_bf16 v[34:37], v[174:177], v[190:193], v[34:37]
	v_mfma_f32_16x16x32_bf16 v[22:25], v[166:169], v[198:201], v[22:25]
	v_mfma_f32_16x16x32_bf16 v[18:21], v[174:177], v[198:201], v[18:21]
	v_mfma_f32_16x16x32_bf16 v[6:9], v[166:169], v[252:255], v[6:9]
	s_setprio 2
	s_barrier
	v_mfma_f32_16x16x32_bf16 v[2:5], v[174:177], v[252:255], v[2:5]
	s_setprio 0
	ds_read_b128 v[134:137], v148
	ds_read_b128 v[150:153], v148 offset:1024
	ds_read_b128 v[154:157], v148 offset:2048
	ds_read_b128 v[158:161], v148 offset:3072
	ds_read_b128 v[162:165], v149
	ds_read_b128 v[166:169], v149 offset:1024
	ds_read_b128 v[170:173], v149 offset:2048
	ds_read_b128 v[248:251], v149 offset:3072
	ds_read_b128 v[178:181], v147 offset:32768
	ds_read_b128 v[182:185], v147 offset:33792
	ds_read_b128 v[186:189], v147 offset:34816
	ds_read_b128 v[190:193], v147 offset:35840
	ds_read_b128 v[194:197], v147 offset:36864
	ds_read_b128 v[198:201], v147 offset:37888
	ds_read_b128 v[202:205], v147 offset:38912
	ds_read_b128 v[206:209], v147 offset:39936
	s_add_u32 s36, s44, 0x2b0000
	s_addc_u32 s37, s45, 0
	s_mov_b32 m0, s52
	s_nop 0
	global_load_lds_dwordx4 v1, s[36:37]
	s_nop 0
	s_mov_b32 m0, s53
	s_nop 0
	global_load_lds_dwordx4 v141, s[36:37]
	s_waitcnt vmcnt(8)
	s_waitcnt lgkmcnt(0)
	s_barrier
	s_setprio 1
	s_waitcnt lgkmcnt(7)
	v_mfma_f32_16x16x32_bf16 v[126:129], v[134:137], v[178:181], v[126:129]
	v_mfma_f32_16x16x32_bf16 v[122:125], v[154:157], v[178:181], v[122:125]
	s_waitcnt lgkmcnt(5)
	v_mfma_f32_16x16x32_bf16 v[110:113], v[134:137], v[186:189], v[110:113]
	v_mfma_f32_16x16x32_bf16 v[106:109], v[154:157], v[186:189], v[106:109]
	s_waitcnt lgkmcnt(3)
	v_mfma_f32_16x16x32_bf16 v[94:97], v[134:137], v[194:197], v[94:97]
	v_mfma_f32_16x16x32_bf16 v[90:93], v[154:157], v[194:197], v[90:93]
	s_waitcnt lgkmcnt(1)
	v_mfma_f32_16x16x32_bf16 v[78:81], v[134:137], v[202:205], v[78:81]
	v_mfma_f32_16x16x32_bf16 v[74:77], v[154:157], v[202:205], v[74:77]
	v_mfma_f32_16x16x32_bf16 v[126:129], v[150:153], v[182:185], v[126:129]
	v_mfma_f32_16x16x32_bf16 v[122:125], v[158:161], v[182:185], v[122:125]
	v_mfma_f32_16x16x32_bf16 v[110:113], v[150:153], v[190:193], v[110:113]
	v_mfma_f32_16x16x32_bf16 v[106:109], v[158:161], v[190:193], v[106:109]
	v_mfma_f32_16x16x32_bf16 v[94:97], v[150:153], v[198:201], v[94:97]
	v_mfma_f32_16x16x32_bf16 v[90:93], v[158:161], v[198:201], v[90:93]
	s_waitcnt lgkmcnt(0)
	v_mfma_f32_16x16x32_bf16 v[78:81], v[150:153], v[206:209], v[78:81]
	v_mfma_f32_16x16x32_bf16 v[74:77], v[158:161], v[206:209], v[74:77]
	s_setprio 0
	s_setprio 1
	v_mfma_f32_16x16x32_bf16 v[118:121], v[162:165], v[178:181], v[118:121]
	v_mfma_f32_16x16x32_bf16 v[114:117], v[170:173], v[178:181], v[114:117]
	v_mfma_f32_16x16x32_bf16 v[102:105], v[162:165], v[186:189], v[102:105]
	v_mfma_f32_16x16x32_bf16 v[98:101], v[170:173], v[186:189], v[98:101]
	v_mfma_f32_16x16x32_bf16 v[86:89], v[162:165], v[194:197], v[86:89]
	v_mfma_f32_16x16x32_bf16 v[82:85], v[170:173], v[194:197], v[82:85]
	v_mfma_f32_16x16x32_bf16 v[70:73], v[162:165], v[202:205], v[70:73]
	v_mfma_f32_16x16x32_bf16 v[66:69], v[170:173], v[202:205], v[66:69]
	v_mfma_f32_16x16x32_bf16 v[118:121], v[166:169], v[182:185], v[118:121]
	v_mfma_f32_16x16x32_bf16 v[114:117], v[248:251], v[182:185], v[114:117]
	v_mfma_f32_16x16x32_bf16 v[102:105], v[166:169], v[190:193], v[102:105]
	v_mfma_f32_16x16x32_bf16 v[98:101], v[248:251], v[190:193], v[98:101]
	v_mfma_f32_16x16x32_bf16 v[86:89], v[166:169], v[198:201], v[86:89]
	v_mfma_f32_16x16x32_bf16 v[82:85], v[248:251], v[198:201], v[82:85]
	v_mfma_f32_16x16x32_bf16 v[70:73], v[166:169], v[206:209], v[70:73]
	s_setprio 2
	s_barrier
; #define PG8_STAGE(bufoff, gbase, voff) do { _Pragma("unroll") for (int _i = 0; _i < 2; ++_i) \
;         asm volatile("s_mov_b32 m0, %2\n\ts_nop 0\n\tglobal_load_lds_dwordx4 %0, %1" :: "v"((voff)[_i]), "s"((const char*)(gbase)), "s"(ldsbase + (unsigned)(bufoff) + ldsw + (unsigned)_i * 8192u) : "memory", "m0"); } while (0)
; #define PG8_LDA(dst, b, h) do { _Pragma("unroll") for (int m = 0; m < 4; ++m) _Pragma("unroll") for (int k = 0; k < 2; ++k) dst[m][k] = *(const PG8_LAS bf16x8*)(lds + PG8_SA(b, h) + aoff + m * 2048 + k * 1024); } while (0)
; #define PG8_MMA(ai, bj, At, Bt) do { __builtin_amdgcn_s_setprio(1); _Pragma("unroll") for (int m = 0; m < 4; ++m) _Pragma("unroll") for (int n = 0; n < 2; ++n) _Pragma("unroll") for (int k = 0; k < 2; ++k) \
;         acc[ai][bj][m][n] = __builtin_amdgcn_mfma_f32_16x16x32_bf16(Bt[n][k], At[m][k], acc[ai][bj][m][n], 0, 0, 0); __builtin_amdgcn_s_setprio(0); } while (0)
; #define PG8_WAIT_V(n) asm volatile("s_waitcnt vmcnt(" #n ")" ::: "memory")
; #define PG8_WAIT_L(n) asm volatile("s_waitcnt lgkmcnt(" #n ")" ::: "memory")
; #define PG8_BAR __builtin_amdgcn_s_barrier()
; #define PG8_SCHED __builtin_amdgcn_sched_barrier(0)
; template <class Epi, class Sched, bool ALIGN_EPI = false, bool SP2 = false>
; __device__ __forceinline__ void gemm_phase(PG8_LAS unsigned char* lds, const Gemm g, const Sched& S, const Epi& E) {
;     ...
;             PG8_LDA(At, 1, 1); PG8_STAGE(PG8_SB(1, 0), b3, voffB); PG8_STAGE(PG8_SB(1, 1), b3 + hstep, voffB); PG8_STAGE(PG8_SA(1, 0), a3, voffA);
;             PG8_WAIT_V(8); PG8_WAIT_L(0); PG8_BAR; PG8_MMA(1, 0, At, B0); PG8_MMA(1, 1, At, B1); PG8_BAR; PG8_SCHED;
	v_mfma_f32_16x16x32_bf16 v[66:69], v[248:251], v[206:209], v[66:69]
	s_setprio 0
	ds_read_b128 v[178:181], v147 offset:49152
	ds_read_b128 v[182:185], v147 offset:50176
	ds_read_b128 v[186:189], v147 offset:51200
	ds_read_b128 v[190:193], v147 offset:52224
	ds_read_b128 v[194:197], v147 offset:53248
	ds_read_b128 v[198:201], v147 offset:54272
	ds_read_b128 v[202:205], v147 offset:55296
	ds_read_b128 v[252:255], v147 offset:56320
	s_add_u32 s36, s42, 0x80
	s_addc_u32 s37, s43, 0
	s_mov_b32 m0, s54
	s_nop 0
	global_load_lds_dwordx4 v140, s[36:37]
	s_nop 0
	s_mov_b32 m0, s55
	s_nop 0
	global_load_lds_dwordx4 v142, s[36:37]
	s_add_u32 s36, s42, 0x2b0080
	s_addc_u32 s37, s43, 0
	s_mov_b32 m0, s58
	s_nop 0
	global_load_lds_dwordx4 v140, s[36:37]
	s_nop 0
	s_mov_b32 m0, s59
	s_nop 0
	global_load_lds_dwordx4 v142, s[36:37]
	s_nop 0
	s_mov_b32 m0, s56
	s_nop 0
	global_load_lds_dwordx4 v1, s[40:41]
	s_nop 0
	s_mov_b32 m0, s57
	s_nop 0
	global_load_lds_dwordx4 v141, s[40:41]
	s_waitcnt vmcnt(8)
	s_waitcnt lgkmcnt(0)
	s_barrier
	s_setprio 1
	s_waitcnt lgkmcnt(7)
	v_mfma_f32_16x16x32_bf16 v[62:65], v[134:137], v[178:181], v[62:65]
	v_mfma_f32_16x16x32_bf16 v[58:61], v[154:157], v[178:181], v[58:61]
	s_waitcnt lgkmcnt(5)
	v_mfma_f32_16x16x32_bf16 v[46:49], v[134:137], v[186:189], v[46:49]
	v_mfma_f32_16x16x32_bf16 v[42:45], v[154:157], v[186:189], v[42:45]
	s_waitcnt lgkmcnt(3)
	v_mfma_f32_16x16x32_bf16 v[30:33], v[134:137], v[194:197], v[30:33]
	v_mfma_f32_16x16x32_bf16 v[26:29], v[154:157], v[194:197], v[26:29]
	s_waitcnt lgkmcnt(1)
	v_mfma_f32_16x16x32_bf16 v[14:17], v[134:137], v[202:205], v[14:17]
	v_mfma_f32_16x16x32_bf16 v[10:13], v[154:157], v[202:205], v[10:13]
	v_mfma_f32_16x16x32_bf16 v[62:65], v[150:153], v[182:185], v[62:65]
	v_mfma_f32_16x16x32_bf16 v[58:61], v[158:161], v[182:185], v[58:61]
	v_mfma_f32_16x16x32_bf16 v[46:49], v[150:153], v[190:193], v[46:49]
	v_mfma_f32_16x16x32_bf16 v[42:45], v[158:161], v[190:193], v[42:45]
	v_mfma_f32_16x16x32_bf16 v[30:33], v[150:153], v[198:201], v[30:33]
	v_mfma_f32_16x16x32_bf16 v[26:29], v[158:161], v[198:201], v[26:29]
	s_waitcnt lgkmcnt(0)
	v_mfma_f32_16x16x32_bf16 v[14:17], v[150:153], v[252:255], v[14:17]
	v_mfma_f32_16x16x32_bf16 v[10:13], v[158:161], v[252:255], v[10:13]
	s_setprio 0
	s_setprio 1
	v_mfma_f32_16x16x32_bf16 v[54:57], v[162:165], v[178:181], v[54:57]
	v_mfma_f32_16x16x32_bf16 v[50:53], v[170:173], v[178:181], v[50:53]
	v_mfma_f32_16x16x32_bf16 v[38:41], v[162:165], v[186:189], v[38:41]
	v_mfma_f32_16x16x32_bf16 v[34:37], v[170:173], v[186:189], v[34:37]
	v_mfma_f32_16x16x32_bf16 v[22:25], v[162:165], v[194:197], v[22:25]
	v_mfma_f32_16x16x32_bf16 v[18:21], v[170:173], v[194:197], v[18:21]
	v_mfma_f32_16x16x32_bf16 v[6:9], v[162:165], v[202:205], v[6:9]
	v_mfma_f32_16x16x32_bf16 v[2:5], v[170:173], v[202:205], v[2:5]
	v_mfma_f32_16x16x32_bf16 v[54:57], v[166:169], v[182:185], v[54:57]
	v_mfma_f32_16x16x32_bf16 v[50:53], v[248:251], v[182:185], v[50:53]
	v_mfma_f32_16x16x32_bf16 v[38:41], v[166:169], v[190:193], v[38:41]
	v_mfma_f32_16x16x32_bf16 v[34:37], v[248:251], v[190:193], v[34:37]
	v_mfma_f32_16x16x32_bf16 v[22:25], v[166:169], v[198:201], v[22:25]
	v_mfma_f32_16x16x32_bf16 v[18:21], v[248:251], v[198:201], v[18:21]
	v_mfma_f32_16x16x32_bf16 v[6:9], v[166:169], v[252:255], v[6:9]
	s_setprio 2
	s_barrier
	v_mfma_f32_16x16x32_bf16 v[2:5], v[248:251], v[252:255], v[2:5]
	s_setprio 0
	s_add_i32 s69, s69, 2
	s_add_u32 s67, s67, 0x100
	s_addc_u32 s68, s68, 0
	s_cmpk_gt_u32 s69, 0xa9
	s_mov_b64 s[36:37], s[38:39]
	s_cbranch_scc0 .LBB0_873
	s_and_b64 vcc, exec, s[10:11]
	s_cbranch_vccz .LBB0_876
	s_barrier
